# E-phase GEMM: K-loop unrolled x8, accumulators start from C=0 instead of v_mov zeroing, half of each tile's epilogue stores deferred into the next tile's K-loop (one per iteration)
# speedup vs baseline: 1.0146x; 1.0090x over previous
; __device__ __forceinline__ unsigned xb_add(unsigned* p, unsigned v) { return __hip_atomic_fetch_add(p, v, __ATOMIC_RELAXED, __HIP_MEMORY_SCOPE_AGENT); }
; __device__ __forceinline__ unsigned xb_xcc_id() { return (unsigned)__builtin_amdgcn_s_getreg((3 << 11) | 20) & 0xFu; }
; __global__ void __launch_bounds__(512) fwd_kernel(Params p_arg) {
;     ...
;     const int ph_lo = p_arg.ph_lo, ph_hi = p_arg.ph_hi;
;     unsigned nbar = 0;
;     unsigned* const xbar = (unsigned*)(p_arg.ws + OFF_BAR); const unsigned xcc = xb_xcc_id(); unsigned xb_nloc = 0u, xb_nx = 0u;
;     if (threadIdx.x == 0) (void)xb_add(&xbar[XB_XCNT(xcc)], 1u);
;     if (ph_lo < 0) grid.sync();
;     for (int ph = ph_lo; ph < ph_hi; ++ph)
.LBB0_3:
	s_or_b64 exec, exec, s[4:5]
	s_cmp_gt_i32 s86, -1
	s_cbranch_scc0 .LBB0_5
	s_cmp_ge_i32 s86, s87
	s_cbranch_scc0 .LBB0_16
.Lexit_a:
	s_endpgm
.LBB0_5:
	v_lshrrev_b32_e32 v1, 20, v0
	v_lshrrev_b32_e32 v0, 10, v0
	v_or_b32_e32 v0, v0, v1
	s_movk_i32 s4, 0x3ff
	v_and_or_b32 v0, v0, s4, v167
	v_cmp_eq_u32_e32 vcc, 0, v0
	s_barrier
	s_and_saveexec_b64 s[4:5], vcc
	s_cbranch_execz .LBB0_15
	buffer_wbl2 sc1
	s_waitcnt vmcnt(0)
	s_load_dwordx2 s[6:7], s[6:7], 0x58
	v_mov_b32_e32 v2, 0
	s_mov_b64 s[8:9], exec
	v_mbcnt_lo_u32_b32 v1, s8, 0
	v_mbcnt_hi_u32_b32 v1, s9, v1
	s_waitcnt lgkmcnt(0)
	global_load_dword v0, v2, s[6:7] offset:40
	v_cmp_eq_u32_e32 vcc, 0, v1
	s_and_saveexec_b64 s[10:11], vcc
	s_cbranch_execz .LBB0_8
	s_bcnt1_i32_b64 s8, s[8:9]
	v_mov_b32_e32 v3, s8
	global_atomic_add v3, v2, v3, s[6:7] offset:32 sc0

; #define PG8_STAGE(bufoff, gbase, voff) do { _Pragma("unroll") for (int _i = 0; _i < 2; ++_i) \
;         __builtin_amdgcn_global_load_lds((const unsigned*)((const char*)(gbase) + (voff)[_i]), (LAS unsigned*)(lds + (bufoff) + ldsw + _i * 8192), 16, 0, 0); } while (0)
; #define PG8_LDA(dst, b, h) do { _Pragma("unroll") for (int m = 0; m < 4; ++m) _Pragma("unroll") for (int k = 0; k < 2; ++k) dst[m][k] = *(const LAS bf16x8*)(lds + PG8_SA(b, h) + aoff + m * 2048 + k * 1024); } while (0)
; #define PG8_LDB(dst, b, h) do { _Pragma("unroll") for (int n = 0; n < 2; ++n) _Pragma("unroll") for (int k = 0; k < 2; ++k) dst[n][k] = *(const LAS bf16x8*)(lds + PG8_SB(b, h) + boff + n * 2048 + k * 1024); } while (0)
; #define PG8_MMA(ai, bj, At, Bt) do { __builtin_amdgcn_s_setprio(1); _Pragma("unroll") for (int m = 0; m < 4; ++m) _Pragma("unroll") for (int n = 0; n < 2; ++n) _Pragma("unroll") for (int k = 0; k < 2; ++k) \
;         acc[ai][bj][m][n] = __builtin_amdgcn_mfma_f32_16x16x32_bf16(Bt[n][k], At[m][k], acc[ai][bj][m][n], 0, 0, 0); __builtin_amdgcn_s_setprio(0); } while (0)
; template <class Epi>
; __device__ __forceinline__ void gemm_phase(LAS unsigned char* lds, const Gemm g, const StaticOrder& S, const Epi& E) {
;     ...
;         const bool has_next = S.next(ui + 1, nxt);
;         const char* nA = has_next ? (const char*)g.A + (size_t)nxt.pm * tstep : cA; const char* nB = has_next ? (const char*)g.Bt + (size_t)nxt.pn * tstep : cB;
;     ...
;             const bool last = (t == nt - 2);
;             const char* a1 = cA + (size_t)(t + 1) * kstep;
;             const char* a2 = last ? nA : cA + (size_t)(t + 2) * kstep; const char* b2 = last ? nB : cB + (size_t)(t + 2) * kstep;
;             const char* a3 = a2 + kstep; const char* b3 = b2 + kstep;
;             PG8_LDB(B0, 0, 0); PG8_SCHED; PG8_LDA(At, 0, 0); PG8_STAGE(PG8_SA(1, 1), a1 + hstep, voffA);
;             PG8_WAIT_L(8); PG8_BAR; PG8_WAIT_L(0); PG8_MMA(0, 0, At, B0); PG8_BAR; PG8_SCHED;
;             PG8_LDB(B1, 0, 1); PG8_STAGE(PG8_SB(0, 0), b2, voffB);
;             PG8_BAR; PG8_WAIT_L(0); PG8_MMA(0, 1, At, B1); PG8_BAR;
;             PG8_LDA(At, 0, 1); PG8_STAGE(PG8_SA(0, 0), a2, voffA);
;             PG8_BAR; PG8_WAIT_L(0); PG8_MMA(1, 0, At, B0); PG8_BAR; PG8_SCHED;
;             PG8_STAGE(PG8_SB(0, 1), b2 + hstep, voffB);
;             PG8_WAIT_V(6); PG8_BAR; PG8_MMA(1, 1, At, B1); PG8_BAR;
.LBB0_169:
	v_mov_b64_e32 v[2:3], 0x800
	s_ashr_i32 s11, s10, 31
	v_cmp_lt_i64_e32 vcc, s[12:13], v[2:3]
	s_lshl_b64 s[12:13], s[10:11], 19
	s_add_u32 s12, s44, s12
	s_addc_u32 s13, s45, s13
	s_and_b64 s[24:25], vcc, exec
	s_cselect_b32 s11, s13, s37
	s_cselect_b32 s71, s12, s36
	s_ashr_i32 s9, s8, 31
	s_lshl_b64 s[24:25], s[8:9], 19
	s_add_u32 s24, s46, s24
	s_addc_u32 s25, s47, s25
	s_and_b64 s[42:43], vcc, exec
	s_cselect_b32 s9, s25, s7
	s_cselect_b32 s90, s24, s6
	s_add_u32 s36, s36, 0x40080
	s_addc_u32 s37, s37, 0
	s_add_u32 s91, s6, 0x100
	s_addc_u32 s92, s7, 0
	s_mov_b32 s93, -2
.LBB0_170:
	s_add_u32 s6, s36, 0xfffc0080
	s_addc_u32 s7, s37, -1
	s_add_i32 s58, 0, 0x10000
	v_add_u32_e32 v144, s58, v147
	ds_read_b128 v[140:143], v144
	ds_read_b128 v[152:155], v144 offset:1024
	ds_read_b128 v[168:171], v144 offset:2048
	ds_read_b128 v[172:175], v144 offset:3072
	s_cmp_eq_u32 s93, 12
	s_cselect_b32 s43, s11, s7
	s_cselect_b32 s42, s71, s6
	s_cselect_b32 s7, s9, s92
	s_cselect_b32 s6, s90, s91
	s_add_i32 m0, s49, 0xc000
	ds_read_b128 v[176:179], v150
	ds_read_b128 v[180:183], v150 offset:1024
	ds_read_b128 v[184:187], v150 offset:2048
	ds_read_b128 v[204:207], v150 offset:3072
	ds_read_b128 v[208:211], v150 offset:4096
	ds_read_b128 v[212:215], v150 offset:5120
	ds_read_b128 v[216:219], v150 offset:6144
	ds_read_b128 v[226:229], v150 offset:7168
	global_load_lds_dwordx4 v136, s[36:37]
	s_add_i32 m0, s49, 0xe000
	s_nop 0
	global_load_lds_dwordx4 v138, s[36:37]
	s_waitcnt lgkmcnt(8)
	s_barrier
	s_waitcnt lgkmcnt(0)
	s_setprio 1
	s_waitcnt lgkmcnt(0)
	v_mfma_f32_16x16x32_bf16 v[126:129], v[140:143], v[176:179], 0
	v_mfma_f32_16x16x32_bf16 v[122:125], v[168:171], v[176:179], 0
	v_mfma_f32_16x16x32_bf16 v[110:113], v[140:143], v[184:187], 0
	v_mfma_f32_16x16x32_bf16 v[106:109], v[168:171], v[184:187], 0
	v_mfma_f32_16x16x32_bf16 v[94:97], v[140:143], v[208:211], 0
	v_mfma_f32_16x16x32_bf16 v[90:93], v[168:171], v[208:211], 0
	v_mfma_f32_16x16x32_bf16 v[78:81], v[140:143], v[216:219], 0
	v_mfma_f32_16x16x32_bf16 v[74:77], v[168:171], v[216:219], 0
	v_mfma_f32_16x16x32_bf16 v[126:129], v[152:155], v[180:183], v[126:129]
	v_mfma_f32_16x16x32_bf16 v[122:125], v[172:175], v[180:183], v[122:125]
	v_mfma_f32_16x16x32_bf16 v[110:113], v[152:155], v[204:207], v[110:113]
	v_mfma_f32_16x16x32_bf16 v[106:109], v[172:175], v[204:207], v[106:109]
	v_mfma_f32_16x16x32_bf16 v[94:97], v[152:155], v[212:215], v[94:97]
	v_mfma_f32_16x16x32_bf16 v[90:93], v[172:175], v[212:215], v[90:93]
	v_mfma_f32_16x16x32_bf16 v[78:81], v[152:155], v[226:229], v[78:81]
	v_mfma_f32_16x16x32_bf16 v[74:77], v[172:175], v[226:229], v[74:77]
	s_setprio 0
	s_barrier
	s_add_i32 s70, 0, 0x14000
	v_add_u32_e32 v144, s70, v147
	s_add_i32 s58, s58, s48
	ds_read_b128 v[230:233], v144
	ds_read_b128 v[234:237], v144 offset:1024
	ds_read_b128 v[238:241], v144 offset:2048
	ds_read_b128 v[242:245], v144 offset:3072
	s_mov_b32 m0, s58
	s_nop 0
	global_load_lds_dwordx4 v0, s[6:7]
	s_add_i32 m0, s58, 0x2000
	s_nop 0
	global_load_lds_dwordx4 v130, s[6:7]
	s_barrier
	s_waitcnt lgkmcnt(0)
	s_setprio 1
	s_waitcnt lgkmcnt(0)
	v_mfma_f32_16x16x32_bf16 v[118:121], v[230:233], v[176:179], 0
	v_mfma_f32_16x16x32_bf16 v[114:117], v[238:241], v[176:179], 0
	v_mfma_f32_16x16x32_bf16 v[102:105], v[230:233], v[184:187], 0
	v_mfma_f32_16x16x32_bf16 v[98:101], v[238:241], v[184:187], 0
	v_mfma_f32_16x16x32_bf16 v[86:89], v[230:233], v[208:211], 0
	v_mfma_f32_16x16x32_bf16 v[82:85], v[238:241], v[208:211], 0
	v_mfma_f32_16x16x32_bf16 v[70:73], v[230:233], v[216:219], 0
	v_mfma_f32_16x16x32_bf16 v[66:69], v[238:241], v[216:219], 0
	v_mfma_f32_16x16x32_bf16 v[118:121], v[234:237], v[180:183], v[118:121]
	v_mfma_f32_16x16x32_bf16 v[114:117], v[242:245], v[180:183], v[114:117]
	v_mfma_f32_16x16x32_bf16 v[102:105], v[234:237], v[204:207], v[102:105]
	v_mfma_f32_16x16x32_bf16 v[98:101], v[242:245], v[204:207], v[98:101]
	v_mfma_f32_16x16x32_bf16 v[86:89], v[234:237], v[212:215], v[86:89]
	v_mfma_f32_16x16x32_bf16 v[82:85], v[242:245], v[212:215], v[82:85]
	v_mfma_f32_16x16x32_bf16 v[70:73], v[234:237], v[226:229], v[70:73]
	v_mfma_f32_16x16x32_bf16 v[66:69], v[242:245], v[226:229], v[66:69]
	s_setprio 0
	s_mov_b32 m0, s49
	s_add_u32 vcc_lo, s42, 0x80
	s_addc_u32 vcc_hi, s43, 0
	s_barrier
	ds_read_b128 v[176:179], v150 offset:16384
	ds_read_b128 v[180:183], v150 offset:17408
	ds_read_b128 v[184:187], v150 offset:18432
	ds_read_b128 v[204:207], v150 offset:19456
	ds_read_b128 v[208:211], v150 offset:20480
	ds_read_b128 v[212:215], v150 offset:21504
	ds_read_b128 v[216:219], v150 offset:22528
	ds_read_b128 v[226:229], v150 offset:23552
	global_load_lds_dwordx4 v134, s[42:43]
	s_mov_b32 m0, s54
	s_nop 0
	global_load_lds_dwordx4 v132, s[42:43]
	s_barrier
	s_waitcnt lgkmcnt(0)
	s_setprio 1
	s_waitcnt lgkmcnt(0)
	v_mfma_f32_16x16x32_bf16 v[62:65], v[140:143], v[176:179], 0
	v_mfma_f32_16x16x32_bf16 v[58:61], v[168:171], v[176:179], 0
	v_mfma_f32_16x16x32_bf16 v[46:49], v[140:143], v[184:187], 0
	v_mfma_f32_16x16x32_bf16 v[42:45], v[168:171], v[184:187], 0
	v_mfma_f32_16x16x32_bf16 v[30:33], v[140:143], v[208:211], 0
	v_mfma_f32_16x16x32_bf16 v[26:29], v[168:171], v[208:211], 0
	v_mfma_f32_16x16x32_bf16 v[14:17], v[140:143], v[216:219], 0
	v_mfma_f32_16x16x32_bf16 v[10:13], v[168:171], v[216:219], 0
	v_mfma_f32_16x16x32_bf16 v[62:65], v[152:155], v[180:183], v[62:65]
	v_mfma_f32_16x16x32_bf16 v[58:61], v[172:175], v[180:183], v[58:61]
	v_mfma_f32_16x16x32_bf16 v[46:49], v[152:155], v[204:207], v[46:49]
	v_mfma_f32_16x16x32_bf16 v[42:45], v[172:175], v[204:207], v[42:45]
	v_mfma_f32_16x16x32_bf16 v[30:33], v[152:155], v[212:215], v[30:33]
	v_mfma_f32_16x16x32_bf16 v[26:29], v[172:175], v[212:215], v[26:29]
	v_mfma_f32_16x16x32_bf16 v[14:17], v[152:155], v[226:229], v[14:17]
	v_mfma_f32_16x16x32_bf16 v[10:13], v[172:175], v[226:229], v[10:13]
	s_setprio 0
	s_barrier
	s_add_u32 s60, s6, 0x40000
	s_addc_u32 s61, s7, 0
	s_add_i32 s58, s70, s48
	s_mov_b32 m0, s58
	s_nop 0
	global_load_lds_dwordx4 v0, s[60:61]
	s_add_i32 m0, s58, 0x2000
	s_nop 0
	global_load_lds_dwordx4 v130, s[60:61]
	s_waitcnt vmcnt(6)
	s_barrier
	s_setprio 1
	v_mfma_f32_16x16x32_bf16 v[54:57], v[230:233], v[176:179], 0
	v_mfma_f32_16x16x32_bf16 v[50:53], v[238:241], v[176:179], 0
	s_cmp_eq_u32 s89, 0
	s_cbranch_scc1 .LdsE_skip_0
	global_store_dwordx4 v250, v[158:161], s[4:5]
; #define PG8_STAGE(bufoff, gbase, voff) do { _Pragma("unroll") for (int _i = 0; _i < 2; ++_i) \
;         __builtin_amdgcn_global_load_lds((const unsigned*)((const char*)(gbase) + (voff)[_i]), (LAS unsigned*)(lds + (bufoff) + ldsw + _i * 8192), 16, 0, 0); } while (0)
; #define PG8_LDA(dst, b, h) do { _Pragma("unroll") for (int m = 0; m < 4; ++m) _Pragma("unroll") for (int k = 0; k < 2; ++k) dst[m][k] = *(const LAS bf16x8*)(lds + PG8_SA(b, h) + aoff + m * 2048 + k * 1024); } while (0)
; #define PG8_LDB(dst, b, h) do { _Pragma("unroll") for (int n = 0; n < 2; ++n) _Pragma("unroll") for (int k = 0; k < 2; ++k) dst[n][k] = *(const LAS bf16x8*)(lds + PG8_SB(b, h) + boff + n * 2048 + k * 1024); } while (0)
; #define PG8_MMA(ai, bj, At, Bt) do { __builtin_amdgcn_s_setprio(1); _Pragma("unroll") for (int m = 0; m < 4; ++m) _Pragma("unroll") for (int n = 0; n < 2; ++n) _Pragma("unroll") for (int k = 0; k < 2; ++k) \
;         acc[ai][bj][m][n] = __builtin_amdgcn_mfma_f32_16x16x32_bf16(Bt[n][k], At[m][k], acc[ai][bj][m][n], 0, 0, 0); __builtin_amdgcn_s_setprio(0); } while (0)
; #define PG8_WAIT_V(n) asm volatile("s_waitcnt vmcnt(" #n ")" ::: "memory")
; #define PG8_WAIT_L(n) asm volatile("s_waitcnt lgkmcnt(" #n ")" ::: "memory")
; #define PG8_BAR __builtin_amdgcn_s_barrier()
; #define PG8_SCHED __builtin_amdgcn_sched_barrier(0)
; template <class Epi>
; __device__ __forceinline__ void gemm_phase(LAS unsigned char* lds, const Gemm g, const StaticOrder& S, const Epi& E) {
;     ...
;             PG8_WAIT_V(6); PG8_BAR; PG8_MMA(1, 1, At, B1); PG8_BAR;
;             PG8_LDB(B0, 1, 0); PG8_SCHED; PG8_LDA(At, 1, 0); PG8_STAGE(PG8_SA(0, 1), a2 + hstep, voffA);
;             PG8_WAIT_L(8); PG8_BAR; PG8_WAIT_L(0); PG8_MMA(0, 0, At, B0); PG8_BAR; PG8_SCHED;
;             PG8_LDB(B1, 1, 1); PG8_STAGE(PG8_SB(1, 0), b3, voffB);
;             PG8_BAR; PG8_WAIT_L(0); PG8_MMA(0, 1, At, B1); PG8_BAR;
;             PG8_LDA(At, 1, 1); PG8_STAGE(PG8_SA(1, 0), a3, voffA);
;             PG8_BAR; PG8_WAIT_L(0); PG8_MMA(1, 0, At, B0); PG8_BAR; PG8_SCHED;
.LdsE_skip_0:
	v_mfma_f32_16x16x32_bf16 v[38:41], v[230:233], v[184:187], 0
	v_mfma_f32_16x16x32_bf16 v[34:37], v[238:241], v[184:187], 0
	v_mfma_f32_16x16x32_bf16 v[22:25], v[230:233], v[208:211], 0
	v_mfma_f32_16x16x32_bf16 v[18:21], v[238:241], v[208:211], 0
	v_mfma_f32_16x16x32_bf16 v[6:9], v[230:233], v[216:219], 0
	v_mfma_f32_16x16x32_bf16 v[2:5], v[238:241], v[216:219], 0
	v_mfma_f32_16x16x32_bf16 v[54:57], v[234:237], v[180:183], v[54:57]
	v_mfma_f32_16x16x32_bf16 v[50:53], v[242:245], v[180:183], v[50:53]
	v_mfma_f32_16x16x32_bf16 v[38:41], v[234:237], v[204:207], v[38:41]
	v_mfma_f32_16x16x32_bf16 v[34:37], v[242:245], v[204:207], v[34:37]
	v_mfma_f32_16x16x32_bf16 v[22:25], v[234:237], v[212:215], v[22:25]
	v_mfma_f32_16x16x32_bf16 v[18:21], v[242:245], v[212:215], v[18:21]
	v_mfma_f32_16x16x32_bf16 v[6:9], v[234:237], v[226:229], v[6:9]
	v_mfma_f32_16x16x32_bf16 v[2:5], v[242:245], v[226:229], v[2:5]
	s_setprio 0
	s_add_i32 s58, 0, 0x18000
	v_add_u32_e32 v151, s58, v147
	s_barrier
	ds_read_b128 v[140:143], v151
	ds_read_b128 v[152:155], v151 offset:1024
	ds_read_b128 v[168:171], v151 offset:2048
	ds_read_b128 v[172:175], v151 offset:3072
	s_add_u32 s42, s42, 0x40000
	s_addc_u32 s43, s43, 0
	s_mov_b32 m0, s55
	ds_read_b128 v[176:179], v150 offset:32768
	ds_read_b128 v[180:183], v150 offset:33792
	ds_read_b128 v[184:187], v150 offset:34816
	ds_read_b128 v[204:207], v150 offset:35840
	ds_read_b128 v[208:211], v150 offset:36864
	ds_read_b128 v[212:215], v150 offset:37888
	ds_read_b128 v[216:219], v150 offset:38912
	ds_read_b128 v[226:229], v150 offset:39936
	global_load_lds_dwordx4 v134, s[42:43]
	s_mov_b32 m0, s83
	s_nop 0
	global_load_lds_dwordx4 v132, s[42:43]
	s_waitcnt lgkmcnt(8)
	s_barrier
	s_waitcnt lgkmcnt(0)
	s_setprio 1
	s_waitcnt lgkmcnt(0)
	v_mfma_f32_16x16x32_bf16 v[126:129], v[140:143], v[176:179], v[126:129]
	v_mfma_f32_16x16x32_bf16 v[122:125], v[168:171], v[176:179], v[122:125]
	v_mfma_f32_16x16x32_bf16 v[110:113], v[140:143], v[184:187], v[110:113]
	v_mfma_f32_16x16x32_bf16 v[106:109], v[168:171], v[184:187], v[106:109]
	v_mfma_f32_16x16x32_bf16 v[94:97], v[140:143], v[208:211], v[94:97]
	v_mfma_f32_16x16x32_bf16 v[90:93], v[168:171], v[208:211], v[90:93]
	v_mfma_f32_16x16x32_bf16 v[78:81], v[140:143], v[216:219], v[78:81]
	v_mfma_f32_16x16x32_bf16 v[74:77], v[168:171], v[216:219], v[74:77]
	v_mfma_f32_16x16x32_bf16 v[126:129], v[152:155], v[180:183], v[126:129]
	v_mfma_f32_16x16x32_bf16 v[122:125], v[172:175], v[180:183], v[122:125]
	v_mfma_f32_16x16x32_bf16 v[110:113], v[152:155], v[204:207], v[110:113]
	v_mfma_f32_16x16x32_bf16 v[106:109], v[172:175], v[204:207], v[106:109]
	v_mfma_f32_16x16x32_bf16 v[94:97], v[152:155], v[212:215], v[94:97]
	v_mfma_f32_16x16x32_bf16 v[90:93], v[172:175], v[212:215], v[90:93]
	v_mfma_f32_16x16x32_bf16 v[78:81], v[152:155], v[226:229], v[78:81]
	v_mfma_f32_16x16x32_bf16 v[74:77], v[172:175], v[226:229], v[74:77]
	s_setprio 0
	s_barrier
	s_add_i32 s42, 0, 0x1c000
	s_add_i32 s43, s58, s48
	v_add_u32_e32 v151, s42, v147
	s_add_u32 s60, s6, 0x80
	s_addc_u32 s61, s7, 0
	s_mov_b32 m0, s43
	ds_read_b128 v[230:233], v151
	ds_read_b128 v[234:237], v151 offset:1024
	ds_read_b128 v[238:241], v151 offset:2048
	ds_read_b128 v[242:245], v151 offset:3072
	global_load_lds_dwordx4 v0, s[60:61]
	s_add_i32 m0, s43, 0x2000
	s_nop 0
	global_load_lds_dwordx4 v130, s[60:61]
	s_barrier
	s_waitcnt lgkmcnt(0)
	s_setprio 1
	s_waitcnt lgkmcnt(0)
	v_mfma_f32_16x16x32_bf16 v[118:121], v[230:233], v[176:179], v[118:121]
	v_mfma_f32_16x16x32_bf16 v[114:117], v[238:241], v[176:179], v[114:117]
	v_mfma_f32_16x16x32_bf16 v[102:105], v[230:233], v[184:187], v[102:105]
	v_mfma_f32_16x16x32_bf16 v[98:101], v[238:241], v[184:187], v[98:101]
	v_mfma_f32_16x16x32_bf16 v[86:89], v[230:233], v[208:211], v[86:89]
	v_mfma_f32_16x16x32_bf16 v[82:85], v[238:241], v[208:211], v[82:85]
	v_mfma_f32_16x16x32_bf16 v[70:73], v[230:233], v[216:219], v[70:73]
	v_mfma_f32_16x16x32_bf16 v[66:69], v[238:241], v[216:219], v[66:69]
	v_mfma_f32_16x16x32_bf16 v[118:121], v[234:237], v[180:183], v[118:121]
	v_mfma_f32_16x16x32_bf16 v[114:117], v[242:245], v[180:183], v[114:117]
	v_mfma_f32_16x16x32_bf16 v[102:105], v[234:237], v[204:207], v[102:105]
	v_mfma_f32_16x16x32_bf16 v[98:101], v[242:245], v[204:207], v[98:101]
	v_mfma_f32_16x16x32_bf16 v[86:89], v[234:237], v[212:215], v[86:89]
	v_mfma_f32_16x16x32_bf16 v[82:85], v[242:245], v[212:215], v[82:85]
	v_mfma_f32_16x16x32_bf16 v[70:73], v[234:237], v[226:229], v[70:73]
	v_mfma_f32_16x16x32_bf16 v[66:69], v[242:245], v[226:229], v[66:69]
	s_setprio 0
	s_mov_b32 m0, s84
	s_barrier
	ds_read_b128 v[176:179], v150 offset:49152
	ds_read_b128 v[180:183], v150 offset:50176
	ds_read_b128 v[184:187], v150 offset:51200
	ds_read_b128 v[204:207], v150 offset:52224
	ds_read_b128 v[208:211], v150 offset:53248
	ds_read_b128 v[212:215], v150 offset:54272
	ds_read_b128 v[216:219], v150 offset:55296
	ds_read_b128 v[226:229], v150 offset:56320
	global_load_lds_dwordx4 v134, vcc
	s_mov_b32 m0, s85
	s_nop 0
	global_load_lds_dwordx4 v132, vcc
	s_barrier
; #define PG8_STAGE(bufoff, gbase, voff) do { _Pragma("unroll") for (int _i = 0; _i < 2; ++_i) \
;         __builtin_amdgcn_global_load_lds((const unsigned*)((const char*)(gbase) + (voff)[_i]), (LAS unsigned*)(lds + (bufoff) + ldsw + _i * 8192), 16, 0, 0); } while (0)
; #define PG8_LDA(dst, b, h) do { _Pragma("unroll") for (int m = 0; m < 4; ++m) _Pragma("unroll") for (int k = 0; k < 2; ++k) dst[m][k] = *(const LAS bf16x8*)(lds + PG8_SA(b, h) + aoff + m * 2048 + k * 1024); } while (0)
; #define PG8_WAIT_V(n) asm volatile("s_waitcnt vmcnt(" #n ")" ::: "memory")
; #define PG8_WAIT_L(n) asm volatile("s_waitcnt lgkmcnt(" #n ")" ::: "memory")
; template <class Epi>
; __device__ __forceinline__ void gemm_phase(LAS unsigned char* lds, const Gemm g, const StaticOrder& S, const Epi& E) {
;     ...
;             const bool last = (t == nt - 2);
;             const char* a1 = cA + (size_t)(t + 1) * kstep;
;             const char* a2 = last ? nA : cA + (size_t)(t + 2) * kstep; const char* b2 = last ? nB : cB + (size_t)(t + 2) * kstep;
;             const char* a3 = a2 + kstep; const char* b3 = b2 + kstep;
;             PG8_LDB(B0, 0, 0); PG8_SCHED; PG8_LDA(At, 0, 0); PG8_STAGE(PG8_SA(1, 1), a1 + hstep, voffA);
;             PG8_WAIT_L(8); PG8_BAR; PG8_WAIT_L(0); PG8_MMA(0, 0, At, B0); PG8_BAR; PG8_SCHED;
;             PG8_LDB(B1, 0, 1); PG8_STAGE(PG8_SB(0, 0), b2, voffB);
;             PG8_BAR; PG8_WAIT_L(0); PG8_MMA(0, 1, At, B1); PG8_BAR;
;             PG8_LDA(At, 0, 1); PG8_STAGE(PG8_SA(0, 0), a2, voffA);
;             PG8_BAR; PG8_WAIT_L(0); PG8_MMA(1, 0, At, B0); PG8_BAR; PG8_SCHED;
;             PG8_STAGE(PG8_SB(0, 1), b2 + hstep, voffB);
;             PG8_WAIT_V(6); PG8_BAR; PG8_MMA(1, 1, At, B1); PG8_BAR;
;             PG8_LDB(B0, 1, 0); PG8_SCHED; PG8_LDA(At, 1, 0); PG8_STAGE(PG8_SA(0, 1), a2 + hstep, voffA);
;             PG8_WAIT_L(8); PG8_BAR; PG8_WAIT_L(0); PG8_MMA(0, 0, At, B0); PG8_BAR; PG8_SCHED;
;             PG8_LDB(B1, 1, 1); PG8_STAGE(PG8_SB(1, 0), b3, voffB);
;             PG8_BAR; PG8_WAIT_L(0); PG8_MMA(0, 1, At, B1); PG8_BAR;
;             PG8_LDA(At, 1, 1); PG8_STAGE(PG8_SA(1, 0), a3, voffA);
;             PG8_BAR; PG8_WAIT_L(0); PG8_MMA(1, 0, At, B0); PG8_BAR; PG8_SCHED;
;             PG8_STAGE(PG8_SB(1, 1), b3 + hstep, voffB);
;             PG8_WAIT_V(6); PG8_BAR; PG8_MMA(1, 1, At, B1); PG8_BAR;
;         }
	s_waitcnt lgkmcnt(0)
	s_setprio 1
	s_waitcnt lgkmcnt(0)
	v_mfma_f32_16x16x32_bf16 v[62:65], v[140:143], v[176:179], v[62:65]
	v_mfma_f32_16x16x32_bf16 v[58:61], v[168:171], v[176:179], v[58:61]
	v_mfma_f32_16x16x32_bf16 v[46:49], v[140:143], v[184:187], v[46:49]
	v_mfma_f32_16x16x32_bf16 v[42:45], v[168:171], v[184:187], v[42:45]
	v_mfma_f32_16x16x32_bf16 v[30:33], v[140:143], v[208:211], v[30:33]
	v_mfma_f32_16x16x32_bf16 v[26:29], v[168:171], v[208:211], v[26:29]
	v_mfma_f32_16x16x32_bf16 v[14:17], v[140:143], v[216:219], v[14:17]
	v_mfma_f32_16x16x32_bf16 v[10:13], v[168:171], v[216:219], v[10:13]
	v_mfma_f32_16x16x32_bf16 v[62:65], v[152:155], v[180:183], v[62:65]
	v_mfma_f32_16x16x32_bf16 v[58:61], v[172:175], v[180:183], v[58:61]
	v_mfma_f32_16x16x32_bf16 v[46:49], v[152:155], v[204:207], v[46:49]
	v_mfma_f32_16x16x32_bf16 v[42:45], v[172:175], v[204:207], v[42:45]
	v_mfma_f32_16x16x32_bf16 v[30:33], v[152:155], v[212:215], v[30:33]
	v_mfma_f32_16x16x32_bf16 v[26:29], v[172:175], v[212:215], v[26:29]
	v_mfma_f32_16x16x32_bf16 v[14:17], v[152:155], v[226:229], v[14:17]
	v_mfma_f32_16x16x32_bf16 v[10:13], v[172:175], v[226:229], v[10:13]
	s_setprio 0
	s_barrier
	s_add_u32 s6, s6, 0x40080
	s_addc_u32 s7, s7, 0
	s_add_i32 s42, s42, s48
	s_mov_b32 m0, s42
	s_nop 0
	global_load_lds_dwordx4 v0, s[6:7]
	s_add_i32 m0, s42, 0x2000
	s_nop 0
	global_load_lds_dwordx4 v130, s[6:7]
	s_waitcnt vmcnt(6)
	s_barrier
	s_setprio 1
	v_mfma_f32_16x16x32_bf16 v[54:57], v[230:233], v[176:179], v[54:57]
	v_mfma_f32_16x16x32_bf16 v[50:53], v[238:241], v[176:179], v[50:53]
	v_mfma_f32_16x16x32_bf16 v[38:41], v[230:233], v[184:187], v[38:41]
	v_mfma_f32_16x16x32_bf16 v[34:37], v[238:241], v[184:187], v[34:37]
	v_mfma_f32_16x16x32_bf16 v[22:25], v[230:233], v[208:211], v[22:25]
	v_mfma_f32_16x16x32_bf16 v[18:21], v[238:241], v[208:211], v[18:21]
	v_mfma_f32_16x16x32_bf16 v[6:9], v[230:233], v[216:219], v[6:9]
	v_mfma_f32_16x16x32_bf16 v[2:5], v[238:241], v[216:219], v[2:5]
	v_mfma_f32_16x16x32_bf16 v[54:57], v[234:237], v[180:183], v[54:57]
	v_mfma_f32_16x16x32_bf16 v[50:53], v[242:245], v[180:183], v[50:53]
	v_mfma_f32_16x16x32_bf16 v[38:41], v[234:237], v[204:207], v[38:41]
	v_mfma_f32_16x16x32_bf16 v[34:37], v[242:245], v[204:207], v[34:37]
	v_mfma_f32_16x16x32_bf16 v[22:25], v[234:237], v[212:215], v[22:25]
	v_mfma_f32_16x16x32_bf16 v[18:21], v[242:245], v[212:215], v[18:21]
	v_mfma_f32_16x16x32_bf16 v[6:9], v[234:237], v[226:229], v[6:9]
	v_mfma_f32_16x16x32_bf16 v[2:5], v[242:245], v[226:229], v[2:5]
	s_setprio 0
	s_add_i32 s93, s93, 2
	s_add_u32 s36, s36, 0x100
	s_addc_u32 s37, s37, 0
	s_add_u32 s91, s91, 0x100
	s_addc_u32 s92, s92, 0
	s_cmp_gt_u32 s93, 13
	s_barrier
	s_add_u32 s6, s36, 0xfffc0080
	s_addc_u32 s7, s37, -1
	s_add_i32 s58, 0, 0x10000
	v_add_u32_e32 v144, s58, v147
	ds_read_b128 v[140:143], v144
	ds_read_b128 v[152:155], v144 offset:1024
	ds_read_b128 v[168:171], v144 offset:2048
	ds_read_b128 v[172:175], v144 offset:3072
	s_cmp_eq_u32 s93, 12
	s_cselect_b32 s43, s11, s7
	s_cselect_b32 s42, s71, s6
	s_cselect_b32 s7, s9, s92
	s_cselect_b32 s6, s90, s91
	s_add_i32 m0, s49, 0xc000
	ds_read_b128 v[176:179], v150
	ds_read_b128 v[180:183], v150 offset:1024
	ds_read_b128 v[184:187], v150 offset:2048
	ds_read_b128 v[204:207], v150 offset:3072
	ds_read_b128 v[208:211], v150 offset:4096
	ds_read_b128 v[212:215], v150 offset:5120
	ds_read_b128 v[216:219], v150 offset:6144
	ds_read_b128 v[226:229], v150 offset:7168
	global_load_lds_dwordx4 v136, s[36:37]
	s_add_i32 m0, s49, 0xe000
	s_nop 0
	global_load_lds_dwordx4 v138, s[36:37]
	s_waitcnt lgkmcnt(8)
	s_barrier
	s_waitcnt lgkmcnt(0)
	s_setprio 1
	s_waitcnt lgkmcnt(0)
	v_mfma_f32_16x16x32_bf16 v[126:129], v[140:143], v[176:179], v[126:129]
	v_mfma_f32_16x16x32_bf16 v[122:125], v[168:171], v[176:179], v[122:125]
	v_mfma_f32_16x16x32_bf16 v[110:113], v[140:143], v[184:187], v[110:113]
	v_mfma_f32_16x16x32_bf16 v[106:109], v[168:171], v[184:187], v[106:109]
	v_mfma_f32_16x16x32_bf16 v[94:97], v[140:143], v[208:211], v[94:97]
	v_mfma_f32_16x16x32_bf16 v[90:93], v[168:171], v[208:211], v[90:93]
	v_mfma_f32_16x16x32_bf16 v[78:81], v[140:143], v[216:219], v[78:81]
	v_mfma_f32_16x16x32_bf16 v[74:77], v[168:171], v[216:219], v[74:77]
	v_mfma_f32_16x16x32_bf16 v[126:129], v[152:155], v[180:183], v[126:129]
	v_mfma_f32_16x16x32_bf16 v[122:125], v[172:175], v[180:183], v[122:125]
	v_mfma_f32_16x16x32_bf16 v[110:113], v[152:155], v[204:207], v[110:113]
	v_mfma_f32_16x16x32_bf16 v[106:109], v[172:175], v[204:207], v[106:109]
	v_mfma_f32_16x16x32_bf16 v[94:97], v[152:155], v[212:215], v[94:97]
	v_mfma_f32_16x16x32_bf16 v[90:93], v[172:175], v[212:215], v[90:93]
	v_mfma_f32_16x16x32_bf16 v[78:81], v[152:155], v[226:229], v[78:81]
	v_mfma_f32_16x16x32_bf16 v[74:77], v[172:175], v[226:229], v[74:77]
	s_setprio 0
	s_barrier
	s_add_i32 s70, 0, 0x14000
	v_add_u32_e32 v144, s70, v147
	s_add_i32 s58, s58, s48
	ds_read_b128 v[230:233], v144
	ds_read_b128 v[234:237], v144 offset:1024
	ds_read_b128 v[238:241], v144 offset:2048
	ds_read_b128 v[242:245], v144 offset:3072
	s_mov_b32 m0, s58
	s_nop 0
	global_load_lds_dwordx4 v0, s[6:7]
	s_add_i32 m0, s58, 0x2000
	s_nop 0
	global_load_lds_dwordx4 v130, s[6:7]
	s_barrier
; #define PG8_STAGE(bufoff, gbase, voff) do { _Pragma("unroll") for (int _i = 0; _i < 2; ++_i) \
;         __builtin_amdgcn_global_load_lds((const unsigned*)((const char*)(gbase) + (voff)[_i]), (LAS unsigned*)(lds + (bufoff) + ldsw + _i * 8192), 16, 0, 0); } while (0)
; #define PG8_LDA(dst, b, h) do { _Pragma("unroll") for (int m = 0; m < 4; ++m) _Pragma("unroll") for (int k = 0; k < 2; ++k) dst[m][k] = *(const LAS bf16x8*)(lds + PG8_SA(b, h) + aoff + m * 2048 + k * 1024); } while (0)
; #define PG8_LDB(dst, b, h) do { _Pragma("unroll") for (int n = 0; n < 2; ++n) _Pragma("unroll") for (int k = 0; k < 2; ++k) dst[n][k] = *(const LAS bf16x8*)(lds + PG8_SB(b, h) + boff + n * 2048 + k * 1024); } while (0)
; #define PG8_MMA(ai, bj, At, Bt) do { __builtin_amdgcn_s_setprio(1); _Pragma("unroll") for (int m = 0; m < 4; ++m) _Pragma("unroll") for (int n = 0; n < 2; ++n) _Pragma("unroll") for (int k = 0; k < 2; ++k) \
;         acc[ai][bj][m][n] = __builtin_amdgcn_mfma_f32_16x16x32_bf16(Bt[n][k], At[m][k], acc[ai][bj][m][n], 0, 0, 0); __builtin_amdgcn_s_setprio(0); } while (0)
; #define PG8_WAIT_V(n) asm volatile("s_waitcnt vmcnt(" #n ")" ::: "memory")
; #define PG8_WAIT_L(n) asm volatile("s_waitcnt lgkmcnt(" #n ")" ::: "memory")
; #define PG8_BAR __builtin_amdgcn_s_barrier()
; #define PG8_SCHED __builtin_amdgcn_sched_barrier(0)
; template <class Epi>
; __device__ __forceinline__ void gemm_phase(LAS unsigned char* lds, const Gemm g, const StaticOrder& S, const Epi& E) {
;     ...
;             PG8_BAR; PG8_WAIT_L(0); PG8_MMA(0, 1, At, B1); PG8_BAR;
;             PG8_LDA(At, 0, 1); PG8_STAGE(PG8_SA(0, 0), a2, voffA);
;             PG8_BAR; PG8_WAIT_L(0); PG8_MMA(1, 0, At, B0); PG8_BAR; PG8_SCHED;
;             PG8_STAGE(PG8_SB(0, 1), b2 + hstep, voffB);
;             PG8_WAIT_V(6); PG8_BAR; PG8_MMA(1, 1, At, B1); PG8_BAR;
;             PG8_LDB(B0, 1, 0); PG8_SCHED; PG8_LDA(At, 1, 0); PG8_STAGE(PG8_SA(0, 1), a2 + hstep, voffA);
;             PG8_WAIT_L(8); PG8_BAR; PG8_WAIT_L(0); PG8_MMA(0, 0, At, B0); PG8_BAR; PG8_SCHED;
;             PG8_LDB(B1, 1, 1); PG8_STAGE(PG8_SB(1, 0), b3, voffB);
;             PG8_BAR; PG8_WAIT_L(0); PG8_MMA(0, 1, At, B1); PG8_BAR;
;             PG8_LDA(At, 1, 1); PG8_STAGE(PG8_SA(1, 0), a3, voffA);
;             PG8_BAR; PG8_WAIT_L(0); PG8_MMA(1, 0, At, B0); PG8_BAR; PG8_SCHED;
	s_waitcnt lgkmcnt(0)
	s_setprio 1
	s_waitcnt lgkmcnt(0)
	v_mfma_f32_16x16x32_bf16 v[118:121], v[230:233], v[176:179], v[118:121]
	v_mfma_f32_16x16x32_bf16 v[114:117], v[238:241], v[176:179], v[114:117]
	v_mfma_f32_16x16x32_bf16 v[102:105], v[230:233], v[184:187], v[102:105]
	v_mfma_f32_16x16x32_bf16 v[98:101], v[238:241], v[184:187], v[98:101]
	v_mfma_f32_16x16x32_bf16 v[86:89], v[230:233], v[208:211], v[86:89]
	v_mfma_f32_16x16x32_bf16 v[82:85], v[238:241], v[208:211], v[82:85]
	v_mfma_f32_16x16x32_bf16 v[70:73], v[230:233], v[216:219], v[70:73]
	v_mfma_f32_16x16x32_bf16 v[66:69], v[238:241], v[216:219], v[66:69]
	v_mfma_f32_16x16x32_bf16 v[118:121], v[234:237], v[180:183], v[118:121]
	v_mfma_f32_16x16x32_bf16 v[114:117], v[242:245], v[180:183], v[114:117]
	v_mfma_f32_16x16x32_bf16 v[102:105], v[234:237], v[204:207], v[102:105]
	v_mfma_f32_16x16x32_bf16 v[98:101], v[242:245], v[204:207], v[98:101]
	v_mfma_f32_16x16x32_bf16 v[86:89], v[234:237], v[212:215], v[86:89]
	v_mfma_f32_16x16x32_bf16 v[82:85], v[242:245], v[212:215], v[82:85]
	v_mfma_f32_16x16x32_bf16 v[70:73], v[234:237], v[226:229], v[70:73]
	v_mfma_f32_16x16x32_bf16 v[66:69], v[242:245], v[226:229], v[66:69]
	s_setprio 0
	s_mov_b32 m0, s49
	s_add_u32 vcc_lo, s42, 0x80
	s_addc_u32 vcc_hi, s43, 0
	s_barrier
	ds_read_b128 v[176:179], v150 offset:16384
	ds_read_b128 v[180:183], v150 offset:17408
	ds_read_b128 v[184:187], v150 offset:18432
	ds_read_b128 v[204:207], v150 offset:19456
	ds_read_b128 v[208:211], v150 offset:20480
	ds_read_b128 v[212:215], v150 offset:21504
	ds_read_b128 v[216:219], v150 offset:22528
	ds_read_b128 v[226:229], v150 offset:23552
	global_load_lds_dwordx4 v134, s[42:43]
	s_mov_b32 m0, s54
	s_nop 0
	global_load_lds_dwordx4 v132, s[42:43]
	s_barrier
	s_waitcnt lgkmcnt(0)
	s_setprio 1
	s_waitcnt lgkmcnt(0)
	v_mfma_f32_16x16x32_bf16 v[62:65], v[140:143], v[176:179], v[62:65]
	v_mfma_f32_16x16x32_bf16 v[58:61], v[168:171], v[176:179], v[58:61]
	v_mfma_f32_16x16x32_bf16 v[46:49], v[140:143], v[184:187], v[46:49]
	v_mfma_f32_16x16x32_bf16 v[42:45], v[168:171], v[184:187], v[42:45]
	v_mfma_f32_16x16x32_bf16 v[30:33], v[140:143], v[208:211], v[30:33]
	v_mfma_f32_16x16x32_bf16 v[26:29], v[168:171], v[208:211], v[26:29]
	v_mfma_f32_16x16x32_bf16 v[14:17], v[140:143], v[216:219], v[14:17]
	v_mfma_f32_16x16x32_bf16 v[10:13], v[168:171], v[216:219], v[10:13]
	v_mfma_f32_16x16x32_bf16 v[62:65], v[152:155], v[180:183], v[62:65]
	v_mfma_f32_16x16x32_bf16 v[58:61], v[172:175], v[180:183], v[58:61]
	v_mfma_f32_16x16x32_bf16 v[46:49], v[152:155], v[204:207], v[46:49]
	v_mfma_f32_16x16x32_bf16 v[42:45], v[172:175], v[204:207], v[42:45]
	v_mfma_f32_16x16x32_bf16 v[30:33], v[152:155], v[212:215], v[30:33]
	v_mfma_f32_16x16x32_bf16 v[26:29], v[172:175], v[212:215], v[26:29]
	v_mfma_f32_16x16x32_bf16 v[14:17], v[152:155], v[226:229], v[14:17]
	v_mfma_f32_16x16x32_bf16 v[10:13], v[172:175], v[226:229], v[10:13]
	s_setprio 0
	s_barrier
	s_add_u32 s60, s6, 0x40000
	s_addc_u32 s61, s7, 0
	s_add_i32 s58, s70, s48
	s_mov_b32 m0, s58
	s_nop 0
	global_load_lds_dwordx4 v0, s[60:61]
	s_add_i32 m0, s58, 0x2000
	s_nop 0
	global_load_lds_dwordx4 v130, s[60:61]
	s_waitcnt vmcnt(6)
	s_barrier
	s_setprio 1
	v_mfma_f32_16x16x32_bf16 v[54:57], v[230:233], v[176:179], v[54:57]
	v_mfma_f32_16x16x32_bf16 v[50:53], v[238:241], v[176:179], v[50:53]
	s_cmp_eq_u32 s89, 0
	s_cbranch_scc1 .LdsE_skip_1
	global_store_dwordx4 v250, v[164:167], s[4:5] offset:256
	v_add_u32_e32 v250, 0x20000, v250
.LdsE_skip_1:
	v_mfma_f32_16x16x32_bf16 v[38:41], v[230:233], v[184:187], v[38:41]
	v_mfma_f32_16x16x32_bf16 v[34:37], v[238:241], v[184:187], v[34:37]
	v_mfma_f32_16x16x32_bf16 v[22:25], v[230:233], v[208:211], v[22:25]
	v_mfma_f32_16x16x32_bf16 v[18:21], v[238:241], v[208:211], v[18:21]
	v_mfma_f32_16x16x32_bf16 v[6:9], v[230:233], v[216:219], v[6:9]
	v_mfma_f32_16x16x32_bf16 v[2:5], v[238:241], v[216:219], v[2:5]
	v_mfma_f32_16x16x32_bf16 v[54:57], v[234:237], v[180:183], v[54:57]
	v_mfma_f32_16x16x32_bf16 v[50:53], v[242:245], v[180:183], v[50:53]
	v_mfma_f32_16x16x32_bf16 v[38:41], v[234:237], v[204:207], v[38:41]
	v_mfma_f32_16x16x32_bf16 v[34:37], v[242:245], v[204:207], v[34:37]
	v_mfma_f32_16x16x32_bf16 v[22:25], v[234:237], v[212:215], v[22:25]
	v_mfma_f32_16x16x32_bf16 v[18:21], v[242:245], v[212:215], v[18:21]
	v_mfma_f32_16x16x32_bf16 v[6:9], v[234:237], v[226:229], v[6:9]
	v_mfma_f32_16x16x32_bf16 v[2:5], v[242:245], v[226:229], v[2:5]
	s_setprio 0
	s_add_i32 s58, 0, 0x18000
	v_add_u32_e32 v151, s58, v147
	s_barrier
	ds_read_b128 v[140:143], v151
	ds_read_b128 v[152:155], v151 offset:1024
	ds_read_b128 v[168:171], v151 offset:2048
	ds_read_b128 v[172:175], v151 offset:3072
	s_add_u32 s42, s42, 0x40000
	s_addc_u32 s43, s43, 0
	s_mov_b32 m0, s55
	ds_read_b128 v[176:179], v150 offset:32768
	ds_read_b128 v[180:183], v150 offset:33792
	ds_read_b128 v[184:187], v150 offset:34816
	ds_read_b128 v[204:207], v150 offset:35840
	ds_read_b128 v[208:211], v150 offset:36864
	ds_read_b128 v[212:215], v150 offset:37888
	ds_read_b128 v[216:219], v150 offset:38912
	ds_read_b128 v[226:229], v150 offset:39936
	global_load_lds_dwordx4 v134, s[42:43]
	s_mov_b32 m0, s83
	s_nop 0
	global_load_lds_dwordx4 v132, s[42:43]
	s_waitcnt lgkmcnt(8)
	s_barrier
; #define PG8_STAGE(bufoff, gbase, voff) do { _Pragma("unroll") for (int _i = 0; _i < 2; ++_i) \
;         __builtin_amdgcn_global_load_lds((const unsigned*)((const char*)(gbase) + (voff)[_i]), (LAS unsigned*)(lds + (bufoff) + ldsw + _i * 8192), 16, 0, 0); } while (0)
; #define PG8_LDA(dst, b, h) do { _Pragma("unroll") for (int m = 0; m < 4; ++m) _Pragma("unroll") for (int k = 0; k < 2; ++k) dst[m][k] = *(const LAS bf16x8*)(lds + PG8_SA(b, h) + aoff + m * 2048 + k * 1024); } while (0)
; #define PG8_LDB(dst, b, h) do { _Pragma("unroll") for (int n = 0; n < 2; ++n) _Pragma("unroll") for (int k = 0; k < 2; ++k) dst[n][k] = *(const LAS bf16x8*)(lds + PG8_SB(b, h) + boff + n * 2048 + k * 1024); } while (0)
; #define PG8_MMA(ai, bj, At, Bt) do { __builtin_amdgcn_s_setprio(1); _Pragma("unroll") for (int m = 0; m < 4; ++m) _Pragma("unroll") for (int n = 0; n < 2; ++n) _Pragma("unroll") for (int k = 0; k < 2; ++k) \
;         acc[ai][bj][m][n] = __builtin_amdgcn_mfma_f32_16x16x32_bf16(Bt[n][k], At[m][k], acc[ai][bj][m][n], 0, 0, 0); __builtin_amdgcn_s_setprio(0); } while (0)
; #define PG8_WAIT_V(n) asm volatile("s_waitcnt vmcnt(" #n ")" ::: "memory")
; #define PG8_WAIT_L(n) asm volatile("s_waitcnt lgkmcnt(" #n ")" ::: "memory")
; #define PG8_BAR __builtin_amdgcn_s_barrier()
; #define PG8_SCHED __builtin_amdgcn_sched_barrier(0)
; template <class Epi>
; __device__ __forceinline__ void gemm_phase(LAS unsigned char* lds, const Gemm g, const StaticOrder& S, const Epi& E) {
;     ...
;             PG8_WAIT_L(8); PG8_BAR; PG8_WAIT_L(0); PG8_MMA(0, 0, At, B0); PG8_BAR; PG8_SCHED;
;             PG8_LDB(B1, 1, 1); PG8_STAGE(PG8_SB(1, 0), b3, voffB);
;             PG8_BAR; PG8_WAIT_L(0); PG8_MMA(0, 1, At, B1); PG8_BAR;
;             PG8_LDA(At, 1, 1); PG8_STAGE(PG8_SA(1, 0), a3, voffA);
;             PG8_BAR; PG8_WAIT_L(0); PG8_MMA(1, 0, At, B0); PG8_BAR; PG8_SCHED;
;             PG8_STAGE(PG8_SB(1, 1), b3 + hstep, voffB);
;             PG8_WAIT_V(6); PG8_BAR; PG8_MMA(1, 1, At, B1); PG8_BAR;
;         }
	s_waitcnt lgkmcnt(0)
	s_setprio 1
	s_waitcnt lgkmcnt(0)
	v_mfma_f32_16x16x32_bf16 v[126:129], v[140:143], v[176:179], v[126:129]
	v_mfma_f32_16x16x32_bf16 v[122:125], v[168:171], v[176:179], v[122:125]
	v_mfma_f32_16x16x32_bf16 v[110:113], v[140:143], v[184:187], v[110:113]
	v_mfma_f32_16x16x32_bf16 v[106:109], v[168:171], v[184:187], v[106:109]
	v_mfma_f32_16x16x32_bf16 v[94:97], v[140:143], v[208:211], v[94:97]
	v_mfma_f32_16x16x32_bf16 v[90:93], v[168:171], v[208:211], v[90:93]
	v_mfma_f32_16x16x32_bf16 v[78:81], v[140:143], v[216:219], v[78:81]
	v_mfma_f32_16x16x32_bf16 v[74:77], v[168:171], v[216:219], v[74:77]
	v_mfma_f32_16x16x32_bf16 v[126:129], v[152:155], v[180:183], v[126:129]
	v_mfma_f32_16x16x32_bf16 v[122:125], v[172:175], v[180:183], v[122:125]
	v_mfma_f32_16x16x32_bf16 v[110:113], v[152:155], v[204:207], v[110:113]
	v_mfma_f32_16x16x32_bf16 v[106:109], v[172:175], v[204:207], v[106:109]
	v_mfma_f32_16x16x32_bf16 v[94:97], v[152:155], v[212:215], v[94:97]
	v_mfma_f32_16x16x32_bf16 v[90:93], v[172:175], v[212:215], v[90:93]
	v_mfma_f32_16x16x32_bf16 v[78:81], v[152:155], v[226:229], v[78:81]
	v_mfma_f32_16x16x32_bf16 v[74:77], v[172:175], v[226:229], v[74:77]
	s_setprio 0
	s_barrier
	s_add_i32 s42, 0, 0x1c000
	s_add_i32 s43, s58, s48
	v_add_u32_e32 v151, s42, v147
	s_add_u32 s60, s6, 0x80
	s_addc_u32 s61, s7, 0
	s_mov_b32 m0, s43
	ds_read_b128 v[230:233], v151
	ds_read_b128 v[234:237], v151 offset:1024
	ds_read_b128 v[238:241], v151 offset:2048
	ds_read_b128 v[242:245], v151 offset:3072
	global_load_lds_dwordx4 v0, s[60:61]
	s_add_i32 m0, s43, 0x2000
	s_nop 0
	global_load_lds_dwordx4 v130, s[60:61]
	s_barrier
	s_waitcnt lgkmcnt(0)
	s_setprio 1
	s_waitcnt lgkmcnt(0)
	v_mfma_f32_16x16x32_bf16 v[118:121], v[230:233], v[176:179], v[118:121]
	v_mfma_f32_16x16x32_bf16 v[114:117], v[238:241], v[176:179], v[114:117]
	v_mfma_f32_16x16x32_bf16 v[102:105], v[230:233], v[184:187], v[102:105]
	v_mfma_f32_16x16x32_bf16 v[98:101], v[238:241], v[184:187], v[98:101]
	v_mfma_f32_16x16x32_bf16 v[86:89], v[230:233], v[208:211], v[86:89]
	v_mfma_f32_16x16x32_bf16 v[82:85], v[238:241], v[208:211], v[82:85]
	v_mfma_f32_16x16x32_bf16 v[70:73], v[230:233], v[216:219], v[70:73]
	v_mfma_f32_16x16x32_bf16 v[66:69], v[238:241], v[216:219], v[66:69]
	v_mfma_f32_16x16x32_bf16 v[118:121], v[234:237], v[180:183], v[118:121]
	v_mfma_f32_16x16x32_bf16 v[114:117], v[242:245], v[180:183], v[114:117]
	v_mfma_f32_16x16x32_bf16 v[102:105], v[234:237], v[204:207], v[102:105]
	v_mfma_f32_16x16x32_bf16 v[98:101], v[242:245], v[204:207], v[98:101]
	v_mfma_f32_16x16x32_bf16 v[86:89], v[234:237], v[212:215], v[86:89]
	v_mfma_f32_16x16x32_bf16 v[82:85], v[242:245], v[212:215], v[82:85]
	v_mfma_f32_16x16x32_bf16 v[70:73], v[234:237], v[226:229], v[70:73]
	v_mfma_f32_16x16x32_bf16 v[66:69], v[242:245], v[226:229], v[66:69]
	s_setprio 0
	s_mov_b32 m0, s84
	s_barrier
	ds_read_b128 v[176:179], v150 offset:49152
	ds_read_b128 v[180:183], v150 offset:50176
	ds_read_b128 v[184:187], v150 offset:51200
	ds_read_b128 v[204:207], v150 offset:52224
	ds_read_b128 v[208:211], v150 offset:53248
	ds_read_b128 v[212:215], v150 offset:54272
	ds_read_b128 v[216:219], v150 offset:55296
	ds_read_b128 v[226:229], v150 offset:56320
	global_load_lds_dwordx4 v134, vcc
	s_mov_b32 m0, s85
	s_nop 0
	global_load_lds_dwordx4 v132, vcc
	s_barrier
	s_waitcnt lgkmcnt(0)
	s_setprio 1
	s_waitcnt lgkmcnt(0)
	v_mfma_f32_16x16x32_bf16 v[62:65], v[140:143], v[176:179], v[62:65]
	v_mfma_f32_16x16x32_bf16 v[58:61], v[168:171], v[176:179], v[58:61]
	v_mfma_f32_16x16x32_bf16 v[46:49], v[140:143], v[184:187], v[46:49]
	v_mfma_f32_16x16x32_bf16 v[42:45], v[168:171], v[184:187], v[42:45]
	v_mfma_f32_16x16x32_bf16 v[30:33], v[140:143], v[208:211], v[30:33]
	v_mfma_f32_16x16x32_bf16 v[26:29], v[168:171], v[208:211], v[26:29]
	v_mfma_f32_16x16x32_bf16 v[14:17], v[140:143], v[216:219], v[14:17]
	v_mfma_f32_16x16x32_bf16 v[10:13], v[168:171], v[216:219], v[10:13]
	v_mfma_f32_16x16x32_bf16 v[62:65], v[152:155], v[180:183], v[62:65]
	v_mfma_f32_16x16x32_bf16 v[58:61], v[172:175], v[180:183], v[58:61]
	v_mfma_f32_16x16x32_bf16 v[46:49], v[152:155], v[204:207], v[46:49]
	v_mfma_f32_16x16x32_bf16 v[42:45], v[172:175], v[204:207], v[42:45]
	v_mfma_f32_16x16x32_bf16 v[30:33], v[152:155], v[212:215], v[30:33]
	v_mfma_f32_16x16x32_bf16 v[26:29], v[172:175], v[212:215], v[26:29]
	v_mfma_f32_16x16x32_bf16 v[14:17], v[152:155], v[226:229], v[14:17]
	v_mfma_f32_16x16x32_bf16 v[10:13], v[172:175], v[226:229], v[10:13]
	s_setprio 0
	s_barrier
	s_add_u32 s6, s6, 0x40080
	s_addc_u32 s7, s7, 0
	s_add_i32 s42, s42, s48
	s_mov_b32 m0, s42
	s_nop 0
	global_load_lds_dwordx4 v0, s[6:7]
	s_add_i32 m0, s42, 0x2000
	s_nop 0
	global_load_lds_dwordx4 v130, s[6:7]
	s_waitcnt vmcnt(6)
	s_barrier
	s_setprio 1
	v_mfma_f32_16x16x32_bf16 v[54:57], v[230:233], v[176:179], v[54:57]
	v_mfma_f32_16x16x32_bf16 v[50:53], v[238:241], v[176:179], v[50:53]
	v_mfma_f32_16x16x32_bf16 v[38:41], v[230:233], v[184:187], v[38:41]
	v_mfma_f32_16x16x32_bf16 v[34:37], v[238:241], v[184:187], v[34:37]
	v_mfma_f32_16x16x32_bf16 v[22:25], v[230:233], v[208:211], v[22:25]
	v_mfma_f32_16x16x32_bf16 v[18:21], v[238:241], v[208:211], v[18:21]
	v_mfma_f32_16x16x32_bf16 v[6:9], v[230:233], v[216:219], v[6:9]
	v_mfma_f32_16x16x32_bf16 v[2:5], v[238:241], v[216:219], v[2:5]
	v_mfma_f32_16x16x32_bf16 v[54:57], v[234:237], v[180:183], v[54:57]
	v_mfma_f32_16x16x32_bf16 v[50:53], v[242:245], v[180:183], v[50:53]
	v_mfma_f32_16x16x32_bf16 v[38:41], v[234:237], v[204:207], v[38:41]
	v_mfma_f32_16x16x32_bf16 v[34:37], v[242:245], v[204:207], v[34:37]
	v_mfma_f32_16x16x32_bf16 v[22:25], v[234:237], v[212:215], v[22:25]
	v_mfma_f32_16x16x32_bf16 v[18:21], v[242:245], v[212:215], v[18:21]
	v_mfma_f32_16x16x32_bf16 v[6:9], v[234:237], v[226:229], v[6:9]
	v_mfma_f32_16x16x32_bf16 v[2:5], v[242:245], v[226:229], v[2:5]
	s_setprio 0
	s_add_i32 s93, s93, 2
	s_add_u32 s36, s36, 0x100
	s_addc_u32 s37, s37, 0
	s_add_u32 s91, s91, 0x100
	s_addc_u32 s92, s92, 0
	s_cmp_gt_u32 s93, 13
	s_barrier
; #define PG8_STAGE(bufoff, gbase, voff) do { _Pragma("unroll") for (int _i = 0; _i < 2; ++_i) \
;         __builtin_amdgcn_global_load_lds((const unsigned*)((const char*)(gbase) + (voff)[_i]), (LAS unsigned*)(lds + (bufoff) + ldsw + _i * 8192), 16, 0, 0); } while (0)
; #define PG8_LDA(dst, b, h) do { _Pragma("unroll") for (int m = 0; m < 4; ++m) _Pragma("unroll") for (int k = 0; k < 2; ++k) dst[m][k] = *(const LAS bf16x8*)(lds + PG8_SA(b, h) + aoff + m * 2048 + k * 1024); } while (0)
; #define PG8_LDB(dst, b, h) do { _Pragma("unroll") for (int n = 0; n < 2; ++n) _Pragma("unroll") for (int k = 0; k < 2; ++k) dst[n][k] = *(const LAS bf16x8*)(lds + PG8_SB(b, h) + boff + n * 2048 + k * 1024); } while (0)
; #define PG8_MMA(ai, bj, At, Bt) do { __builtin_amdgcn_s_setprio(1); _Pragma("unroll") for (int m = 0; m < 4; ++m) _Pragma("unroll") for (int n = 0; n < 2; ++n) _Pragma("unroll") for (int k = 0; k < 2; ++k) \
;         acc[ai][bj][m][n] = __builtin_amdgcn_mfma_f32_16x16x32_bf16(Bt[n][k], At[m][k], acc[ai][bj][m][n], 0, 0, 0); __builtin_amdgcn_s_setprio(0); } while (0)
; #define PG8_WAIT_V(n) asm volatile("s_waitcnt vmcnt(" #n ")" ::: "memory")
; #define PG8_WAIT_L(n) asm volatile("s_waitcnt lgkmcnt(" #n ")" ::: "memory")
; #define PG8_BAR __builtin_amdgcn_s_barrier()
; template <class Epi>
; __device__ __forceinline__ void gemm_phase(LAS unsigned char* lds, const Gemm g, const StaticOrder& S, const Epi& E) {
;     ...
;             const bool last = (t == nt - 2);
;             const char* a1 = cA + (size_t)(t + 1) * kstep;
;             const char* a2 = last ? nA : cA + (size_t)(t + 2) * kstep; const char* b2 = last ? nB : cB + (size_t)(t + 2) * kstep;
;             const char* a3 = a2 + kstep; const char* b3 = b2 + kstep;
;             PG8_LDB(B0, 0, 0); PG8_SCHED; PG8_LDA(At, 0, 0); PG8_STAGE(PG8_SA(1, 1), a1 + hstep, voffA);
;             PG8_WAIT_L(8); PG8_BAR; PG8_WAIT_L(0); PG8_MMA(0, 0, At, B0); PG8_BAR; PG8_SCHED;
;             PG8_LDB(B1, 0, 1); PG8_STAGE(PG8_SB(0, 0), b2, voffB);
;             PG8_BAR; PG8_WAIT_L(0); PG8_MMA(0, 1, At, B1); PG8_BAR;
;             PG8_LDA(At, 0, 1); PG8_STAGE(PG8_SA(0, 0), a2, voffA);
;             PG8_BAR; PG8_WAIT_L(0); PG8_MMA(1, 0, At, B0); PG8_BAR; PG8_SCHED;
;             PG8_STAGE(PG8_SB(0, 1), b2 + hstep, voffB);
;             PG8_WAIT_V(6); PG8_BAR; PG8_MMA(1, 1, At, B1); PG8_BAR;
	s_add_u32 s6, s36, 0xfffc0080
	s_addc_u32 s7, s37, -1
	s_add_i32 s58, 0, 0x10000
	v_add_u32_e32 v144, s58, v147
	ds_read_b128 v[140:143], v144
	ds_read_b128 v[152:155], v144 offset:1024
	ds_read_b128 v[168:171], v144 offset:2048
	ds_read_b128 v[172:175], v144 offset:3072
	s_cmp_eq_u32 s93, 12
	s_cselect_b32 s43, s11, s7
	s_cselect_b32 s42, s71, s6
	s_cselect_b32 s7, s9, s92
	s_cselect_b32 s6, s90, s91
	s_add_i32 m0, s49, 0xc000
	ds_read_b128 v[176:179], v150
	ds_read_b128 v[180:183], v150 offset:1024
	ds_read_b128 v[184:187], v150 offset:2048
	ds_read_b128 v[204:207], v150 offset:3072
	ds_read_b128 v[208:211], v150 offset:4096
	ds_read_b128 v[212:215], v150 offset:5120
	ds_read_b128 v[216:219], v150 offset:6144
	ds_read_b128 v[226:229], v150 offset:7168
	global_load_lds_dwordx4 v136, s[36:37]
	s_add_i32 m0, s49, 0xe000
	s_nop 0
	global_load_lds_dwordx4 v138, s[36:37]
	s_waitcnt lgkmcnt(8)
	s_barrier
	s_waitcnt lgkmcnt(0)
	s_setprio 1
	s_waitcnt lgkmcnt(0)
	v_mfma_f32_16x16x32_bf16 v[126:129], v[140:143], v[176:179], v[126:129]
	v_mfma_f32_16x16x32_bf16 v[122:125], v[168:171], v[176:179], v[122:125]
	v_mfma_f32_16x16x32_bf16 v[110:113], v[140:143], v[184:187], v[110:113]
	v_mfma_f32_16x16x32_bf16 v[106:109], v[168:171], v[184:187], v[106:109]
	v_mfma_f32_16x16x32_bf16 v[94:97], v[140:143], v[208:211], v[94:97]
	v_mfma_f32_16x16x32_bf16 v[90:93], v[168:171], v[208:211], v[90:93]
	v_mfma_f32_16x16x32_bf16 v[78:81], v[140:143], v[216:219], v[78:81]
	v_mfma_f32_16x16x32_bf16 v[74:77], v[168:171], v[216:219], v[74:77]
	v_mfma_f32_16x16x32_bf16 v[126:129], v[152:155], v[180:183], v[126:129]
	v_mfma_f32_16x16x32_bf16 v[122:125], v[172:175], v[180:183], v[122:125]
	v_mfma_f32_16x16x32_bf16 v[110:113], v[152:155], v[204:207], v[110:113]
	v_mfma_f32_16x16x32_bf16 v[106:109], v[172:175], v[204:207], v[106:109]
	v_mfma_f32_16x16x32_bf16 v[94:97], v[152:155], v[212:215], v[94:97]
	v_mfma_f32_16x16x32_bf16 v[90:93], v[172:175], v[212:215], v[90:93]
	v_mfma_f32_16x16x32_bf16 v[78:81], v[152:155], v[226:229], v[78:81]
	v_mfma_f32_16x16x32_bf16 v[74:77], v[172:175], v[226:229], v[74:77]
	s_setprio 0
	s_barrier
	s_add_i32 s70, 0, 0x14000
	v_add_u32_e32 v144, s70, v147
	s_add_i32 s58, s58, s48
	ds_read_b128 v[230:233], v144
	ds_read_b128 v[234:237], v144 offset:1024
	ds_read_b128 v[238:241], v144 offset:2048
	ds_read_b128 v[242:245], v144 offset:3072
	s_mov_b32 m0, s58
	s_nop 0
	global_load_lds_dwordx4 v0, s[6:7]
	s_add_i32 m0, s58, 0x2000
	s_nop 0
	global_load_lds_dwordx4 v130, s[6:7]
	s_barrier
	s_waitcnt lgkmcnt(0)
	s_setprio 1
	s_waitcnt lgkmcnt(0)
	v_mfma_f32_16x16x32_bf16 v[118:121], v[230:233], v[176:179], v[118:121]
	v_mfma_f32_16x16x32_bf16 v[114:117], v[238:241], v[176:179], v[114:117]
	v_mfma_f32_16x16x32_bf16 v[102:105], v[230:233], v[184:187], v[102:105]
	v_mfma_f32_16x16x32_bf16 v[98:101], v[238:241], v[184:187], v[98:101]
	v_mfma_f32_16x16x32_bf16 v[86:89], v[230:233], v[208:211], v[86:89]
	v_mfma_f32_16x16x32_bf16 v[82:85], v[238:241], v[208:211], v[82:85]
	v_mfma_f32_16x16x32_bf16 v[70:73], v[230:233], v[216:219], v[70:73]
	v_mfma_f32_16x16x32_bf16 v[66:69], v[238:241], v[216:219], v[66:69]
	v_mfma_f32_16x16x32_bf16 v[118:121], v[234:237], v[180:183], v[118:121]
	v_mfma_f32_16x16x32_bf16 v[114:117], v[242:245], v[180:183], v[114:117]
	v_mfma_f32_16x16x32_bf16 v[102:105], v[234:237], v[204:207], v[102:105]
	v_mfma_f32_16x16x32_bf16 v[98:101], v[242:245], v[204:207], v[98:101]
	v_mfma_f32_16x16x32_bf16 v[86:89], v[234:237], v[212:215], v[86:89]
	v_mfma_f32_16x16x32_bf16 v[82:85], v[242:245], v[212:215], v[82:85]
	v_mfma_f32_16x16x32_bf16 v[70:73], v[234:237], v[226:229], v[70:73]
	v_mfma_f32_16x16x32_bf16 v[66:69], v[242:245], v[226:229], v[66:69]
	s_setprio 0
	s_mov_b32 m0, s49
	s_add_u32 vcc_lo, s42, 0x80
	s_addc_u32 vcc_hi, s43, 0
	s_barrier
	ds_read_b128 v[176:179], v150 offset:16384
	ds_read_b128 v[180:183], v150 offset:17408
	ds_read_b128 v[184:187], v150 offset:18432
	ds_read_b128 v[204:207], v150 offset:19456
	ds_read_b128 v[208:211], v150 offset:20480
	ds_read_b128 v[212:215], v150 offset:21504
	ds_read_b128 v[216:219], v150 offset:22528
	ds_read_b128 v[226:229], v150 offset:23552
	global_load_lds_dwordx4 v134, s[42:43]
	s_mov_b32 m0, s54
	s_nop 0
	global_load_lds_dwordx4 v132, s[42:43]
	s_barrier
	s_waitcnt lgkmcnt(0)
	s_setprio 1
	s_waitcnt lgkmcnt(0)
	v_mfma_f32_16x16x32_bf16 v[62:65], v[140:143], v[176:179], v[62:65]
	v_mfma_f32_16x16x32_bf16 v[58:61], v[168:171], v[176:179], v[58:61]
	v_mfma_f32_16x16x32_bf16 v[46:49], v[140:143], v[184:187], v[46:49]
	v_mfma_f32_16x16x32_bf16 v[42:45], v[168:171], v[184:187], v[42:45]
	v_mfma_f32_16x16x32_bf16 v[30:33], v[140:143], v[208:211], v[30:33]
	v_mfma_f32_16x16x32_bf16 v[26:29], v[168:171], v[208:211], v[26:29]
	v_mfma_f32_16x16x32_bf16 v[14:17], v[140:143], v[216:219], v[14:17]
	v_mfma_f32_16x16x32_bf16 v[10:13], v[168:171], v[216:219], v[10:13]
	v_mfma_f32_16x16x32_bf16 v[62:65], v[152:155], v[180:183], v[62:65]
	v_mfma_f32_16x16x32_bf16 v[58:61], v[172:175], v[180:183], v[58:61]
	v_mfma_f32_16x16x32_bf16 v[46:49], v[152:155], v[204:207], v[46:49]
	v_mfma_f32_16x16x32_bf16 v[42:45], v[172:175], v[204:207], v[42:45]
	v_mfma_f32_16x16x32_bf16 v[30:33], v[152:155], v[212:215], v[30:33]
	v_mfma_f32_16x16x32_bf16 v[26:29], v[172:175], v[212:215], v[26:29]
	v_mfma_f32_16x16x32_bf16 v[14:17], v[152:155], v[226:229], v[14:17]
	v_mfma_f32_16x16x32_bf16 v[10:13], v[172:175], v[226:229], v[10:13]
	s_setprio 0
	s_barrier
	s_add_u32 s60, s6, 0x40000
	s_addc_u32 s61, s7, 0
	s_add_i32 s58, s70, s48
	s_mov_b32 m0, s58
	s_nop 0
	global_load_lds_dwordx4 v0, s[60:61]
	s_add_i32 m0, s58, 0x2000
	s_nop 0
	global_load_lds_dwordx4 v130, s[60:61]
	s_waitcnt vmcnt(6)
	s_barrier
	s_setprio 1
	v_mfma_f32_16x16x32_bf16 v[54:57], v[230:233], v[176:179], v[54:57]
	v_mfma_f32_16x16x32_bf16 v[50:53], v[238:241], v[176:179], v[50:53]
	s_cmp_eq_u32 s89, 0
	s_cbranch_scc1 .LdsE_skip_2
	global_store_dwordx4 v250, v[188:191], s[4:5]
; #define PG8_STAGE(bufoff, gbase, voff) do { _Pragma("unroll") for (int _i = 0; _i < 2; ++_i) \
;         __builtin_amdgcn_global_load_lds((const unsigned*)((const char*)(gbase) + (voff)[_i]), (LAS unsigned*)(lds + (bufoff) + ldsw + _i * 8192), 16, 0, 0); } while (0)
; #define PG8_LDA(dst, b, h) do { _Pragma("unroll") for (int m = 0; m < 4; ++m) _Pragma("unroll") for (int k = 0; k < 2; ++k) dst[m][k] = *(const LAS bf16x8*)(lds + PG8_SA(b, h) + aoff + m * 2048 + k * 1024); } while (0)
; #define PG8_LDB(dst, b, h) do { _Pragma("unroll") for (int n = 0; n < 2; ++n) _Pragma("unroll") for (int k = 0; k < 2; ++k) dst[n][k] = *(const LAS bf16x8*)(lds + PG8_SB(b, h) + boff + n * 2048 + k * 1024); } while (0)
; #define PG8_MMA(ai, bj, At, Bt) do { __builtin_amdgcn_s_setprio(1); _Pragma("unroll") for (int m = 0; m < 4; ++m) _Pragma("unroll") for (int n = 0; n < 2; ++n) _Pragma("unroll") for (int k = 0; k < 2; ++k) \
;         acc[ai][bj][m][n] = __builtin_amdgcn_mfma_f32_16x16x32_bf16(Bt[n][k], At[m][k], acc[ai][bj][m][n], 0, 0, 0); __builtin_amdgcn_s_setprio(0); } while (0)
; #define PG8_WAIT_V(n) asm volatile("s_waitcnt vmcnt(" #n ")" ::: "memory")
; #define PG8_WAIT_L(n) asm volatile("s_waitcnt lgkmcnt(" #n ")" ::: "memory")
; #define PG8_BAR __builtin_amdgcn_s_barrier()
; #define PG8_SCHED __builtin_amdgcn_sched_barrier(0)
; template <class Epi>
; __device__ __forceinline__ void gemm_phase(LAS unsigned char* lds, const Gemm g, const StaticOrder& S, const Epi& E) {
;     ...
;             PG8_WAIT_V(6); PG8_BAR; PG8_MMA(1, 1, At, B1); PG8_BAR;
;             PG8_LDB(B0, 1, 0); PG8_SCHED; PG8_LDA(At, 1, 0); PG8_STAGE(PG8_SA(0, 1), a2 + hstep, voffA);
;             PG8_WAIT_L(8); PG8_BAR; PG8_WAIT_L(0); PG8_MMA(0, 0, At, B0); PG8_BAR; PG8_SCHED;
;             PG8_LDB(B1, 1, 1); PG8_STAGE(PG8_SB(1, 0), b3, voffB);
;             PG8_BAR; PG8_WAIT_L(0); PG8_MMA(0, 1, At, B1); PG8_BAR;
;             PG8_LDA(At, 1, 1); PG8_STAGE(PG8_SA(1, 0), a3, voffA);
;             PG8_BAR; PG8_WAIT_L(0); PG8_MMA(1, 0, At, B0); PG8_BAR; PG8_SCHED;
.LdsE_skip_2:
	v_mfma_f32_16x16x32_bf16 v[38:41], v[230:233], v[184:187], v[38:41]
	v_mfma_f32_16x16x32_bf16 v[34:37], v[238:241], v[184:187], v[34:37]
	v_mfma_f32_16x16x32_bf16 v[22:25], v[230:233], v[208:211], v[22:25]
	v_mfma_f32_16x16x32_bf16 v[18:21], v[238:241], v[208:211], v[18:21]
	v_mfma_f32_16x16x32_bf16 v[6:9], v[230:233], v[216:219], v[6:9]
	v_mfma_f32_16x16x32_bf16 v[2:5], v[238:241], v[216:219], v[2:5]
	v_mfma_f32_16x16x32_bf16 v[54:57], v[234:237], v[180:183], v[54:57]
	v_mfma_f32_16x16x32_bf16 v[50:53], v[242:245], v[180:183], v[50:53]
	v_mfma_f32_16x16x32_bf16 v[38:41], v[234:237], v[204:207], v[38:41]
	v_mfma_f32_16x16x32_bf16 v[34:37], v[242:245], v[204:207], v[34:37]
	v_mfma_f32_16x16x32_bf16 v[22:25], v[234:237], v[212:215], v[22:25]
	v_mfma_f32_16x16x32_bf16 v[18:21], v[242:245], v[212:215], v[18:21]
	v_mfma_f32_16x16x32_bf16 v[6:9], v[234:237], v[226:229], v[6:9]
	v_mfma_f32_16x16x32_bf16 v[2:5], v[242:245], v[226:229], v[2:5]
	s_setprio 0
	s_add_i32 s58, 0, 0x18000
	v_add_u32_e32 v151, s58, v147
	s_barrier
	ds_read_b128 v[140:143], v151
	ds_read_b128 v[152:155], v151 offset:1024
	ds_read_b128 v[168:171], v151 offset:2048
	ds_read_b128 v[172:175], v151 offset:3072
	s_add_u32 s42, s42, 0x40000
	s_addc_u32 s43, s43, 0
	s_mov_b32 m0, s55
	ds_read_b128 v[176:179], v150 offset:32768
	ds_read_b128 v[180:183], v150 offset:33792
	ds_read_b128 v[184:187], v150 offset:34816
	ds_read_b128 v[204:207], v150 offset:35840
	ds_read_b128 v[208:211], v150 offset:36864
	ds_read_b128 v[212:215], v150 offset:37888
	ds_read_b128 v[216:219], v150 offset:38912
	ds_read_b128 v[226:229], v150 offset:39936
	global_load_lds_dwordx4 v134, s[42:43]
	s_mov_b32 m0, s83
	s_nop 0
	global_load_lds_dwordx4 v132, s[42:43]
	s_waitcnt lgkmcnt(8)
	s_barrier
	s_waitcnt lgkmcnt(0)
	s_setprio 1
	s_waitcnt lgkmcnt(0)
	v_mfma_f32_16x16x32_bf16 v[126:129], v[140:143], v[176:179], v[126:129]
	v_mfma_f32_16x16x32_bf16 v[122:125], v[168:171], v[176:179], v[122:125]
	v_mfma_f32_16x16x32_bf16 v[110:113], v[140:143], v[184:187], v[110:113]
	v_mfma_f32_16x16x32_bf16 v[106:109], v[168:171], v[184:187], v[106:109]
	v_mfma_f32_16x16x32_bf16 v[94:97], v[140:143], v[208:211], v[94:97]
	v_mfma_f32_16x16x32_bf16 v[90:93], v[168:171], v[208:211], v[90:93]
	v_mfma_f32_16x16x32_bf16 v[78:81], v[140:143], v[216:219], v[78:81]
	v_mfma_f32_16x16x32_bf16 v[74:77], v[168:171], v[216:219], v[74:77]
	v_mfma_f32_16x16x32_bf16 v[126:129], v[152:155], v[180:183], v[126:129]
	v_mfma_f32_16x16x32_bf16 v[122:125], v[172:175], v[180:183], v[122:125]
	v_mfma_f32_16x16x32_bf16 v[110:113], v[152:155], v[204:207], v[110:113]
	v_mfma_f32_16x16x32_bf16 v[106:109], v[172:175], v[204:207], v[106:109]
	v_mfma_f32_16x16x32_bf16 v[94:97], v[152:155], v[212:215], v[94:97]
	v_mfma_f32_16x16x32_bf16 v[90:93], v[172:175], v[212:215], v[90:93]
	v_mfma_f32_16x16x32_bf16 v[78:81], v[152:155], v[226:229], v[78:81]
	v_mfma_f32_16x16x32_bf16 v[74:77], v[172:175], v[226:229], v[74:77]
	s_setprio 0
	s_barrier
	s_add_i32 s42, 0, 0x1c000
	s_add_i32 s43, s58, s48
	v_add_u32_e32 v151, s42, v147
	s_add_u32 s60, s6, 0x80
	s_addc_u32 s61, s7, 0
	s_mov_b32 m0, s43
	ds_read_b128 v[230:233], v151
	ds_read_b128 v[234:237], v151 offset:1024
	ds_read_b128 v[238:241], v151 offset:2048
	ds_read_b128 v[242:245], v151 offset:3072
	global_load_lds_dwordx4 v0, s[60:61]
	s_add_i32 m0, s43, 0x2000
	s_nop 0
	global_load_lds_dwordx4 v130, s[60:61]
	s_barrier
	s_waitcnt lgkmcnt(0)
	s_setprio 1
	s_waitcnt lgkmcnt(0)
	v_mfma_f32_16x16x32_bf16 v[118:121], v[230:233], v[176:179], v[118:121]
	v_mfma_f32_16x16x32_bf16 v[114:117], v[238:241], v[176:179], v[114:117]
	v_mfma_f32_16x16x32_bf16 v[102:105], v[230:233], v[184:187], v[102:105]
	v_mfma_f32_16x16x32_bf16 v[98:101], v[238:241], v[184:187], v[98:101]
	v_mfma_f32_16x16x32_bf16 v[86:89], v[230:233], v[208:211], v[86:89]
	v_mfma_f32_16x16x32_bf16 v[82:85], v[238:241], v[208:211], v[82:85]
	v_mfma_f32_16x16x32_bf16 v[70:73], v[230:233], v[216:219], v[70:73]
	v_mfma_f32_16x16x32_bf16 v[66:69], v[238:241], v[216:219], v[66:69]
	v_mfma_f32_16x16x32_bf16 v[118:121], v[234:237], v[180:183], v[118:121]
	v_mfma_f32_16x16x32_bf16 v[114:117], v[242:245], v[180:183], v[114:117]
	v_mfma_f32_16x16x32_bf16 v[102:105], v[234:237], v[204:207], v[102:105]
	v_mfma_f32_16x16x32_bf16 v[98:101], v[242:245], v[204:207], v[98:101]
	v_mfma_f32_16x16x32_bf16 v[86:89], v[234:237], v[212:215], v[86:89]
	v_mfma_f32_16x16x32_bf16 v[82:85], v[242:245], v[212:215], v[82:85]
	v_mfma_f32_16x16x32_bf16 v[70:73], v[234:237], v[226:229], v[70:73]
	v_mfma_f32_16x16x32_bf16 v[66:69], v[242:245], v[226:229], v[66:69]
	s_setprio 0
	s_mov_b32 m0, s84
	s_barrier
	ds_read_b128 v[176:179], v150 offset:49152
	ds_read_b128 v[180:183], v150 offset:50176
	ds_read_b128 v[184:187], v150 offset:51200
	ds_read_b128 v[204:207], v150 offset:52224
	ds_read_b128 v[208:211], v150 offset:53248
	ds_read_b128 v[212:215], v150 offset:54272
	ds_read_b128 v[216:219], v150 offset:55296
	ds_read_b128 v[226:229], v150 offset:56320
	global_load_lds_dwordx4 v134, vcc
	s_mov_b32 m0, s85
	s_nop 0
	global_load_lds_dwordx4 v132, vcc
	s_barrier
; #define PG8_STAGE(bufoff, gbase, voff) do { _Pragma("unroll") for (int _i = 0; _i < 2; ++_i) \
;         __builtin_amdgcn_global_load_lds((const unsigned*)((const char*)(gbase) + (voff)[_i]), (LAS unsigned*)(lds + (bufoff) + ldsw + _i * 8192), 16, 0, 0); } while (0)
; #define PG8_LDA(dst, b, h) do { _Pragma("unroll") for (int m = 0; m < 4; ++m) _Pragma("unroll") for (int k = 0; k < 2; ++k) dst[m][k] = *(const LAS bf16x8*)(lds + PG8_SA(b, h) + aoff + m * 2048 + k * 1024); } while (0)
; #define PG8_WAIT_V(n) asm volatile("s_waitcnt vmcnt(" #n ")" ::: "memory")
; #define PG8_WAIT_L(n) asm volatile("s_waitcnt lgkmcnt(" #n ")" ::: "memory")
; template <class Epi>
; __device__ __forceinline__ void gemm_phase(LAS unsigned char* lds, const Gemm g, const StaticOrder& S, const Epi& E) {
;     ...
;             const bool last = (t == nt - 2);
;             const char* a1 = cA + (size_t)(t + 1) * kstep;
;             const char* a2 = last ? nA : cA + (size_t)(t + 2) * kstep; const char* b2 = last ? nB : cB + (size_t)(t + 2) * kstep;
;             const char* a3 = a2 + kstep; const char* b3 = b2 + kstep;
;             PG8_LDB(B0, 0, 0); PG8_SCHED; PG8_LDA(At, 0, 0); PG8_STAGE(PG8_SA(1, 1), a1 + hstep, voffA);
;             PG8_WAIT_L(8); PG8_BAR; PG8_WAIT_L(0); PG8_MMA(0, 0, At, B0); PG8_BAR; PG8_SCHED;
;             PG8_LDB(B1, 0, 1); PG8_STAGE(PG8_SB(0, 0), b2, voffB);
;             PG8_BAR; PG8_WAIT_L(0); PG8_MMA(0, 1, At, B1); PG8_BAR;
;             PG8_LDA(At, 0, 1); PG8_STAGE(PG8_SA(0, 0), a2, voffA);
;             PG8_BAR; PG8_WAIT_L(0); PG8_MMA(1, 0, At, B0); PG8_BAR; PG8_SCHED;
;             PG8_STAGE(PG8_SB(0, 1), b2 + hstep, voffB);
;             PG8_WAIT_V(6); PG8_BAR; PG8_MMA(1, 1, At, B1); PG8_BAR;
;             PG8_LDB(B0, 1, 0); PG8_SCHED; PG8_LDA(At, 1, 0); PG8_STAGE(PG8_SA(0, 1), a2 + hstep, voffA);
;             PG8_WAIT_L(8); PG8_BAR; PG8_WAIT_L(0); PG8_MMA(0, 0, At, B0); PG8_BAR; PG8_SCHED;
;             PG8_LDB(B1, 1, 1); PG8_STAGE(PG8_SB(1, 0), b3, voffB);
;             PG8_BAR; PG8_WAIT_L(0); PG8_MMA(0, 1, At, B1); PG8_BAR;
;             PG8_LDA(At, 1, 1); PG8_STAGE(PG8_SA(1, 0), a3, voffA);
;             PG8_BAR; PG8_WAIT_L(0); PG8_MMA(1, 0, At, B0); PG8_BAR; PG8_SCHED;
;             PG8_STAGE(PG8_SB(1, 1), b3 + hstep, voffB);
;             PG8_WAIT_V(6); PG8_BAR; PG8_MMA(1, 1, At, B1); PG8_BAR;
;         }
	s_waitcnt lgkmcnt(0)
	s_setprio 1
	s_waitcnt lgkmcnt(0)
	v_mfma_f32_16x16x32_bf16 v[62:65], v[140:143], v[176:179], v[62:65]
	v_mfma_f32_16x16x32_bf16 v[58:61], v[168:171], v[176:179], v[58:61]
	v_mfma_f32_16x16x32_bf16 v[46:49], v[140:143], v[184:187], v[46:49]
	v_mfma_f32_16x16x32_bf16 v[42:45], v[168:171], v[184:187], v[42:45]
	v_mfma_f32_16x16x32_bf16 v[30:33], v[140:143], v[208:211], v[30:33]
	v_mfma_f32_16x16x32_bf16 v[26:29], v[168:171], v[208:211], v[26:29]
	v_mfma_f32_16x16x32_bf16 v[14:17], v[140:143], v[216:219], v[14:17]
	v_mfma_f32_16x16x32_bf16 v[10:13], v[168:171], v[216:219], v[10:13]
	v_mfma_f32_16x16x32_bf16 v[62:65], v[152:155], v[180:183], v[62:65]
	v_mfma_f32_16x16x32_bf16 v[58:61], v[172:175], v[180:183], v[58:61]
	v_mfma_f32_16x16x32_bf16 v[46:49], v[152:155], v[204:207], v[46:49]
	v_mfma_f32_16x16x32_bf16 v[42:45], v[172:175], v[204:207], v[42:45]
	v_mfma_f32_16x16x32_bf16 v[30:33], v[152:155], v[212:215], v[30:33]
	v_mfma_f32_16x16x32_bf16 v[26:29], v[172:175], v[212:215], v[26:29]
	v_mfma_f32_16x16x32_bf16 v[14:17], v[152:155], v[226:229], v[14:17]
	v_mfma_f32_16x16x32_bf16 v[10:13], v[172:175], v[226:229], v[10:13]
	s_setprio 0
	s_barrier
	s_add_u32 s6, s6, 0x40080
	s_addc_u32 s7, s7, 0
	s_add_i32 s42, s42, s48
	s_mov_b32 m0, s42
	s_nop 0
	global_load_lds_dwordx4 v0, s[6:7]
	s_add_i32 m0, s42, 0x2000
	s_nop 0
	global_load_lds_dwordx4 v130, s[6:7]
	s_waitcnt vmcnt(6)
	s_barrier
	s_setprio 1
	v_mfma_f32_16x16x32_bf16 v[54:57], v[230:233], v[176:179], v[54:57]
	v_mfma_f32_16x16x32_bf16 v[50:53], v[238:241], v[176:179], v[50:53]
	v_mfma_f32_16x16x32_bf16 v[38:41], v[230:233], v[184:187], v[38:41]
	v_mfma_f32_16x16x32_bf16 v[34:37], v[238:241], v[184:187], v[34:37]
	v_mfma_f32_16x16x32_bf16 v[22:25], v[230:233], v[208:211], v[22:25]
	v_mfma_f32_16x16x32_bf16 v[18:21], v[238:241], v[208:211], v[18:21]
	v_mfma_f32_16x16x32_bf16 v[6:9], v[230:233], v[216:219], v[6:9]
	v_mfma_f32_16x16x32_bf16 v[2:5], v[238:241], v[216:219], v[2:5]
	v_mfma_f32_16x16x32_bf16 v[54:57], v[234:237], v[180:183], v[54:57]
	v_mfma_f32_16x16x32_bf16 v[50:53], v[242:245], v[180:183], v[50:53]
	v_mfma_f32_16x16x32_bf16 v[38:41], v[234:237], v[204:207], v[38:41]
	v_mfma_f32_16x16x32_bf16 v[34:37], v[242:245], v[204:207], v[34:37]
	v_mfma_f32_16x16x32_bf16 v[22:25], v[234:237], v[212:215], v[22:25]
	v_mfma_f32_16x16x32_bf16 v[18:21], v[242:245], v[212:215], v[18:21]
	v_mfma_f32_16x16x32_bf16 v[6:9], v[234:237], v[226:229], v[6:9]
	v_mfma_f32_16x16x32_bf16 v[2:5], v[242:245], v[226:229], v[2:5]
	s_setprio 0
	s_add_i32 s93, s93, 2
	s_add_u32 s36, s36, 0x100
	s_addc_u32 s37, s37, 0
	s_add_u32 s91, s91, 0x100
	s_addc_u32 s92, s92, 0
	s_cmp_gt_u32 s93, 13
	s_barrier
	s_add_u32 s6, s36, 0xfffc0080
	s_addc_u32 s7, s37, -1
	s_add_i32 s58, 0, 0x10000
	v_add_u32_e32 v144, s58, v147
	ds_read_b128 v[140:143], v144
	ds_read_b128 v[152:155], v144 offset:1024
	ds_read_b128 v[168:171], v144 offset:2048
	ds_read_b128 v[172:175], v144 offset:3072
	s_cmp_eq_u32 s93, 12
	s_cselect_b32 s43, s11, s7
	s_cselect_b32 s42, s71, s6
	s_cselect_b32 s7, s9, s92
	s_cselect_b32 s6, s90, s91
	s_add_i32 m0, s49, 0xc000
	ds_read_b128 v[176:179], v150
	ds_read_b128 v[180:183], v150 offset:1024
	ds_read_b128 v[184:187], v150 offset:2048
	ds_read_b128 v[204:207], v150 offset:3072
	ds_read_b128 v[208:211], v150 offset:4096
	ds_read_b128 v[212:215], v150 offset:5120
	ds_read_b128 v[216:219], v150 offset:6144
	ds_read_b128 v[226:229], v150 offset:7168
	global_load_lds_dwordx4 v136, s[36:37]
	s_add_i32 m0, s49, 0xe000
	s_nop 0
	global_load_lds_dwordx4 v138, s[36:37]
	s_waitcnt lgkmcnt(8)
	s_barrier
	s_waitcnt lgkmcnt(0)
	s_setprio 1
	s_waitcnt lgkmcnt(0)
	v_mfma_f32_16x16x32_bf16 v[126:129], v[140:143], v[176:179], v[126:129]
	v_mfma_f32_16x16x32_bf16 v[122:125], v[168:171], v[176:179], v[122:125]
	v_mfma_f32_16x16x32_bf16 v[110:113], v[140:143], v[184:187], v[110:113]
	v_mfma_f32_16x16x32_bf16 v[106:109], v[168:171], v[184:187], v[106:109]
	v_mfma_f32_16x16x32_bf16 v[94:97], v[140:143], v[208:211], v[94:97]
	v_mfma_f32_16x16x32_bf16 v[90:93], v[168:171], v[208:211], v[90:93]
	v_mfma_f32_16x16x32_bf16 v[78:81], v[140:143], v[216:219], v[78:81]
	v_mfma_f32_16x16x32_bf16 v[74:77], v[168:171], v[216:219], v[74:77]
	v_mfma_f32_16x16x32_bf16 v[126:129], v[152:155], v[180:183], v[126:129]
	v_mfma_f32_16x16x32_bf16 v[122:125], v[172:175], v[180:183], v[122:125]
	v_mfma_f32_16x16x32_bf16 v[110:113], v[152:155], v[204:207], v[110:113]
	v_mfma_f32_16x16x32_bf16 v[106:109], v[172:175], v[204:207], v[106:109]
	v_mfma_f32_16x16x32_bf16 v[94:97], v[152:155], v[212:215], v[94:97]
	v_mfma_f32_16x16x32_bf16 v[90:93], v[172:175], v[212:215], v[90:93]
	v_mfma_f32_16x16x32_bf16 v[78:81], v[152:155], v[226:229], v[78:81]
	v_mfma_f32_16x16x32_bf16 v[74:77], v[172:175], v[226:229], v[74:77]
	s_setprio 0
	s_barrier
	s_add_i32 s70, 0, 0x14000
	v_add_u32_e32 v144, s70, v147
	s_add_i32 s58, s58, s48
	ds_read_b128 v[230:233], v144
	ds_read_b128 v[234:237], v144 offset:1024
	ds_read_b128 v[238:241], v144 offset:2048
	ds_read_b128 v[242:245], v144 offset:3072
	s_mov_b32 m0, s58
	s_nop 0
	global_load_lds_dwordx4 v0, s[6:7]
	s_add_i32 m0, s58, 0x2000
	s_nop 0
	global_load_lds_dwordx4 v130, s[6:7]
	s_barrier
; #define PG8_STAGE(bufoff, gbase, voff) do { _Pragma("unroll") for (int _i = 0; _i < 2; ++_i) \
;         __builtin_amdgcn_global_load_lds((const unsigned*)((const char*)(gbase) + (voff)[_i]), (LAS unsigned*)(lds + (bufoff) + ldsw + _i * 8192), 16, 0, 0); } while (0)
; #define PG8_LDA(dst, b, h) do { _Pragma("unroll") for (int m = 0; m < 4; ++m) _Pragma("unroll") for (int k = 0; k < 2; ++k) dst[m][k] = *(const LAS bf16x8*)(lds + PG8_SA(b, h) + aoff + m * 2048 + k * 1024); } while (0)
; #define PG8_LDB(dst, b, h) do { _Pragma("unroll") for (int n = 0; n < 2; ++n) _Pragma("unroll") for (int k = 0; k < 2; ++k) dst[n][k] = *(const LAS bf16x8*)(lds + PG8_SB(b, h) + boff + n * 2048 + k * 1024); } while (0)
; #define PG8_MMA(ai, bj, At, Bt) do { __builtin_amdgcn_s_setprio(1); _Pragma("unroll") for (int m = 0; m < 4; ++m) _Pragma("unroll") for (int n = 0; n < 2; ++n) _Pragma("unroll") for (int k = 0; k < 2; ++k) \
;         acc[ai][bj][m][n] = __builtin_amdgcn_mfma_f32_16x16x32_bf16(Bt[n][k], At[m][k], acc[ai][bj][m][n], 0, 0, 0); __builtin_amdgcn_s_setprio(0); } while (0)
; #define PG8_WAIT_V(n) asm volatile("s_waitcnt vmcnt(" #n ")" ::: "memory")
; #define PG8_WAIT_L(n) asm volatile("s_waitcnt lgkmcnt(" #n ")" ::: "memory")
; #define PG8_BAR __builtin_amdgcn_s_barrier()
; #define PG8_SCHED __builtin_amdgcn_sched_barrier(0)
; template <class Epi>
; __device__ __forceinline__ void gemm_phase(LAS unsigned char* lds, const Gemm g, const StaticOrder& S, const Epi& E) {
;     ...
;             PG8_BAR; PG8_WAIT_L(0); PG8_MMA(0, 1, At, B1); PG8_BAR;
;             PG8_LDA(At, 0, 1); PG8_STAGE(PG8_SA(0, 0), a2, voffA);
;             PG8_BAR; PG8_WAIT_L(0); PG8_MMA(1, 0, At, B0); PG8_BAR; PG8_SCHED;
;             PG8_STAGE(PG8_SB(0, 1), b2 + hstep, voffB);
;             PG8_WAIT_V(6); PG8_BAR; PG8_MMA(1, 1, At, B1); PG8_BAR;
;             PG8_LDB(B0, 1, 0); PG8_SCHED; PG8_LDA(At, 1, 0); PG8_STAGE(PG8_SA(0, 1), a2 + hstep, voffA);
;             PG8_WAIT_L(8); PG8_BAR; PG8_WAIT_L(0); PG8_MMA(0, 0, At, B0); PG8_BAR; PG8_SCHED;
;             PG8_LDB(B1, 1, 1); PG8_STAGE(PG8_SB(1, 0), b3, voffB);
;             PG8_BAR; PG8_WAIT_L(0); PG8_MMA(0, 1, At, B1); PG8_BAR;
;             PG8_LDA(At, 1, 1); PG8_STAGE(PG8_SA(1, 0), a3, voffA);
;             PG8_BAR; PG8_WAIT_L(0); PG8_MMA(1, 0, At, B0); PG8_BAR; PG8_SCHED;
	s_waitcnt lgkmcnt(0)
	s_setprio 1
	s_waitcnt lgkmcnt(0)
	v_mfma_f32_16x16x32_bf16 v[118:121], v[230:233], v[176:179], v[118:121]
	v_mfma_f32_16x16x32_bf16 v[114:117], v[238:241], v[176:179], v[114:117]
	v_mfma_f32_16x16x32_bf16 v[102:105], v[230:233], v[184:187], v[102:105]
	v_mfma_f32_16x16x32_bf16 v[98:101], v[238:241], v[184:187], v[98:101]
	v_mfma_f32_16x16x32_bf16 v[86:89], v[230:233], v[208:211], v[86:89]
	v_mfma_f32_16x16x32_bf16 v[82:85], v[238:241], v[208:211], v[82:85]
	v_mfma_f32_16x16x32_bf16 v[70:73], v[230:233], v[216:219], v[70:73]
	v_mfma_f32_16x16x32_bf16 v[66:69], v[238:241], v[216:219], v[66:69]
	v_mfma_f32_16x16x32_bf16 v[118:121], v[234:237], v[180:183], v[118:121]
	v_mfma_f32_16x16x32_bf16 v[114:117], v[242:245], v[180:183], v[114:117]
	v_mfma_f32_16x16x32_bf16 v[102:105], v[234:237], v[204:207], v[102:105]
	v_mfma_f32_16x16x32_bf16 v[98:101], v[242:245], v[204:207], v[98:101]
	v_mfma_f32_16x16x32_bf16 v[86:89], v[234:237], v[212:215], v[86:89]
	v_mfma_f32_16x16x32_bf16 v[82:85], v[242:245], v[212:215], v[82:85]
	v_mfma_f32_16x16x32_bf16 v[70:73], v[234:237], v[226:229], v[70:73]
	v_mfma_f32_16x16x32_bf16 v[66:69], v[242:245], v[226:229], v[66:69]
	s_setprio 0
	s_mov_b32 m0, s49
	s_add_u32 vcc_lo, s42, 0x80
	s_addc_u32 vcc_hi, s43, 0
	s_barrier
	ds_read_b128 v[176:179], v150 offset:16384
	ds_read_b128 v[180:183], v150 offset:17408
	ds_read_b128 v[184:187], v150 offset:18432
	ds_read_b128 v[204:207], v150 offset:19456
	ds_read_b128 v[208:211], v150 offset:20480
	ds_read_b128 v[212:215], v150 offset:21504
	ds_read_b128 v[216:219], v150 offset:22528
	ds_read_b128 v[226:229], v150 offset:23552
	global_load_lds_dwordx4 v134, s[42:43]
	s_mov_b32 m0, s54
	s_nop 0
	global_load_lds_dwordx4 v132, s[42:43]
	s_barrier
	s_waitcnt lgkmcnt(0)
	s_setprio 1
	s_waitcnt lgkmcnt(0)
	v_mfma_f32_16x16x32_bf16 v[62:65], v[140:143], v[176:179], v[62:65]
	v_mfma_f32_16x16x32_bf16 v[58:61], v[168:171], v[176:179], v[58:61]
	v_mfma_f32_16x16x32_bf16 v[46:49], v[140:143], v[184:187], v[46:49]
	v_mfma_f32_16x16x32_bf16 v[42:45], v[168:171], v[184:187], v[42:45]
	v_mfma_f32_16x16x32_bf16 v[30:33], v[140:143], v[208:211], v[30:33]
	v_mfma_f32_16x16x32_bf16 v[26:29], v[168:171], v[208:211], v[26:29]
	v_mfma_f32_16x16x32_bf16 v[14:17], v[140:143], v[216:219], v[14:17]
	v_mfma_f32_16x16x32_bf16 v[10:13], v[168:171], v[216:219], v[10:13]
	v_mfma_f32_16x16x32_bf16 v[62:65], v[152:155], v[180:183], v[62:65]
	v_mfma_f32_16x16x32_bf16 v[58:61], v[172:175], v[180:183], v[58:61]
	v_mfma_f32_16x16x32_bf16 v[46:49], v[152:155], v[204:207], v[46:49]
	v_mfma_f32_16x16x32_bf16 v[42:45], v[172:175], v[204:207], v[42:45]
	v_mfma_f32_16x16x32_bf16 v[30:33], v[152:155], v[212:215], v[30:33]
	v_mfma_f32_16x16x32_bf16 v[26:29], v[172:175], v[212:215], v[26:29]
	v_mfma_f32_16x16x32_bf16 v[14:17], v[152:155], v[226:229], v[14:17]
	v_mfma_f32_16x16x32_bf16 v[10:13], v[172:175], v[226:229], v[10:13]
	s_setprio 0
	s_barrier
	s_add_u32 s60, s6, 0x40000
	s_addc_u32 s61, s7, 0
	s_add_i32 s58, s70, s48
	s_mov_b32 m0, s58
	s_nop 0
	global_load_lds_dwordx4 v0, s[60:61]
	s_add_i32 m0, s58, 0x2000
	s_nop 0
	global_load_lds_dwordx4 v130, s[60:61]
	s_waitcnt vmcnt(6)
	s_barrier
	s_setprio 1
	v_mfma_f32_16x16x32_bf16 v[54:57], v[230:233], v[176:179], v[54:57]
	v_mfma_f32_16x16x32_bf16 v[50:53], v[238:241], v[176:179], v[50:53]
	s_cmp_eq_u32 s89, 0
	s_cbranch_scc1 .LdsE_skip_3
	global_store_dwordx4 v250, v[192:195], s[4:5] offset:256
	v_add_u32_e32 v250, 0x20000, v250
.LdsE_skip_3:
	v_mfma_f32_16x16x32_bf16 v[38:41], v[230:233], v[184:187], v[38:41]
	v_mfma_f32_16x16x32_bf16 v[34:37], v[238:241], v[184:187], v[34:37]
	v_mfma_f32_16x16x32_bf16 v[22:25], v[230:233], v[208:211], v[22:25]
	v_mfma_f32_16x16x32_bf16 v[18:21], v[238:241], v[208:211], v[18:21]
	v_mfma_f32_16x16x32_bf16 v[6:9], v[230:233], v[216:219], v[6:9]
	v_mfma_f32_16x16x32_bf16 v[2:5], v[238:241], v[216:219], v[2:5]
	v_mfma_f32_16x16x32_bf16 v[54:57], v[234:237], v[180:183], v[54:57]
	v_mfma_f32_16x16x32_bf16 v[50:53], v[242:245], v[180:183], v[50:53]
	v_mfma_f32_16x16x32_bf16 v[38:41], v[234:237], v[204:207], v[38:41]
	v_mfma_f32_16x16x32_bf16 v[34:37], v[242:245], v[204:207], v[34:37]
	v_mfma_f32_16x16x32_bf16 v[22:25], v[234:237], v[212:215], v[22:25]
	v_mfma_f32_16x16x32_bf16 v[18:21], v[242:245], v[212:215], v[18:21]
	v_mfma_f32_16x16x32_bf16 v[6:9], v[234:237], v[226:229], v[6:9]
	v_mfma_f32_16x16x32_bf16 v[2:5], v[242:245], v[226:229], v[2:5]
	s_setprio 0
	s_add_i32 s58, 0, 0x18000
	v_add_u32_e32 v151, s58, v147
	s_barrier
	ds_read_b128 v[140:143], v151
	ds_read_b128 v[152:155], v151 offset:1024
	ds_read_b128 v[168:171], v151 offset:2048
	ds_read_b128 v[172:175], v151 offset:3072
	s_add_u32 s42, s42, 0x40000
	s_addc_u32 s43, s43, 0
	s_mov_b32 m0, s55
	ds_read_b128 v[176:179], v150 offset:32768
	ds_read_b128 v[180:183], v150 offset:33792
	ds_read_b128 v[184:187], v150 offset:34816
	ds_read_b128 v[204:207], v150 offset:35840
	ds_read_b128 v[208:211], v150 offset:36864
	ds_read_b128 v[212:215], v150 offset:37888
	ds_read_b128 v[216:219], v150 offset:38912
	ds_read_b128 v[226:229], v150 offset:39936
	global_load_lds_dwordx4 v134, s[42:43]
	s_mov_b32 m0, s83
	s_nop 0
	global_load_lds_dwordx4 v132, s[42:43]
	s_waitcnt lgkmcnt(8)
	s_barrier
; #define PG8_STAGE(bufoff, gbase, voff) do { _Pragma("unroll") for (int _i = 0; _i < 2; ++_i) \
;         __builtin_amdgcn_global_load_lds((const unsigned*)((const char*)(gbase) + (voff)[_i]), (LAS unsigned*)(lds + (bufoff) + ldsw + _i * 8192), 16, 0, 0); } while (0)
; #define PG8_LDA(dst, b, h) do { _Pragma("unroll") for (int m = 0; m < 4; ++m) _Pragma("unroll") for (int k = 0; k < 2; ++k) dst[m][k] = *(const LAS bf16x8*)(lds + PG8_SA(b, h) + aoff + m * 2048 + k * 1024); } while (0)
; #define PG8_LDB(dst, b, h) do { _Pragma("unroll") for (int n = 0; n < 2; ++n) _Pragma("unroll") for (int k = 0; k < 2; ++k) dst[n][k] = *(const LAS bf16x8*)(lds + PG8_SB(b, h) + boff + n * 2048 + k * 1024); } while (0)
; #define PG8_MMA(ai, bj, At, Bt) do { __builtin_amdgcn_s_setprio(1); _Pragma("unroll") for (int m = 0; m < 4; ++m) _Pragma("unroll") for (int n = 0; n < 2; ++n) _Pragma("unroll") for (int k = 0; k < 2; ++k) \
;         acc[ai][bj][m][n] = __builtin_amdgcn_mfma_f32_16x16x32_bf16(Bt[n][k], At[m][k], acc[ai][bj][m][n], 0, 0, 0); __builtin_amdgcn_s_setprio(0); } while (0)
; #define PG8_WAIT_V(n) asm volatile("s_waitcnt vmcnt(" #n ")" ::: "memory")
; #define PG8_WAIT_L(n) asm volatile("s_waitcnt lgkmcnt(" #n ")" ::: "memory")
; #define PG8_BAR __builtin_amdgcn_s_barrier()
; #define PG8_SCHED __builtin_amdgcn_sched_barrier(0)
; template <class Epi>
; __device__ __forceinline__ void gemm_phase(LAS unsigned char* lds, const Gemm g, const StaticOrder& S, const Epi& E) {
;     ...
;             PG8_WAIT_L(8); PG8_BAR; PG8_WAIT_L(0); PG8_MMA(0, 0, At, B0); PG8_BAR; PG8_SCHED;
;             PG8_LDB(B1, 1, 1); PG8_STAGE(PG8_SB(1, 0), b3, voffB);
;             PG8_BAR; PG8_WAIT_L(0); PG8_MMA(0, 1, At, B1); PG8_BAR;
;             PG8_LDA(At, 1, 1); PG8_STAGE(PG8_SA(1, 0), a3, voffA);
;             PG8_BAR; PG8_WAIT_L(0); PG8_MMA(1, 0, At, B0); PG8_BAR; PG8_SCHED;
;             PG8_STAGE(PG8_SB(1, 1), b3 + hstep, voffB);
;             PG8_WAIT_V(6); PG8_BAR; PG8_MMA(1, 1, At, B1); PG8_BAR;
;         }
	s_waitcnt lgkmcnt(0)
	s_setprio 1
	s_waitcnt lgkmcnt(0)
	v_mfma_f32_16x16x32_bf16 v[126:129], v[140:143], v[176:179], v[126:129]
	v_mfma_f32_16x16x32_bf16 v[122:125], v[168:171], v[176:179], v[122:125]
	v_mfma_f32_16x16x32_bf16 v[110:113], v[140:143], v[184:187], v[110:113]
	v_mfma_f32_16x16x32_bf16 v[106:109], v[168:171], v[184:187], v[106:109]
	v_mfma_f32_16x16x32_bf16 v[94:97], v[140:143], v[208:211], v[94:97]
	v_mfma_f32_16x16x32_bf16 v[90:93], v[168:171], v[208:211], v[90:93]
	v_mfma_f32_16x16x32_bf16 v[78:81], v[140:143], v[216:219], v[78:81]
	v_mfma_f32_16x16x32_bf16 v[74:77], v[168:171], v[216:219], v[74:77]
	v_mfma_f32_16x16x32_bf16 v[126:129], v[152:155], v[180:183], v[126:129]
	v_mfma_f32_16x16x32_bf16 v[122:125], v[172:175], v[180:183], v[122:125]
	v_mfma_f32_16x16x32_bf16 v[110:113], v[152:155], v[204:207], v[110:113]
	v_mfma_f32_16x16x32_bf16 v[106:109], v[172:175], v[204:207], v[106:109]
	v_mfma_f32_16x16x32_bf16 v[94:97], v[152:155], v[212:215], v[94:97]
	v_mfma_f32_16x16x32_bf16 v[90:93], v[172:175], v[212:215], v[90:93]
	v_mfma_f32_16x16x32_bf16 v[78:81], v[152:155], v[226:229], v[78:81]
	v_mfma_f32_16x16x32_bf16 v[74:77], v[172:175], v[226:229], v[74:77]
	s_setprio 0
	s_barrier
	s_add_i32 s42, 0, 0x1c000
	s_add_i32 s43, s58, s48
	v_add_u32_e32 v151, s42, v147
	s_add_u32 s60, s6, 0x80
	s_addc_u32 s61, s7, 0
	s_mov_b32 m0, s43
	ds_read_b128 v[230:233], v151
	ds_read_b128 v[234:237], v151 offset:1024
	ds_read_b128 v[238:241], v151 offset:2048
	ds_read_b128 v[242:245], v151 offset:3072
	global_load_lds_dwordx4 v0, s[60:61]
	s_add_i32 m0, s43, 0x2000
	s_nop 0
	global_load_lds_dwordx4 v130, s[60:61]
	s_barrier
	s_waitcnt lgkmcnt(0)
	s_setprio 1
	s_waitcnt lgkmcnt(0)
	v_mfma_f32_16x16x32_bf16 v[118:121], v[230:233], v[176:179], v[118:121]
	v_mfma_f32_16x16x32_bf16 v[114:117], v[238:241], v[176:179], v[114:117]
	v_mfma_f32_16x16x32_bf16 v[102:105], v[230:233], v[184:187], v[102:105]
	v_mfma_f32_16x16x32_bf16 v[98:101], v[238:241], v[184:187], v[98:101]
	v_mfma_f32_16x16x32_bf16 v[86:89], v[230:233], v[208:211], v[86:89]
	v_mfma_f32_16x16x32_bf16 v[82:85], v[238:241], v[208:211], v[82:85]
	v_mfma_f32_16x16x32_bf16 v[70:73], v[230:233], v[216:219], v[70:73]
	v_mfma_f32_16x16x32_bf16 v[66:69], v[238:241], v[216:219], v[66:69]
	v_mfma_f32_16x16x32_bf16 v[118:121], v[234:237], v[180:183], v[118:121]
	v_mfma_f32_16x16x32_bf16 v[114:117], v[242:245], v[180:183], v[114:117]
	v_mfma_f32_16x16x32_bf16 v[102:105], v[234:237], v[204:207], v[102:105]
	v_mfma_f32_16x16x32_bf16 v[98:101], v[242:245], v[204:207], v[98:101]
	v_mfma_f32_16x16x32_bf16 v[86:89], v[234:237], v[212:215], v[86:89]
	v_mfma_f32_16x16x32_bf16 v[82:85], v[242:245], v[212:215], v[82:85]
	v_mfma_f32_16x16x32_bf16 v[70:73], v[234:237], v[226:229], v[70:73]
	v_mfma_f32_16x16x32_bf16 v[66:69], v[242:245], v[226:229], v[66:69]
	s_setprio 0
	s_mov_b32 m0, s84
	s_barrier
	ds_read_b128 v[176:179], v150 offset:49152
	ds_read_b128 v[180:183], v150 offset:50176
	ds_read_b128 v[184:187], v150 offset:51200
	ds_read_b128 v[204:207], v150 offset:52224
	ds_read_b128 v[208:211], v150 offset:53248
	ds_read_b128 v[212:215], v150 offset:54272
	ds_read_b128 v[216:219], v150 offset:55296
	ds_read_b128 v[226:229], v150 offset:56320
	global_load_lds_dwordx4 v134, vcc
	s_mov_b32 m0, s85
	s_nop 0
	global_load_lds_dwordx4 v132, vcc
	s_barrier
	s_waitcnt lgkmcnt(0)
	s_setprio 1
	s_waitcnt lgkmcnt(0)
	v_mfma_f32_16x16x32_bf16 v[62:65], v[140:143], v[176:179], v[62:65]
	v_mfma_f32_16x16x32_bf16 v[58:61], v[168:171], v[176:179], v[58:61]
	v_mfma_f32_16x16x32_bf16 v[46:49], v[140:143], v[184:187], v[46:49]
	v_mfma_f32_16x16x32_bf16 v[42:45], v[168:171], v[184:187], v[42:45]
	v_mfma_f32_16x16x32_bf16 v[30:33], v[140:143], v[208:211], v[30:33]
	v_mfma_f32_16x16x32_bf16 v[26:29], v[168:171], v[208:211], v[26:29]
	v_mfma_f32_16x16x32_bf16 v[14:17], v[140:143], v[216:219], v[14:17]
	v_mfma_f32_16x16x32_bf16 v[10:13], v[168:171], v[216:219], v[10:13]
	v_mfma_f32_16x16x32_bf16 v[62:65], v[152:155], v[180:183], v[62:65]
	v_mfma_f32_16x16x32_bf16 v[58:61], v[172:175], v[180:183], v[58:61]
	v_mfma_f32_16x16x32_bf16 v[46:49], v[152:155], v[204:207], v[46:49]
	v_mfma_f32_16x16x32_bf16 v[42:45], v[172:175], v[204:207], v[42:45]
	v_mfma_f32_16x16x32_bf16 v[30:33], v[152:155], v[212:215], v[30:33]
	v_mfma_f32_16x16x32_bf16 v[26:29], v[172:175], v[212:215], v[26:29]
	v_mfma_f32_16x16x32_bf16 v[14:17], v[152:155], v[226:229], v[14:17]
	v_mfma_f32_16x16x32_bf16 v[10:13], v[172:175], v[226:229], v[10:13]
	s_setprio 0
	s_barrier
	s_add_u32 s6, s6, 0x40080
	s_addc_u32 s7, s7, 0
	s_add_i32 s42, s42, s48
	s_mov_b32 m0, s42
	s_nop 0
	global_load_lds_dwordx4 v0, s[6:7]
	s_add_i32 m0, s42, 0x2000
	s_nop 0
	global_load_lds_dwordx4 v130, s[6:7]
	s_waitcnt vmcnt(6)
	s_barrier
	s_setprio 1
	v_mfma_f32_16x16x32_bf16 v[54:57], v[230:233], v[176:179], v[54:57]
	v_mfma_f32_16x16x32_bf16 v[50:53], v[238:241], v[176:179], v[50:53]
	v_mfma_f32_16x16x32_bf16 v[38:41], v[230:233], v[184:187], v[38:41]
	v_mfma_f32_16x16x32_bf16 v[34:37], v[238:241], v[184:187], v[34:37]
	v_mfma_f32_16x16x32_bf16 v[22:25], v[230:233], v[208:211], v[22:25]
	v_mfma_f32_16x16x32_bf16 v[18:21], v[238:241], v[208:211], v[18:21]
	v_mfma_f32_16x16x32_bf16 v[6:9], v[230:233], v[216:219], v[6:9]
	v_mfma_f32_16x16x32_bf16 v[2:5], v[238:241], v[216:219], v[2:5]
	v_mfma_f32_16x16x32_bf16 v[54:57], v[234:237], v[180:183], v[54:57]
	v_mfma_f32_16x16x32_bf16 v[50:53], v[242:245], v[180:183], v[50:53]
	v_mfma_f32_16x16x32_bf16 v[38:41], v[234:237], v[204:207], v[38:41]
	v_mfma_f32_16x16x32_bf16 v[34:37], v[242:245], v[204:207], v[34:37]
	v_mfma_f32_16x16x32_bf16 v[22:25], v[234:237], v[212:215], v[22:25]
	v_mfma_f32_16x16x32_bf16 v[18:21], v[242:245], v[212:215], v[18:21]
	v_mfma_f32_16x16x32_bf16 v[6:9], v[234:237], v[226:229], v[6:9]
	v_mfma_f32_16x16x32_bf16 v[2:5], v[242:245], v[226:229], v[2:5]
	s_setprio 0
	s_add_i32 s93, s93, 2
	s_add_u32 s36, s36, 0x100
	s_addc_u32 s37, s37, 0
	s_add_u32 s91, s91, 0x100
	s_addc_u32 s92, s92, 0
	s_cmp_gt_u32 s93, 13
	s_barrier
; #define PG8_STAGE(bufoff, gbase, voff) do { _Pragma("unroll") for (int _i = 0; _i < 2; ++_i) \
;         __builtin_amdgcn_global_load_lds((const unsigned*)((const char*)(gbase) + (voff)[_i]), (LAS unsigned*)(lds + (bufoff) + ldsw + _i * 8192), 16, 0, 0); } while (0)
; #define PG8_LDA(dst, b, h) do { _Pragma("unroll") for (int m = 0; m < 4; ++m) _Pragma("unroll") for (int k = 0; k < 2; ++k) dst[m][k] = *(const LAS bf16x8*)(lds + PG8_SA(b, h) + aoff + m * 2048 + k * 1024); } while (0)
; #define PG8_LDB(dst, b, h) do { _Pragma("unroll") for (int n = 0; n < 2; ++n) _Pragma("unroll") for (int k = 0; k < 2; ++k) dst[n][k] = *(const LAS bf16x8*)(lds + PG8_SB(b, h) + boff + n * 2048 + k * 1024); } while (0)
; #define PG8_MMA(ai, bj, At, Bt) do { __builtin_amdgcn_s_setprio(1); _Pragma("unroll") for (int m = 0; m < 4; ++m) _Pragma("unroll") for (int n = 0; n < 2; ++n) _Pragma("unroll") for (int k = 0; k < 2; ++k) \
;         acc[ai][bj][m][n] = __builtin_amdgcn_mfma_f32_16x16x32_bf16(Bt[n][k], At[m][k], acc[ai][bj][m][n], 0, 0, 0); __builtin_amdgcn_s_setprio(0); } while (0)
; #define PG8_WAIT_V(n) asm volatile("s_waitcnt vmcnt(" #n ")" ::: "memory")
; #define PG8_WAIT_L(n) asm volatile("s_waitcnt lgkmcnt(" #n ")" ::: "memory")
; #define PG8_BAR __builtin_amdgcn_s_barrier()
; template <class Epi>
; __device__ __forceinline__ void gemm_phase(LAS unsigned char* lds, const Gemm g, const StaticOrder& S, const Epi& E) {
;     ...
;             const bool last = (t == nt - 2);
;             const char* a1 = cA + (size_t)(t + 1) * kstep;
;             const char* a2 = last ? nA : cA + (size_t)(t + 2) * kstep; const char* b2 = last ? nB : cB + (size_t)(t + 2) * kstep;
;             const char* a3 = a2 + kstep; const char* b3 = b2 + kstep;
;             PG8_LDB(B0, 0, 0); PG8_SCHED; PG8_LDA(At, 0, 0); PG8_STAGE(PG8_SA(1, 1), a1 + hstep, voffA);
;             PG8_WAIT_L(8); PG8_BAR; PG8_WAIT_L(0); PG8_MMA(0, 0, At, B0); PG8_BAR; PG8_SCHED;
;             PG8_LDB(B1, 0, 1); PG8_STAGE(PG8_SB(0, 0), b2, voffB);
;             PG8_BAR; PG8_WAIT_L(0); PG8_MMA(0, 1, At, B1); PG8_BAR;
;             PG8_LDA(At, 0, 1); PG8_STAGE(PG8_SA(0, 0), a2, voffA);
;             PG8_BAR; PG8_WAIT_L(0); PG8_MMA(1, 0, At, B0); PG8_BAR; PG8_SCHED;
;             PG8_STAGE(PG8_SB(0, 1), b2 + hstep, voffB);
;             PG8_WAIT_V(6); PG8_BAR; PG8_MMA(1, 1, At, B1); PG8_BAR;
	s_add_u32 s6, s36, 0xfffc0080
	s_addc_u32 s7, s37, -1
	s_add_i32 s58, 0, 0x10000
	v_add_u32_e32 v144, s58, v147
	ds_read_b128 v[140:143], v144
	ds_read_b128 v[152:155], v144 offset:1024
	ds_read_b128 v[168:171], v144 offset:2048
	ds_read_b128 v[172:175], v144 offset:3072
	s_cmp_eq_u32 s93, 12
	s_cselect_b32 s43, s11, s7
	s_cselect_b32 s42, s71, s6
	s_cselect_b32 s7, s9, s92
	s_cselect_b32 s6, s90, s91
	s_add_i32 m0, s49, 0xc000
	ds_read_b128 v[176:179], v150
	ds_read_b128 v[180:183], v150 offset:1024
	ds_read_b128 v[184:187], v150 offset:2048
	ds_read_b128 v[204:207], v150 offset:3072
	ds_read_b128 v[208:211], v150 offset:4096
	ds_read_b128 v[212:215], v150 offset:5120
	ds_read_b128 v[216:219], v150 offset:6144
	ds_read_b128 v[226:229], v150 offset:7168
	global_load_lds_dwordx4 v136, s[36:37]
	s_add_i32 m0, s49, 0xe000
	s_nop 0
	global_load_lds_dwordx4 v138, s[36:37]
	s_waitcnt lgkmcnt(8)
	s_barrier
	s_waitcnt lgkmcnt(0)
	s_setprio 1
	s_waitcnt lgkmcnt(0)
	v_mfma_f32_16x16x32_bf16 v[126:129], v[140:143], v[176:179], v[126:129]
	v_mfma_f32_16x16x32_bf16 v[122:125], v[168:171], v[176:179], v[122:125]
	v_mfma_f32_16x16x32_bf16 v[110:113], v[140:143], v[184:187], v[110:113]
	v_mfma_f32_16x16x32_bf16 v[106:109], v[168:171], v[184:187], v[106:109]
	v_mfma_f32_16x16x32_bf16 v[94:97], v[140:143], v[208:211], v[94:97]
	v_mfma_f32_16x16x32_bf16 v[90:93], v[168:171], v[208:211], v[90:93]
	v_mfma_f32_16x16x32_bf16 v[78:81], v[140:143], v[216:219], v[78:81]
	v_mfma_f32_16x16x32_bf16 v[74:77], v[168:171], v[216:219], v[74:77]
	v_mfma_f32_16x16x32_bf16 v[126:129], v[152:155], v[180:183], v[126:129]
	v_mfma_f32_16x16x32_bf16 v[122:125], v[172:175], v[180:183], v[122:125]
	v_mfma_f32_16x16x32_bf16 v[110:113], v[152:155], v[204:207], v[110:113]
	v_mfma_f32_16x16x32_bf16 v[106:109], v[172:175], v[204:207], v[106:109]
	v_mfma_f32_16x16x32_bf16 v[94:97], v[152:155], v[212:215], v[94:97]
	v_mfma_f32_16x16x32_bf16 v[90:93], v[172:175], v[212:215], v[90:93]
	v_mfma_f32_16x16x32_bf16 v[78:81], v[152:155], v[226:229], v[78:81]
	v_mfma_f32_16x16x32_bf16 v[74:77], v[172:175], v[226:229], v[74:77]
	s_setprio 0
	s_barrier
	s_add_i32 s70, 0, 0x14000
	v_add_u32_e32 v144, s70, v147
	s_add_i32 s58, s58, s48
	ds_read_b128 v[230:233], v144
	ds_read_b128 v[234:237], v144 offset:1024
	ds_read_b128 v[238:241], v144 offset:2048
	ds_read_b128 v[242:245], v144 offset:3072
	s_mov_b32 m0, s58
	s_nop 0
	global_load_lds_dwordx4 v0, s[6:7]
	s_add_i32 m0, s58, 0x2000
	s_nop 0
	global_load_lds_dwordx4 v130, s[6:7]
	s_barrier
	s_waitcnt lgkmcnt(0)
	s_setprio 1
	s_waitcnt lgkmcnt(0)
	v_mfma_f32_16x16x32_bf16 v[118:121], v[230:233], v[176:179], v[118:121]
	v_mfma_f32_16x16x32_bf16 v[114:117], v[238:241], v[176:179], v[114:117]
	v_mfma_f32_16x16x32_bf16 v[102:105], v[230:233], v[184:187], v[102:105]
	v_mfma_f32_16x16x32_bf16 v[98:101], v[238:241], v[184:187], v[98:101]
	v_mfma_f32_16x16x32_bf16 v[86:89], v[230:233], v[208:211], v[86:89]
	v_mfma_f32_16x16x32_bf16 v[82:85], v[238:241], v[208:211], v[82:85]
	v_mfma_f32_16x16x32_bf16 v[70:73], v[230:233], v[216:219], v[70:73]
	v_mfma_f32_16x16x32_bf16 v[66:69], v[238:241], v[216:219], v[66:69]
	v_mfma_f32_16x16x32_bf16 v[118:121], v[234:237], v[180:183], v[118:121]
	v_mfma_f32_16x16x32_bf16 v[114:117], v[242:245], v[180:183], v[114:117]
	v_mfma_f32_16x16x32_bf16 v[102:105], v[234:237], v[204:207], v[102:105]
	v_mfma_f32_16x16x32_bf16 v[98:101], v[242:245], v[204:207], v[98:101]
	v_mfma_f32_16x16x32_bf16 v[86:89], v[234:237], v[212:215], v[86:89]
	v_mfma_f32_16x16x32_bf16 v[82:85], v[242:245], v[212:215], v[82:85]
	v_mfma_f32_16x16x32_bf16 v[70:73], v[234:237], v[226:229], v[70:73]
	v_mfma_f32_16x16x32_bf16 v[66:69], v[242:245], v[226:229], v[66:69]
	s_setprio 0
	s_mov_b32 m0, s49
	s_add_u32 vcc_lo, s42, 0x80
	s_addc_u32 vcc_hi, s43, 0
	s_barrier
	ds_read_b128 v[176:179], v150 offset:16384
	ds_read_b128 v[180:183], v150 offset:17408
	ds_read_b128 v[184:187], v150 offset:18432
	ds_read_b128 v[204:207], v150 offset:19456
	ds_read_b128 v[208:211], v150 offset:20480
	ds_read_b128 v[212:215], v150 offset:21504
	ds_read_b128 v[216:219], v150 offset:22528
	ds_read_b128 v[226:229], v150 offset:23552
	global_load_lds_dwordx4 v134, s[42:43]
	s_mov_b32 m0, s54
	s_nop 0
	global_load_lds_dwordx4 v132, s[42:43]
	s_barrier
	s_waitcnt lgkmcnt(0)
	s_setprio 1
	s_waitcnt lgkmcnt(0)
	v_mfma_f32_16x16x32_bf16 v[62:65], v[140:143], v[176:179], v[62:65]
	v_mfma_f32_16x16x32_bf16 v[58:61], v[168:171], v[176:179], v[58:61]
	v_mfma_f32_16x16x32_bf16 v[46:49], v[140:143], v[184:187], v[46:49]
	v_mfma_f32_16x16x32_bf16 v[42:45], v[168:171], v[184:187], v[42:45]
	v_mfma_f32_16x16x32_bf16 v[30:33], v[140:143], v[208:211], v[30:33]
	v_mfma_f32_16x16x32_bf16 v[26:29], v[168:171], v[208:211], v[26:29]
	v_mfma_f32_16x16x32_bf16 v[14:17], v[140:143], v[216:219], v[14:17]
	v_mfma_f32_16x16x32_bf16 v[10:13], v[168:171], v[216:219], v[10:13]
	v_mfma_f32_16x16x32_bf16 v[62:65], v[152:155], v[180:183], v[62:65]
	v_mfma_f32_16x16x32_bf16 v[58:61], v[172:175], v[180:183], v[58:61]
	v_mfma_f32_16x16x32_bf16 v[46:49], v[152:155], v[204:207], v[46:49]
	v_mfma_f32_16x16x32_bf16 v[42:45], v[172:175], v[204:207], v[42:45]
	v_mfma_f32_16x16x32_bf16 v[30:33], v[152:155], v[212:215], v[30:33]
	v_mfma_f32_16x16x32_bf16 v[26:29], v[172:175], v[212:215], v[26:29]
	v_mfma_f32_16x16x32_bf16 v[14:17], v[152:155], v[226:229], v[14:17]
	v_mfma_f32_16x16x32_bf16 v[10:13], v[172:175], v[226:229], v[10:13]
	s_setprio 0
	s_barrier
	s_add_u32 s60, s6, 0x40000
	s_addc_u32 s61, s7, 0
	s_add_i32 s58, s70, s48
	s_mov_b32 m0, s58
	s_nop 0
	global_load_lds_dwordx4 v0, s[60:61]
	s_add_i32 m0, s58, 0x2000
	s_nop 0
	global_load_lds_dwordx4 v130, s[60:61]
	s_waitcnt vmcnt(6)
	s_barrier
	s_setprio 1
	v_mfma_f32_16x16x32_bf16 v[54:57], v[230:233], v[176:179], v[54:57]
	v_mfma_f32_16x16x32_bf16 v[50:53], v[238:241], v[176:179], v[50:53]
	s_cmp_eq_u32 s89, 0
	s_cbranch_scc1 .LdsE_skip_4
	global_store_dwordx4 v250, v[196:199], s[4:5]
; #define PG8_STAGE(bufoff, gbase, voff) do { _Pragma("unroll") for (int _i = 0; _i < 2; ++_i) \
;         __builtin_amdgcn_global_load_lds((const unsigned*)((const char*)(gbase) + (voff)[_i]), (LAS unsigned*)(lds + (bufoff) + ldsw + _i * 8192), 16, 0, 0); } while (0)
; #define PG8_LDA(dst, b, h) do { _Pragma("unroll") for (int m = 0; m < 4; ++m) _Pragma("unroll") for (int k = 0; k < 2; ++k) dst[m][k] = *(const LAS bf16x8*)(lds + PG8_SA(b, h) + aoff + m * 2048 + k * 1024); } while (0)
; #define PG8_LDB(dst, b, h) do { _Pragma("unroll") for (int n = 0; n < 2; ++n) _Pragma("unroll") for (int k = 0; k < 2; ++k) dst[n][k] = *(const LAS bf16x8*)(lds + PG8_SB(b, h) + boff + n * 2048 + k * 1024); } while (0)
; #define PG8_MMA(ai, bj, At, Bt) do { __builtin_amdgcn_s_setprio(1); _Pragma("unroll") for (int m = 0; m < 4; ++m) _Pragma("unroll") for (int n = 0; n < 2; ++n) _Pragma("unroll") for (int k = 0; k < 2; ++k) \
;         acc[ai][bj][m][n] = __builtin_amdgcn_mfma_f32_16x16x32_bf16(Bt[n][k], At[m][k], acc[ai][bj][m][n], 0, 0, 0); __builtin_amdgcn_s_setprio(0); } while (0)
; #define PG8_WAIT_V(n) asm volatile("s_waitcnt vmcnt(" #n ")" ::: "memory")
; #define PG8_WAIT_L(n) asm volatile("s_waitcnt lgkmcnt(" #n ")" ::: "memory")
; #define PG8_BAR __builtin_amdgcn_s_barrier()
; #define PG8_SCHED __builtin_amdgcn_sched_barrier(0)
; template <class Epi>
; __device__ __forceinline__ void gemm_phase(LAS unsigned char* lds, const Gemm g, const StaticOrder& S, const Epi& E) {
;     ...
;             PG8_WAIT_V(6); PG8_BAR; PG8_MMA(1, 1, At, B1); PG8_BAR;
;             PG8_LDB(B0, 1, 0); PG8_SCHED; PG8_LDA(At, 1, 0); PG8_STAGE(PG8_SA(0, 1), a2 + hstep, voffA);
;             PG8_WAIT_L(8); PG8_BAR; PG8_WAIT_L(0); PG8_MMA(0, 0, At, B0); PG8_BAR; PG8_SCHED;
;             PG8_LDB(B1, 1, 1); PG8_STAGE(PG8_SB(1, 0), b3, voffB);
;             PG8_BAR; PG8_WAIT_L(0); PG8_MMA(0, 1, At, B1); PG8_BAR;
;             PG8_LDA(At, 1, 1); PG8_STAGE(PG8_SA(1, 0), a3, voffA);
;             PG8_BAR; PG8_WAIT_L(0); PG8_MMA(1, 0, At, B0); PG8_BAR; PG8_SCHED;
.LdsE_skip_4:
	v_mfma_f32_16x16x32_bf16 v[38:41], v[230:233], v[184:187], v[38:41]
	v_mfma_f32_16x16x32_bf16 v[34:37], v[238:241], v[184:187], v[34:37]
	v_mfma_f32_16x16x32_bf16 v[22:25], v[230:233], v[208:211], v[22:25]
	v_mfma_f32_16x16x32_bf16 v[18:21], v[238:241], v[208:211], v[18:21]
	v_mfma_f32_16x16x32_bf16 v[6:9], v[230:233], v[216:219], v[6:9]
	v_mfma_f32_16x16x32_bf16 v[2:5], v[238:241], v[216:219], v[2:5]
	v_mfma_f32_16x16x32_bf16 v[54:57], v[234:237], v[180:183], v[54:57]
	v_mfma_f32_16x16x32_bf16 v[50:53], v[242:245], v[180:183], v[50:53]
	v_mfma_f32_16x16x32_bf16 v[38:41], v[234:237], v[204:207], v[38:41]
	v_mfma_f32_16x16x32_bf16 v[34:37], v[242:245], v[204:207], v[34:37]
	v_mfma_f32_16x16x32_bf16 v[22:25], v[234:237], v[212:215], v[22:25]
	v_mfma_f32_16x16x32_bf16 v[18:21], v[242:245], v[212:215], v[18:21]
	v_mfma_f32_16x16x32_bf16 v[6:9], v[234:237], v[226:229], v[6:9]
	v_mfma_f32_16x16x32_bf16 v[2:5], v[242:245], v[226:229], v[2:5]
	s_setprio 0
	s_add_i32 s58, 0, 0x18000
	v_add_u32_e32 v151, s58, v147
	s_barrier
	ds_read_b128 v[140:143], v151
	ds_read_b128 v[152:155], v151 offset:1024
	ds_read_b128 v[168:171], v151 offset:2048
	ds_read_b128 v[172:175], v151 offset:3072
	s_add_u32 s42, s42, 0x40000
	s_addc_u32 s43, s43, 0
	s_mov_b32 m0, s55
	ds_read_b128 v[176:179], v150 offset:32768
	ds_read_b128 v[180:183], v150 offset:33792
	ds_read_b128 v[184:187], v150 offset:34816
	ds_read_b128 v[204:207], v150 offset:35840
	ds_read_b128 v[208:211], v150 offset:36864
	ds_read_b128 v[212:215], v150 offset:37888
	ds_read_b128 v[216:219], v150 offset:38912
	ds_read_b128 v[226:229], v150 offset:39936
	global_load_lds_dwordx4 v134, s[42:43]
	s_mov_b32 m0, s83
	s_nop 0
	global_load_lds_dwordx4 v132, s[42:43]
	s_waitcnt lgkmcnt(8)
	s_barrier
	s_waitcnt lgkmcnt(0)
	s_setprio 1
	s_waitcnt lgkmcnt(0)
	v_mfma_f32_16x16x32_bf16 v[126:129], v[140:143], v[176:179], v[126:129]
	v_mfma_f32_16x16x32_bf16 v[122:125], v[168:171], v[176:179], v[122:125]
	v_mfma_f32_16x16x32_bf16 v[110:113], v[140:143], v[184:187], v[110:113]
	v_mfma_f32_16x16x32_bf16 v[106:109], v[168:171], v[184:187], v[106:109]
	v_mfma_f32_16x16x32_bf16 v[94:97], v[140:143], v[208:211], v[94:97]
	v_mfma_f32_16x16x32_bf16 v[90:93], v[168:171], v[208:211], v[90:93]
	v_mfma_f32_16x16x32_bf16 v[78:81], v[140:143], v[216:219], v[78:81]
	v_mfma_f32_16x16x32_bf16 v[74:77], v[168:171], v[216:219], v[74:77]
	v_mfma_f32_16x16x32_bf16 v[126:129], v[152:155], v[180:183], v[126:129]
	v_mfma_f32_16x16x32_bf16 v[122:125], v[172:175], v[180:183], v[122:125]
	v_mfma_f32_16x16x32_bf16 v[110:113], v[152:155], v[204:207], v[110:113]
	v_mfma_f32_16x16x32_bf16 v[106:109], v[172:175], v[204:207], v[106:109]
	v_mfma_f32_16x16x32_bf16 v[94:97], v[152:155], v[212:215], v[94:97]
	v_mfma_f32_16x16x32_bf16 v[90:93], v[172:175], v[212:215], v[90:93]
	v_mfma_f32_16x16x32_bf16 v[78:81], v[152:155], v[226:229], v[78:81]
	v_mfma_f32_16x16x32_bf16 v[74:77], v[172:175], v[226:229], v[74:77]
	s_setprio 0
	s_barrier
	s_add_i32 s42, 0, 0x1c000
	s_add_i32 s43, s58, s48
	v_add_u32_e32 v151, s42, v147
	s_add_u32 s60, s6, 0x80
	s_addc_u32 s61, s7, 0
	s_mov_b32 m0, s43
	ds_read_b128 v[230:233], v151
	ds_read_b128 v[234:237], v151 offset:1024
	ds_read_b128 v[238:241], v151 offset:2048
	ds_read_b128 v[242:245], v151 offset:3072
	global_load_lds_dwordx4 v0, s[60:61]
	s_add_i32 m0, s43, 0x2000
	s_nop 0
	global_load_lds_dwordx4 v130, s[60:61]
	s_barrier
	s_waitcnt lgkmcnt(0)
	s_setprio 1
	s_waitcnt lgkmcnt(0)
	v_mfma_f32_16x16x32_bf16 v[118:121], v[230:233], v[176:179], v[118:121]
	v_mfma_f32_16x16x32_bf16 v[114:117], v[238:241], v[176:179], v[114:117]
	v_mfma_f32_16x16x32_bf16 v[102:105], v[230:233], v[184:187], v[102:105]
	v_mfma_f32_16x16x32_bf16 v[98:101], v[238:241], v[184:187], v[98:101]
	v_mfma_f32_16x16x32_bf16 v[86:89], v[230:233], v[208:211], v[86:89]
	v_mfma_f32_16x16x32_bf16 v[82:85], v[238:241], v[208:211], v[82:85]
	v_mfma_f32_16x16x32_bf16 v[70:73], v[230:233], v[216:219], v[70:73]
	v_mfma_f32_16x16x32_bf16 v[66:69], v[238:241], v[216:219], v[66:69]
	v_mfma_f32_16x16x32_bf16 v[118:121], v[234:237], v[180:183], v[118:121]
	v_mfma_f32_16x16x32_bf16 v[114:117], v[242:245], v[180:183], v[114:117]
	v_mfma_f32_16x16x32_bf16 v[102:105], v[234:237], v[204:207], v[102:105]
	v_mfma_f32_16x16x32_bf16 v[98:101], v[242:245], v[204:207], v[98:101]
	v_mfma_f32_16x16x32_bf16 v[86:89], v[234:237], v[212:215], v[86:89]
	v_mfma_f32_16x16x32_bf16 v[82:85], v[242:245], v[212:215], v[82:85]
	v_mfma_f32_16x16x32_bf16 v[70:73], v[234:237], v[226:229], v[70:73]
	v_mfma_f32_16x16x32_bf16 v[66:69], v[242:245], v[226:229], v[66:69]
	s_setprio 0
	s_mov_b32 m0, s84
	s_barrier
	ds_read_b128 v[176:179], v150 offset:49152
	ds_read_b128 v[180:183], v150 offset:50176
	ds_read_b128 v[184:187], v150 offset:51200
	ds_read_b128 v[204:207], v150 offset:52224
	ds_read_b128 v[208:211], v150 offset:53248
	ds_read_b128 v[212:215], v150 offset:54272
	ds_read_b128 v[216:219], v150 offset:55296
	ds_read_b128 v[226:229], v150 offset:56320
	global_load_lds_dwordx4 v134, vcc
	s_mov_b32 m0, s85
	s_nop 0
	global_load_lds_dwordx4 v132, vcc
	s_barrier
; #define PG8_STAGE(bufoff, gbase, voff) do { _Pragma("unroll") for (int _i = 0; _i < 2; ++_i) \
;         __builtin_amdgcn_global_load_lds((const unsigned*)((const char*)(gbase) + (voff)[_i]), (LAS unsigned*)(lds + (bufoff) + ldsw + _i * 8192), 16, 0, 0); } while (0)
; #define PG8_LDA(dst, b, h) do { _Pragma("unroll") for (int m = 0; m < 4; ++m) _Pragma("unroll") for (int k = 0; k < 2; ++k) dst[m][k] = *(const LAS bf16x8*)(lds + PG8_SA(b, h) + aoff + m * 2048 + k * 1024); } while (0)
; #define PG8_WAIT_V(n) asm volatile("s_waitcnt vmcnt(" #n ")" ::: "memory")
; #define PG8_WAIT_L(n) asm volatile("s_waitcnt lgkmcnt(" #n ")" ::: "memory")
; template <class Epi>
; __device__ __forceinline__ void gemm_phase(LAS unsigned char* lds, const Gemm g, const StaticOrder& S, const Epi& E) {
;     ...
;             const bool last = (t == nt - 2);
;             const char* a1 = cA + (size_t)(t + 1) * kstep;
;             const char* a2 = last ? nA : cA + (size_t)(t + 2) * kstep; const char* b2 = last ? nB : cB + (size_t)(t + 2) * kstep;
;             const char* a3 = a2 + kstep; const char* b3 = b2 + kstep;
;             PG8_LDB(B0, 0, 0); PG8_SCHED; PG8_LDA(At, 0, 0); PG8_STAGE(PG8_SA(1, 1), a1 + hstep, voffA);
;             PG8_WAIT_L(8); PG8_BAR; PG8_WAIT_L(0); PG8_MMA(0, 0, At, B0); PG8_BAR; PG8_SCHED;
;             PG8_LDB(B1, 0, 1); PG8_STAGE(PG8_SB(0, 0), b2, voffB);
;             PG8_BAR; PG8_WAIT_L(0); PG8_MMA(0, 1, At, B1); PG8_BAR;
;             PG8_LDA(At, 0, 1); PG8_STAGE(PG8_SA(0, 0), a2, voffA);
;             PG8_BAR; PG8_WAIT_L(0); PG8_MMA(1, 0, At, B0); PG8_BAR; PG8_SCHED;
;             PG8_STAGE(PG8_SB(0, 1), b2 + hstep, voffB);
;             PG8_WAIT_V(6); PG8_BAR; PG8_MMA(1, 1, At, B1); PG8_BAR;
;             PG8_LDB(B0, 1, 0); PG8_SCHED; PG8_LDA(At, 1, 0); PG8_STAGE(PG8_SA(0, 1), a2 + hstep, voffA);
;             PG8_WAIT_L(8); PG8_BAR; PG8_WAIT_L(0); PG8_MMA(0, 0, At, B0); PG8_BAR; PG8_SCHED;
;             PG8_LDB(B1, 1, 1); PG8_STAGE(PG8_SB(1, 0), b3, voffB);
;             PG8_BAR; PG8_WAIT_L(0); PG8_MMA(0, 1, At, B1); PG8_BAR;
;             PG8_LDA(At, 1, 1); PG8_STAGE(PG8_SA(1, 0), a3, voffA);
;             PG8_BAR; PG8_WAIT_L(0); PG8_MMA(1, 0, At, B0); PG8_BAR; PG8_SCHED;
;             PG8_STAGE(PG8_SB(1, 1), b3 + hstep, voffB);
;             PG8_WAIT_V(6); PG8_BAR; PG8_MMA(1, 1, At, B1); PG8_BAR;
;         }
	s_waitcnt lgkmcnt(0)
	s_setprio 1
	s_waitcnt lgkmcnt(0)
	v_mfma_f32_16x16x32_bf16 v[62:65], v[140:143], v[176:179], v[62:65]
	v_mfma_f32_16x16x32_bf16 v[58:61], v[168:171], v[176:179], v[58:61]
	v_mfma_f32_16x16x32_bf16 v[46:49], v[140:143], v[184:187], v[46:49]
	v_mfma_f32_16x16x32_bf16 v[42:45], v[168:171], v[184:187], v[42:45]
	v_mfma_f32_16x16x32_bf16 v[30:33], v[140:143], v[208:211], v[30:33]
	v_mfma_f32_16x16x32_bf16 v[26:29], v[168:171], v[208:211], v[26:29]
	v_mfma_f32_16x16x32_bf16 v[14:17], v[140:143], v[216:219], v[14:17]
	v_mfma_f32_16x16x32_bf16 v[10:13], v[168:171], v[216:219], v[10:13]
	v_mfma_f32_16x16x32_bf16 v[62:65], v[152:155], v[180:183], v[62:65]
	v_mfma_f32_16x16x32_bf16 v[58:61], v[172:175], v[180:183], v[58:61]
	v_mfma_f32_16x16x32_bf16 v[46:49], v[152:155], v[204:207], v[46:49]
	v_mfma_f32_16x16x32_bf16 v[42:45], v[172:175], v[204:207], v[42:45]
	v_mfma_f32_16x16x32_bf16 v[30:33], v[152:155], v[212:215], v[30:33]
	v_mfma_f32_16x16x32_bf16 v[26:29], v[172:175], v[212:215], v[26:29]
	v_mfma_f32_16x16x32_bf16 v[14:17], v[152:155], v[226:229], v[14:17]
	v_mfma_f32_16x16x32_bf16 v[10:13], v[172:175], v[226:229], v[10:13]
	s_setprio 0
	s_barrier
	s_add_u32 s6, s6, 0x40080
	s_addc_u32 s7, s7, 0
	s_add_i32 s42, s42, s48
	s_mov_b32 m0, s42
	s_nop 0
	global_load_lds_dwordx4 v0, s[6:7]
	s_add_i32 m0, s42, 0x2000
	s_nop 0
	global_load_lds_dwordx4 v130, s[6:7]
	s_waitcnt vmcnt(6)
	s_barrier
	s_setprio 1
	v_mfma_f32_16x16x32_bf16 v[54:57], v[230:233], v[176:179], v[54:57]
	v_mfma_f32_16x16x32_bf16 v[50:53], v[238:241], v[176:179], v[50:53]
	v_mfma_f32_16x16x32_bf16 v[38:41], v[230:233], v[184:187], v[38:41]
	v_mfma_f32_16x16x32_bf16 v[34:37], v[238:241], v[184:187], v[34:37]
	v_mfma_f32_16x16x32_bf16 v[22:25], v[230:233], v[208:211], v[22:25]
	v_mfma_f32_16x16x32_bf16 v[18:21], v[238:241], v[208:211], v[18:21]
	v_mfma_f32_16x16x32_bf16 v[6:9], v[230:233], v[216:219], v[6:9]
	v_mfma_f32_16x16x32_bf16 v[2:5], v[238:241], v[216:219], v[2:5]
	v_mfma_f32_16x16x32_bf16 v[54:57], v[234:237], v[180:183], v[54:57]
	v_mfma_f32_16x16x32_bf16 v[50:53], v[242:245], v[180:183], v[50:53]
	v_mfma_f32_16x16x32_bf16 v[38:41], v[234:237], v[204:207], v[38:41]
	v_mfma_f32_16x16x32_bf16 v[34:37], v[242:245], v[204:207], v[34:37]
	v_mfma_f32_16x16x32_bf16 v[22:25], v[234:237], v[212:215], v[22:25]
	v_mfma_f32_16x16x32_bf16 v[18:21], v[242:245], v[212:215], v[18:21]
	v_mfma_f32_16x16x32_bf16 v[6:9], v[234:237], v[226:229], v[6:9]
	v_mfma_f32_16x16x32_bf16 v[2:5], v[242:245], v[226:229], v[2:5]
	s_setprio 0
	s_add_i32 s93, s93, 2
	s_add_u32 s36, s36, 0x100
	s_addc_u32 s37, s37, 0
	s_add_u32 s91, s91, 0x100
	s_addc_u32 s92, s92, 0
	s_cmp_gt_u32 s93, 13
	s_barrier
	s_add_u32 s6, s36, 0xfffc0080
	s_addc_u32 s7, s37, -1
	s_add_i32 s58, 0, 0x10000
	v_add_u32_e32 v144, s58, v147
	ds_read_b128 v[140:143], v144
	ds_read_b128 v[152:155], v144 offset:1024
	ds_read_b128 v[168:171], v144 offset:2048
	ds_read_b128 v[172:175], v144 offset:3072
	s_cmp_eq_u32 s93, 12
	s_cselect_b32 s43, s11, s7
	s_cselect_b32 s42, s71, s6
	s_cselect_b32 s7, s9, s92
	s_cselect_b32 s6, s90, s91
	s_add_i32 m0, s49, 0xc000
	ds_read_b128 v[176:179], v150
	ds_read_b128 v[180:183], v150 offset:1024
	ds_read_b128 v[184:187], v150 offset:2048
	ds_read_b128 v[204:207], v150 offset:3072
	ds_read_b128 v[208:211], v150 offset:4096
	ds_read_b128 v[212:215], v150 offset:5120
	ds_read_b128 v[216:219], v150 offset:6144
	ds_read_b128 v[226:229], v150 offset:7168
	global_load_lds_dwordx4 v136, s[36:37]
	s_add_i32 m0, s49, 0xe000
	s_nop 0
	global_load_lds_dwordx4 v138, s[36:37]
	s_waitcnt lgkmcnt(8)
	s_barrier
	s_waitcnt lgkmcnt(0)
	s_setprio 1
	s_waitcnt lgkmcnt(0)
	v_mfma_f32_16x16x32_bf16 v[126:129], v[140:143], v[176:179], v[126:129]
	v_mfma_f32_16x16x32_bf16 v[122:125], v[168:171], v[176:179], v[122:125]
	v_mfma_f32_16x16x32_bf16 v[110:113], v[140:143], v[184:187], v[110:113]
	v_mfma_f32_16x16x32_bf16 v[106:109], v[168:171], v[184:187], v[106:109]
	v_mfma_f32_16x16x32_bf16 v[94:97], v[140:143], v[208:211], v[94:97]
	v_mfma_f32_16x16x32_bf16 v[90:93], v[168:171], v[208:211], v[90:93]
	v_mfma_f32_16x16x32_bf16 v[78:81], v[140:143], v[216:219], v[78:81]
	v_mfma_f32_16x16x32_bf16 v[74:77], v[168:171], v[216:219], v[74:77]
	v_mfma_f32_16x16x32_bf16 v[126:129], v[152:155], v[180:183], v[126:129]
	v_mfma_f32_16x16x32_bf16 v[122:125], v[172:175], v[180:183], v[122:125]
	v_mfma_f32_16x16x32_bf16 v[110:113], v[152:155], v[204:207], v[110:113]
	v_mfma_f32_16x16x32_bf16 v[106:109], v[172:175], v[204:207], v[106:109]
	v_mfma_f32_16x16x32_bf16 v[94:97], v[152:155], v[212:215], v[94:97]
	v_mfma_f32_16x16x32_bf16 v[90:93], v[172:175], v[212:215], v[90:93]
	v_mfma_f32_16x16x32_bf16 v[78:81], v[152:155], v[226:229], v[78:81]
	v_mfma_f32_16x16x32_bf16 v[74:77], v[172:175], v[226:229], v[74:77]
	s_setprio 0
	s_barrier
	s_add_i32 s70, 0, 0x14000
	v_add_u32_e32 v144, s70, v147
	s_add_i32 s58, s58, s48
	ds_read_b128 v[230:233], v144
	ds_read_b128 v[234:237], v144 offset:1024
	ds_read_b128 v[238:241], v144 offset:2048
	ds_read_b128 v[242:245], v144 offset:3072
	s_mov_b32 m0, s58
	s_nop 0
	global_load_lds_dwordx4 v0, s[6:7]
	s_add_i32 m0, s58, 0x2000
	s_nop 0
	global_load_lds_dwordx4 v130, s[6:7]
	s_barrier
; #define PG8_STAGE(bufoff, gbase, voff) do { _Pragma("unroll") for (int _i = 0; _i < 2; ++_i) \
;         __builtin_amdgcn_global_load_lds((const unsigned*)((const char*)(gbase) + (voff)[_i]), (LAS unsigned*)(lds + (bufoff) + ldsw + _i * 8192), 16, 0, 0); } while (0)
; #define PG8_LDA(dst, b, h) do { _Pragma("unroll") for (int m = 0; m < 4; ++m) _Pragma("unroll") for (int k = 0; k < 2; ++k) dst[m][k] = *(const LAS bf16x8*)(lds + PG8_SA(b, h) + aoff + m * 2048 + k * 1024); } while (0)
; #define PG8_LDB(dst, b, h) do { _Pragma("unroll") for (int n = 0; n < 2; ++n) _Pragma("unroll") for (int k = 0; k < 2; ++k) dst[n][k] = *(const LAS bf16x8*)(lds + PG8_SB(b, h) + boff + n * 2048 + k * 1024); } while (0)
; #define PG8_MMA(ai, bj, At, Bt) do { __builtin_amdgcn_s_setprio(1); _Pragma("unroll") for (int m = 0; m < 4; ++m) _Pragma("unroll") for (int n = 0; n < 2; ++n) _Pragma("unroll") for (int k = 0; k < 2; ++k) \
;         acc[ai][bj][m][n] = __builtin_amdgcn_mfma_f32_16x16x32_bf16(Bt[n][k], At[m][k], acc[ai][bj][m][n], 0, 0, 0); __builtin_amdgcn_s_setprio(0); } while (0)
; #define PG8_WAIT_V(n) asm volatile("s_waitcnt vmcnt(" #n ")" ::: "memory")
; #define PG8_WAIT_L(n) asm volatile("s_waitcnt lgkmcnt(" #n ")" ::: "memory")
; #define PG8_BAR __builtin_amdgcn_s_barrier()
; #define PG8_SCHED __builtin_amdgcn_sched_barrier(0)
; template <class Epi>
; __device__ __forceinline__ void gemm_phase(LAS unsigned char* lds, const Gemm g, const StaticOrder& S, const Epi& E) {
;     ...
;             PG8_BAR; PG8_WAIT_L(0); PG8_MMA(0, 1, At, B1); PG8_BAR;
;             PG8_LDA(At, 0, 1); PG8_STAGE(PG8_SA(0, 0), a2, voffA);
;             PG8_BAR; PG8_WAIT_L(0); PG8_MMA(1, 0, At, B0); PG8_BAR; PG8_SCHED;
;             PG8_STAGE(PG8_SB(0, 1), b2 + hstep, voffB);
;             PG8_WAIT_V(6); PG8_BAR; PG8_MMA(1, 1, At, B1); PG8_BAR;
;             PG8_LDB(B0, 1, 0); PG8_SCHED; PG8_LDA(At, 1, 0); PG8_STAGE(PG8_SA(0, 1), a2 + hstep, voffA);
;             PG8_WAIT_L(8); PG8_BAR; PG8_WAIT_L(0); PG8_MMA(0, 0, At, B0); PG8_BAR; PG8_SCHED;
;             PG8_LDB(B1, 1, 1); PG8_STAGE(PG8_SB(1, 0), b3, voffB);
;             PG8_BAR; PG8_WAIT_L(0); PG8_MMA(0, 1, At, B1); PG8_BAR;
;             PG8_LDA(At, 1, 1); PG8_STAGE(PG8_SA(1, 0), a3, voffA);
;             PG8_BAR; PG8_WAIT_L(0); PG8_MMA(1, 0, At, B0); PG8_BAR; PG8_SCHED;
	s_waitcnt lgkmcnt(0)
	s_setprio 1
	s_waitcnt lgkmcnt(0)
	v_mfma_f32_16x16x32_bf16 v[118:121], v[230:233], v[176:179], v[118:121]
	v_mfma_f32_16x16x32_bf16 v[114:117], v[238:241], v[176:179], v[114:117]
	v_mfma_f32_16x16x32_bf16 v[102:105], v[230:233], v[184:187], v[102:105]
	v_mfma_f32_16x16x32_bf16 v[98:101], v[238:241], v[184:187], v[98:101]
	v_mfma_f32_16x16x32_bf16 v[86:89], v[230:233], v[208:211], v[86:89]
	v_mfma_f32_16x16x32_bf16 v[82:85], v[238:241], v[208:211], v[82:85]
	v_mfma_f32_16x16x32_bf16 v[70:73], v[230:233], v[216:219], v[70:73]
	v_mfma_f32_16x16x32_bf16 v[66:69], v[238:241], v[216:219], v[66:69]
	v_mfma_f32_16x16x32_bf16 v[118:121], v[234:237], v[180:183], v[118:121]
	v_mfma_f32_16x16x32_bf16 v[114:117], v[242:245], v[180:183], v[114:117]
	v_mfma_f32_16x16x32_bf16 v[102:105], v[234:237], v[204:207], v[102:105]
	v_mfma_f32_16x16x32_bf16 v[98:101], v[242:245], v[204:207], v[98:101]
	v_mfma_f32_16x16x32_bf16 v[86:89], v[234:237], v[212:215], v[86:89]
	v_mfma_f32_16x16x32_bf16 v[82:85], v[242:245], v[212:215], v[82:85]
	v_mfma_f32_16x16x32_bf16 v[70:73], v[234:237], v[226:229], v[70:73]
	v_mfma_f32_16x16x32_bf16 v[66:69], v[242:245], v[226:229], v[66:69]
	s_setprio 0
	s_mov_b32 m0, s49
	s_add_u32 vcc_lo, s42, 0x80
	s_addc_u32 vcc_hi, s43, 0
	s_barrier
	ds_read_b128 v[176:179], v150 offset:16384
	ds_read_b128 v[180:183], v150 offset:17408
	ds_read_b128 v[184:187], v150 offset:18432
	ds_read_b128 v[204:207], v150 offset:19456
	ds_read_b128 v[208:211], v150 offset:20480
	ds_read_b128 v[212:215], v150 offset:21504
	ds_read_b128 v[216:219], v150 offset:22528
	ds_read_b128 v[226:229], v150 offset:23552
	global_load_lds_dwordx4 v134, s[42:43]
	s_mov_b32 m0, s54
	s_nop 0
	global_load_lds_dwordx4 v132, s[42:43]
	s_barrier
	s_waitcnt lgkmcnt(0)
	s_setprio 1
	s_waitcnt lgkmcnt(0)
	v_mfma_f32_16x16x32_bf16 v[62:65], v[140:143], v[176:179], v[62:65]
	v_mfma_f32_16x16x32_bf16 v[58:61], v[168:171], v[176:179], v[58:61]
	v_mfma_f32_16x16x32_bf16 v[46:49], v[140:143], v[184:187], v[46:49]
	v_mfma_f32_16x16x32_bf16 v[42:45], v[168:171], v[184:187], v[42:45]
	v_mfma_f32_16x16x32_bf16 v[30:33], v[140:143], v[208:211], v[30:33]
	v_mfma_f32_16x16x32_bf16 v[26:29], v[168:171], v[208:211], v[26:29]
	v_mfma_f32_16x16x32_bf16 v[14:17], v[140:143], v[216:219], v[14:17]
	v_mfma_f32_16x16x32_bf16 v[10:13], v[168:171], v[216:219], v[10:13]
	v_mfma_f32_16x16x32_bf16 v[62:65], v[152:155], v[180:183], v[62:65]
	v_mfma_f32_16x16x32_bf16 v[58:61], v[172:175], v[180:183], v[58:61]
	v_mfma_f32_16x16x32_bf16 v[46:49], v[152:155], v[204:207], v[46:49]
	v_mfma_f32_16x16x32_bf16 v[42:45], v[172:175], v[204:207], v[42:45]
	v_mfma_f32_16x16x32_bf16 v[30:33], v[152:155], v[212:215], v[30:33]
	v_mfma_f32_16x16x32_bf16 v[26:29], v[172:175], v[212:215], v[26:29]
	v_mfma_f32_16x16x32_bf16 v[14:17], v[152:155], v[226:229], v[14:17]
	v_mfma_f32_16x16x32_bf16 v[10:13], v[172:175], v[226:229], v[10:13]
	s_setprio 0
	s_barrier
	s_add_u32 s60, s6, 0x40000
	s_addc_u32 s61, s7, 0
	s_add_i32 s58, s70, s48
	s_mov_b32 m0, s58
	s_nop 0
	global_load_lds_dwordx4 v0, s[60:61]
	s_add_i32 m0, s58, 0x2000
	s_nop 0
	global_load_lds_dwordx4 v130, s[60:61]
	s_waitcnt vmcnt(6)
	s_barrier
	s_setprio 1
	v_mfma_f32_16x16x32_bf16 v[54:57], v[230:233], v[176:179], v[54:57]
	v_mfma_f32_16x16x32_bf16 v[50:53], v[238:241], v[176:179], v[50:53]
	s_cmp_eq_u32 s89, 0
	s_cbranch_scc1 .LdsE_skip_5
	global_store_dwordx4 v250, v[200:203], s[4:5] offset:256
	v_add_u32_e32 v250, 0x20000, v250
.LdsE_skip_5:
	v_mfma_f32_16x16x32_bf16 v[38:41], v[230:233], v[184:187], v[38:41]
	v_mfma_f32_16x16x32_bf16 v[34:37], v[238:241], v[184:187], v[34:37]
	v_mfma_f32_16x16x32_bf16 v[22:25], v[230:233], v[208:211], v[22:25]
	v_mfma_f32_16x16x32_bf16 v[18:21], v[238:241], v[208:211], v[18:21]
	v_mfma_f32_16x16x32_bf16 v[6:9], v[230:233], v[216:219], v[6:9]
	v_mfma_f32_16x16x32_bf16 v[2:5], v[238:241], v[216:219], v[2:5]
	v_mfma_f32_16x16x32_bf16 v[54:57], v[234:237], v[180:183], v[54:57]
	v_mfma_f32_16x16x32_bf16 v[50:53], v[242:245], v[180:183], v[50:53]
	v_mfma_f32_16x16x32_bf16 v[38:41], v[234:237], v[204:207], v[38:41]
	v_mfma_f32_16x16x32_bf16 v[34:37], v[242:245], v[204:207], v[34:37]
	v_mfma_f32_16x16x32_bf16 v[22:25], v[234:237], v[212:215], v[22:25]
	v_mfma_f32_16x16x32_bf16 v[18:21], v[242:245], v[212:215], v[18:21]
	v_mfma_f32_16x16x32_bf16 v[6:9], v[234:237], v[226:229], v[6:9]
	v_mfma_f32_16x16x32_bf16 v[2:5], v[242:245], v[226:229], v[2:5]
	s_setprio 0
	s_add_i32 s58, 0, 0x18000
	v_add_u32_e32 v151, s58, v147
	s_barrier
	ds_read_b128 v[140:143], v151
	ds_read_b128 v[152:155], v151 offset:1024
	ds_read_b128 v[168:171], v151 offset:2048
	ds_read_b128 v[172:175], v151 offset:3072
	s_add_u32 s42, s42, 0x40000
	s_addc_u32 s43, s43, 0
	s_mov_b32 m0, s55
	ds_read_b128 v[176:179], v150 offset:32768
	ds_read_b128 v[180:183], v150 offset:33792
	ds_read_b128 v[184:187], v150 offset:34816
	ds_read_b128 v[204:207], v150 offset:35840
	ds_read_b128 v[208:211], v150 offset:36864
	ds_read_b128 v[212:215], v150 offset:37888
	ds_read_b128 v[216:219], v150 offset:38912
	ds_read_b128 v[226:229], v150 offset:39936
	global_load_lds_dwordx4 v134, s[42:43]
	s_mov_b32 m0, s83
	s_nop 0
	global_load_lds_dwordx4 v132, s[42:43]
	s_waitcnt lgkmcnt(8)
	s_barrier
; #define PG8_STAGE(bufoff, gbase, voff) do { _Pragma("unroll") for (int _i = 0; _i < 2; ++_i) \
;         __builtin_amdgcn_global_load_lds((const unsigned*)((const char*)(gbase) + (voff)[_i]), (LAS unsigned*)(lds + (bufoff) + ldsw + _i * 8192), 16, 0, 0); } while (0)
; #define PG8_LDA(dst, b, h) do { _Pragma("unroll") for (int m = 0; m < 4; ++m) _Pragma("unroll") for (int k = 0; k < 2; ++k) dst[m][k] = *(const LAS bf16x8*)(lds + PG8_SA(b, h) + aoff + m * 2048 + k * 1024); } while (0)
; #define PG8_LDB(dst, b, h) do { _Pragma("unroll") for (int n = 0; n < 2; ++n) _Pragma("unroll") for (int k = 0; k < 2; ++k) dst[n][k] = *(const LAS bf16x8*)(lds + PG8_SB(b, h) + boff + n * 2048 + k * 1024); } while (0)
; #define PG8_MMA(ai, bj, At, Bt) do { __builtin_amdgcn_s_setprio(1); _Pragma("unroll") for (int m = 0; m < 4; ++m) _Pragma("unroll") for (int n = 0; n < 2; ++n) _Pragma("unroll") for (int k = 0; k < 2; ++k) \
;         acc[ai][bj][m][n] = __builtin_amdgcn_mfma_f32_16x16x32_bf16(Bt[n][k], At[m][k], acc[ai][bj][m][n], 0, 0, 0); __builtin_amdgcn_s_setprio(0); } while (0)
; #define PG8_WAIT_V(n) asm volatile("s_waitcnt vmcnt(" #n ")" ::: "memory")
; #define PG8_WAIT_L(n) asm volatile("s_waitcnt lgkmcnt(" #n ")" ::: "memory")
; #define PG8_BAR __builtin_amdgcn_s_barrier()
; #define PG8_SCHED __builtin_amdgcn_sched_barrier(0)
; template <class Epi>
; __device__ __forceinline__ void gemm_phase(LAS unsigned char* lds, const Gemm g, const StaticOrder& S, const Epi& E) {
;     ...
;             PG8_WAIT_L(8); PG8_BAR; PG8_WAIT_L(0); PG8_MMA(0, 0, At, B0); PG8_BAR; PG8_SCHED;
;             PG8_LDB(B1, 1, 1); PG8_STAGE(PG8_SB(1, 0), b3, voffB);
;             PG8_BAR; PG8_WAIT_L(0); PG8_MMA(0, 1, At, B1); PG8_BAR;
;             PG8_LDA(At, 1, 1); PG8_STAGE(PG8_SA(1, 0), a3, voffA);
;             PG8_BAR; PG8_WAIT_L(0); PG8_MMA(1, 0, At, B0); PG8_BAR; PG8_SCHED;
;             PG8_STAGE(PG8_SB(1, 1), b3 + hstep, voffB);
;             PG8_WAIT_V(6); PG8_BAR; PG8_MMA(1, 1, At, B1); PG8_BAR;
;         }
	s_waitcnt lgkmcnt(0)
	s_setprio 1
	s_waitcnt lgkmcnt(0)
	v_mfma_f32_16x16x32_bf16 v[126:129], v[140:143], v[176:179], v[126:129]
	v_mfma_f32_16x16x32_bf16 v[122:125], v[168:171], v[176:179], v[122:125]
	v_mfma_f32_16x16x32_bf16 v[110:113], v[140:143], v[184:187], v[110:113]
	v_mfma_f32_16x16x32_bf16 v[106:109], v[168:171], v[184:187], v[106:109]
	v_mfma_f32_16x16x32_bf16 v[94:97], v[140:143], v[208:211], v[94:97]
	v_mfma_f32_16x16x32_bf16 v[90:93], v[168:171], v[208:211], v[90:93]
	v_mfma_f32_16x16x32_bf16 v[78:81], v[140:143], v[216:219], v[78:81]
	v_mfma_f32_16x16x32_bf16 v[74:77], v[168:171], v[216:219], v[74:77]
	v_mfma_f32_16x16x32_bf16 v[126:129], v[152:155], v[180:183], v[126:129]
	v_mfma_f32_16x16x32_bf16 v[122:125], v[172:175], v[180:183], v[122:125]
	v_mfma_f32_16x16x32_bf16 v[110:113], v[152:155], v[204:207], v[110:113]
	v_mfma_f32_16x16x32_bf16 v[106:109], v[172:175], v[204:207], v[106:109]
	v_mfma_f32_16x16x32_bf16 v[94:97], v[152:155], v[212:215], v[94:97]
	v_mfma_f32_16x16x32_bf16 v[90:93], v[172:175], v[212:215], v[90:93]
	v_mfma_f32_16x16x32_bf16 v[78:81], v[152:155], v[226:229], v[78:81]
	v_mfma_f32_16x16x32_bf16 v[74:77], v[172:175], v[226:229], v[74:77]
	s_setprio 0
	s_barrier
	s_add_i32 s42, 0, 0x1c000
	s_add_i32 s43, s58, s48
	v_add_u32_e32 v151, s42, v147
	s_add_u32 s60, s6, 0x80
	s_addc_u32 s61, s7, 0
	s_mov_b32 m0, s43
	ds_read_b128 v[230:233], v151
	ds_read_b128 v[234:237], v151 offset:1024
	ds_read_b128 v[238:241], v151 offset:2048
	ds_read_b128 v[242:245], v151 offset:3072
	global_load_lds_dwordx4 v0, s[60:61]
	s_add_i32 m0, s43, 0x2000
	s_nop 0
	global_load_lds_dwordx4 v130, s[60:61]
	s_barrier
	s_waitcnt lgkmcnt(0)
	s_setprio 1
	s_waitcnt lgkmcnt(0)
	v_mfma_f32_16x16x32_bf16 v[118:121], v[230:233], v[176:179], v[118:121]
	v_mfma_f32_16x16x32_bf16 v[114:117], v[238:241], v[176:179], v[114:117]
	v_mfma_f32_16x16x32_bf16 v[102:105], v[230:233], v[184:187], v[102:105]
	v_mfma_f32_16x16x32_bf16 v[98:101], v[238:241], v[184:187], v[98:101]
	v_mfma_f32_16x16x32_bf16 v[86:89], v[230:233], v[208:211], v[86:89]
	v_mfma_f32_16x16x32_bf16 v[82:85], v[238:241], v[208:211], v[82:85]
	v_mfma_f32_16x16x32_bf16 v[70:73], v[230:233], v[216:219], v[70:73]
	v_mfma_f32_16x16x32_bf16 v[66:69], v[238:241], v[216:219], v[66:69]
	v_mfma_f32_16x16x32_bf16 v[118:121], v[234:237], v[180:183], v[118:121]
	v_mfma_f32_16x16x32_bf16 v[114:117], v[242:245], v[180:183], v[114:117]
	v_mfma_f32_16x16x32_bf16 v[102:105], v[234:237], v[204:207], v[102:105]
	v_mfma_f32_16x16x32_bf16 v[98:101], v[242:245], v[204:207], v[98:101]
	v_mfma_f32_16x16x32_bf16 v[86:89], v[234:237], v[212:215], v[86:89]
	v_mfma_f32_16x16x32_bf16 v[82:85], v[242:245], v[212:215], v[82:85]
	v_mfma_f32_16x16x32_bf16 v[70:73], v[234:237], v[226:229], v[70:73]
	v_mfma_f32_16x16x32_bf16 v[66:69], v[242:245], v[226:229], v[66:69]
	s_setprio 0
	s_mov_b32 m0, s84
	s_barrier
	ds_read_b128 v[176:179], v150 offset:49152
	ds_read_b128 v[180:183], v150 offset:50176
	ds_read_b128 v[184:187], v150 offset:51200
	ds_read_b128 v[204:207], v150 offset:52224
	ds_read_b128 v[208:211], v150 offset:53248
	ds_read_b128 v[212:215], v150 offset:54272
	ds_read_b128 v[216:219], v150 offset:55296
	ds_read_b128 v[226:229], v150 offset:56320
	global_load_lds_dwordx4 v134, vcc
	s_mov_b32 m0, s85
	s_nop 0
	global_load_lds_dwordx4 v132, vcc
	s_barrier
	s_waitcnt lgkmcnt(0)
	s_setprio 1
	s_waitcnt lgkmcnt(0)
	v_mfma_f32_16x16x32_bf16 v[62:65], v[140:143], v[176:179], v[62:65]
	v_mfma_f32_16x16x32_bf16 v[58:61], v[168:171], v[176:179], v[58:61]
	v_mfma_f32_16x16x32_bf16 v[46:49], v[140:143], v[184:187], v[46:49]
	v_mfma_f32_16x16x32_bf16 v[42:45], v[168:171], v[184:187], v[42:45]
	v_mfma_f32_16x16x32_bf16 v[30:33], v[140:143], v[208:211], v[30:33]
	v_mfma_f32_16x16x32_bf16 v[26:29], v[168:171], v[208:211], v[26:29]
	v_mfma_f32_16x16x32_bf16 v[14:17], v[140:143], v[216:219], v[14:17]
	v_mfma_f32_16x16x32_bf16 v[10:13], v[168:171], v[216:219], v[10:13]
	v_mfma_f32_16x16x32_bf16 v[62:65], v[152:155], v[180:183], v[62:65]
	v_mfma_f32_16x16x32_bf16 v[58:61], v[172:175], v[180:183], v[58:61]
	v_mfma_f32_16x16x32_bf16 v[46:49], v[152:155], v[204:207], v[46:49]
	v_mfma_f32_16x16x32_bf16 v[42:45], v[172:175], v[204:207], v[42:45]
	v_mfma_f32_16x16x32_bf16 v[30:33], v[152:155], v[212:215], v[30:33]
	v_mfma_f32_16x16x32_bf16 v[26:29], v[172:175], v[212:215], v[26:29]
	v_mfma_f32_16x16x32_bf16 v[14:17], v[152:155], v[226:229], v[14:17]
	v_mfma_f32_16x16x32_bf16 v[10:13], v[172:175], v[226:229], v[10:13]
	s_setprio 0
	s_barrier
	s_add_u32 s6, s6, 0x40080
	s_addc_u32 s7, s7, 0
	s_add_i32 s42, s42, s48
	s_mov_b32 m0, s42
	s_nop 0
	global_load_lds_dwordx4 v0, s[6:7]
	s_add_i32 m0, s42, 0x2000
	s_nop 0
	global_load_lds_dwordx4 v130, s[6:7]
	s_waitcnt vmcnt(6)
	s_barrier
	s_setprio 1
	v_mfma_f32_16x16x32_bf16 v[54:57], v[230:233], v[176:179], v[54:57]
	v_mfma_f32_16x16x32_bf16 v[50:53], v[238:241], v[176:179], v[50:53]
	v_mfma_f32_16x16x32_bf16 v[38:41], v[230:233], v[184:187], v[38:41]
	v_mfma_f32_16x16x32_bf16 v[34:37], v[238:241], v[184:187], v[34:37]
	v_mfma_f32_16x16x32_bf16 v[22:25], v[230:233], v[208:211], v[22:25]
	v_mfma_f32_16x16x32_bf16 v[18:21], v[238:241], v[208:211], v[18:21]
	v_mfma_f32_16x16x32_bf16 v[6:9], v[230:233], v[216:219], v[6:9]
	v_mfma_f32_16x16x32_bf16 v[2:5], v[238:241], v[216:219], v[2:5]
	v_mfma_f32_16x16x32_bf16 v[54:57], v[234:237], v[180:183], v[54:57]
	v_mfma_f32_16x16x32_bf16 v[50:53], v[242:245], v[180:183], v[50:53]
	v_mfma_f32_16x16x32_bf16 v[38:41], v[234:237], v[204:207], v[38:41]
	v_mfma_f32_16x16x32_bf16 v[34:37], v[242:245], v[204:207], v[34:37]
	v_mfma_f32_16x16x32_bf16 v[22:25], v[234:237], v[212:215], v[22:25]
	v_mfma_f32_16x16x32_bf16 v[18:21], v[242:245], v[212:215], v[18:21]
	v_mfma_f32_16x16x32_bf16 v[6:9], v[234:237], v[226:229], v[6:9]
	v_mfma_f32_16x16x32_bf16 v[2:5], v[242:245], v[226:229], v[2:5]
	s_setprio 0
	s_add_i32 s93, s93, 2
	s_add_u32 s36, s36, 0x100
	s_addc_u32 s37, s37, 0
	s_add_u32 s91, s91, 0x100
	s_addc_u32 s92, s92, 0
	s_cmp_gt_u32 s93, 13
	s_barrier
; #define PG8_STAGE(bufoff, gbase, voff) do { _Pragma("unroll") for (int _i = 0; _i < 2; ++_i) \
;         __builtin_amdgcn_global_load_lds((const unsigned*)((const char*)(gbase) + (voff)[_i]), (LAS unsigned*)(lds + (bufoff) + ldsw + _i * 8192), 16, 0, 0); } while (0)
; #define PG8_LDA(dst, b, h) do { _Pragma("unroll") for (int m = 0; m < 4; ++m) _Pragma("unroll") for (int k = 0; k < 2; ++k) dst[m][k] = *(const LAS bf16x8*)(lds + PG8_SA(b, h) + aoff + m * 2048 + k * 1024); } while (0)
; #define PG8_LDB(dst, b, h) do { _Pragma("unroll") for (int n = 0; n < 2; ++n) _Pragma("unroll") for (int k = 0; k < 2; ++k) dst[n][k] = *(const LAS bf16x8*)(lds + PG8_SB(b, h) + boff + n * 2048 + k * 1024); } while (0)
; #define PG8_MMA(ai, bj, At, Bt) do { __builtin_amdgcn_s_setprio(1); _Pragma("unroll") for (int m = 0; m < 4; ++m) _Pragma("unroll") for (int n = 0; n < 2; ++n) _Pragma("unroll") for (int k = 0; k < 2; ++k) \
;         acc[ai][bj][m][n] = __builtin_amdgcn_mfma_f32_16x16x32_bf16(Bt[n][k], At[m][k], acc[ai][bj][m][n], 0, 0, 0); __builtin_amdgcn_s_setprio(0); } while (0)
; #define PG8_WAIT_V(n) asm volatile("s_waitcnt vmcnt(" #n ")" ::: "memory")
; #define PG8_WAIT_L(n) asm volatile("s_waitcnt lgkmcnt(" #n ")" ::: "memory")
; #define PG8_BAR __builtin_amdgcn_s_barrier()
; template <class Epi>
; __device__ __forceinline__ void gemm_phase(LAS unsigned char* lds, const Gemm g, const StaticOrder& S, const Epi& E) {
;     ...
;             const bool last = (t == nt - 2);
;             const char* a1 = cA + (size_t)(t + 1) * kstep;
;             const char* a2 = last ? nA : cA + (size_t)(t + 2) * kstep; const char* b2 = last ? nB : cB + (size_t)(t + 2) * kstep;
;             const char* a3 = a2 + kstep; const char* b3 = b2 + kstep;
;             PG8_LDB(B0, 0, 0); PG8_SCHED; PG8_LDA(At, 0, 0); PG8_STAGE(PG8_SA(1, 1), a1 + hstep, voffA);
;             PG8_WAIT_L(8); PG8_BAR; PG8_WAIT_L(0); PG8_MMA(0, 0, At, B0); PG8_BAR; PG8_SCHED;
;             PG8_LDB(B1, 0, 1); PG8_STAGE(PG8_SB(0, 0), b2, voffB);
;             PG8_BAR; PG8_WAIT_L(0); PG8_MMA(0, 1, At, B1); PG8_BAR;
;             PG8_LDA(At, 0, 1); PG8_STAGE(PG8_SA(0, 0), a2, voffA);
;             PG8_BAR; PG8_WAIT_L(0); PG8_MMA(1, 0, At, B0); PG8_BAR; PG8_SCHED;
;             PG8_STAGE(PG8_SB(0, 1), b2 + hstep, voffB);
;             PG8_WAIT_V(6); PG8_BAR; PG8_MMA(1, 1, At, B1); PG8_BAR;
	s_add_u32 s6, s36, 0xfffc0080
	s_addc_u32 s7, s37, -1
	s_add_i32 s58, 0, 0x10000
	v_add_u32_e32 v144, s58, v147
	ds_read_b128 v[140:143], v144
	ds_read_b128 v[152:155], v144 offset:1024
	ds_read_b128 v[168:171], v144 offset:2048
	ds_read_b128 v[172:175], v144 offset:3072
	s_cmp_eq_u32 s93, 12
	s_cselect_b32 s43, s11, s7
	s_cselect_b32 s42, s71, s6
	s_cselect_b32 s7, s9, s92
	s_cselect_b32 s6, s90, s91
	s_add_i32 m0, s49, 0xc000
	ds_read_b128 v[176:179], v150
	ds_read_b128 v[180:183], v150 offset:1024
	ds_read_b128 v[184:187], v150 offset:2048
	ds_read_b128 v[204:207], v150 offset:3072
	ds_read_b128 v[208:211], v150 offset:4096
	ds_read_b128 v[212:215], v150 offset:5120
	ds_read_b128 v[216:219], v150 offset:6144
	ds_read_b128 v[226:229], v150 offset:7168
	global_load_lds_dwordx4 v136, s[36:37]
	s_add_i32 m0, s49, 0xe000
	s_nop 0
	global_load_lds_dwordx4 v138, s[36:37]
	s_waitcnt lgkmcnt(8)
	s_barrier
	s_waitcnt lgkmcnt(0)
	s_setprio 1
	s_waitcnt lgkmcnt(0)
	v_mfma_f32_16x16x32_bf16 v[126:129], v[140:143], v[176:179], v[126:129]
	v_mfma_f32_16x16x32_bf16 v[122:125], v[168:171], v[176:179], v[122:125]
	v_mfma_f32_16x16x32_bf16 v[110:113], v[140:143], v[184:187], v[110:113]
	v_mfma_f32_16x16x32_bf16 v[106:109], v[168:171], v[184:187], v[106:109]
	v_mfma_f32_16x16x32_bf16 v[94:97], v[140:143], v[208:211], v[94:97]
	v_mfma_f32_16x16x32_bf16 v[90:93], v[168:171], v[208:211], v[90:93]
	v_mfma_f32_16x16x32_bf16 v[78:81], v[140:143], v[216:219], v[78:81]
	v_mfma_f32_16x16x32_bf16 v[74:77], v[168:171], v[216:219], v[74:77]
	v_mfma_f32_16x16x32_bf16 v[126:129], v[152:155], v[180:183], v[126:129]
	v_mfma_f32_16x16x32_bf16 v[122:125], v[172:175], v[180:183], v[122:125]
	v_mfma_f32_16x16x32_bf16 v[110:113], v[152:155], v[204:207], v[110:113]
	v_mfma_f32_16x16x32_bf16 v[106:109], v[172:175], v[204:207], v[106:109]
	v_mfma_f32_16x16x32_bf16 v[94:97], v[152:155], v[212:215], v[94:97]
	v_mfma_f32_16x16x32_bf16 v[90:93], v[172:175], v[212:215], v[90:93]
	v_mfma_f32_16x16x32_bf16 v[78:81], v[152:155], v[226:229], v[78:81]
	v_mfma_f32_16x16x32_bf16 v[74:77], v[172:175], v[226:229], v[74:77]
	s_setprio 0
	s_barrier
	s_add_i32 s70, 0, 0x14000
	v_add_u32_e32 v144, s70, v147
	s_add_i32 s58, s58, s48
	ds_read_b128 v[230:233], v144
	ds_read_b128 v[234:237], v144 offset:1024
	ds_read_b128 v[238:241], v144 offset:2048
	ds_read_b128 v[242:245], v144 offset:3072
	s_mov_b32 m0, s58
	s_nop 0
	global_load_lds_dwordx4 v0, s[6:7]
	s_add_i32 m0, s58, 0x2000
	s_nop 0
	global_load_lds_dwordx4 v130, s[6:7]
	s_barrier
	s_waitcnt lgkmcnt(0)
	s_setprio 1
	s_waitcnt lgkmcnt(0)
	v_mfma_f32_16x16x32_bf16 v[118:121], v[230:233], v[176:179], v[118:121]
	v_mfma_f32_16x16x32_bf16 v[114:117], v[238:241], v[176:179], v[114:117]
	v_mfma_f32_16x16x32_bf16 v[102:105], v[230:233], v[184:187], v[102:105]
	v_mfma_f32_16x16x32_bf16 v[98:101], v[238:241], v[184:187], v[98:101]
	v_mfma_f32_16x16x32_bf16 v[86:89], v[230:233], v[208:211], v[86:89]
	v_mfma_f32_16x16x32_bf16 v[82:85], v[238:241], v[208:211], v[82:85]
	v_mfma_f32_16x16x32_bf16 v[70:73], v[230:233], v[216:219], v[70:73]
	v_mfma_f32_16x16x32_bf16 v[66:69], v[238:241], v[216:219], v[66:69]
	v_mfma_f32_16x16x32_bf16 v[118:121], v[234:237], v[180:183], v[118:121]
	v_mfma_f32_16x16x32_bf16 v[114:117], v[242:245], v[180:183], v[114:117]
	v_mfma_f32_16x16x32_bf16 v[102:105], v[234:237], v[204:207], v[102:105]
	v_mfma_f32_16x16x32_bf16 v[98:101], v[242:245], v[204:207], v[98:101]
	v_mfma_f32_16x16x32_bf16 v[86:89], v[234:237], v[212:215], v[86:89]
	v_mfma_f32_16x16x32_bf16 v[82:85], v[242:245], v[212:215], v[82:85]
	v_mfma_f32_16x16x32_bf16 v[70:73], v[234:237], v[226:229], v[70:73]
	v_mfma_f32_16x16x32_bf16 v[66:69], v[242:245], v[226:229], v[66:69]
	s_setprio 0
	s_mov_b32 m0, s49
	s_add_u32 vcc_lo, s42, 0x80
	s_addc_u32 vcc_hi, s43, 0
	s_barrier
	ds_read_b128 v[176:179], v150 offset:16384
	ds_read_b128 v[180:183], v150 offset:17408
	ds_read_b128 v[184:187], v150 offset:18432
	ds_read_b128 v[204:207], v150 offset:19456
	ds_read_b128 v[208:211], v150 offset:20480
	ds_read_b128 v[212:215], v150 offset:21504
	ds_read_b128 v[216:219], v150 offset:22528
	ds_read_b128 v[226:229], v150 offset:23552
	global_load_lds_dwordx4 v134, s[42:43]
	s_mov_b32 m0, s54
	s_nop 0
	global_load_lds_dwordx4 v132, s[42:43]
	s_barrier
	s_waitcnt lgkmcnt(0)
	s_setprio 1
	s_waitcnt lgkmcnt(0)
	v_mfma_f32_16x16x32_bf16 v[62:65], v[140:143], v[176:179], v[62:65]
	v_mfma_f32_16x16x32_bf16 v[58:61], v[168:171], v[176:179], v[58:61]
	v_mfma_f32_16x16x32_bf16 v[46:49], v[140:143], v[184:187], v[46:49]
	v_mfma_f32_16x16x32_bf16 v[42:45], v[168:171], v[184:187], v[42:45]
	v_mfma_f32_16x16x32_bf16 v[30:33], v[140:143], v[208:211], v[30:33]
	v_mfma_f32_16x16x32_bf16 v[26:29], v[168:171], v[208:211], v[26:29]
	v_mfma_f32_16x16x32_bf16 v[14:17], v[140:143], v[216:219], v[14:17]
	v_mfma_f32_16x16x32_bf16 v[10:13], v[168:171], v[216:219], v[10:13]
	v_mfma_f32_16x16x32_bf16 v[62:65], v[152:155], v[180:183], v[62:65]
	v_mfma_f32_16x16x32_bf16 v[58:61], v[172:175], v[180:183], v[58:61]
	v_mfma_f32_16x16x32_bf16 v[46:49], v[152:155], v[204:207], v[46:49]
	v_mfma_f32_16x16x32_bf16 v[42:45], v[172:175], v[204:207], v[42:45]
	v_mfma_f32_16x16x32_bf16 v[30:33], v[152:155], v[212:215], v[30:33]
	v_mfma_f32_16x16x32_bf16 v[26:29], v[172:175], v[212:215], v[26:29]
	v_mfma_f32_16x16x32_bf16 v[14:17], v[152:155], v[226:229], v[14:17]
	v_mfma_f32_16x16x32_bf16 v[10:13], v[172:175], v[226:229], v[10:13]
	s_setprio 0
	s_barrier
	s_add_u32 s60, s6, 0x40000
	s_addc_u32 s61, s7, 0
	s_add_i32 s58, s70, s48
	s_mov_b32 m0, s58
	s_nop 0
	global_load_lds_dwordx4 v0, s[60:61]
	s_add_i32 m0, s58, 0x2000
	s_nop 0
	global_load_lds_dwordx4 v130, s[60:61]
	s_waitcnt vmcnt(6)
	s_barrier
	s_setprio 1
	v_mfma_f32_16x16x32_bf16 v[54:57], v[230:233], v[176:179], v[54:57]
	v_mfma_f32_16x16x32_bf16 v[50:53], v[238:241], v[176:179], v[50:53]
	s_cmp_eq_u32 s89, 0
	s_cbranch_scc1 .LdsE_skip_6
	global_store_dwordx4 v250, v[222:225], s[4:5]
; #define PG8_STAGE(bufoff, gbase, voff) do { _Pragma("unroll") for (int _i = 0; _i < 2; ++_i) \
;         __builtin_amdgcn_global_load_lds((const unsigned*)((const char*)(gbase) + (voff)[_i]), (LAS unsigned*)(lds + (bufoff) + ldsw + _i * 8192), 16, 0, 0); } while (0)
; #define PG8_LDA(dst, b, h) do { _Pragma("unroll") for (int m = 0; m < 4; ++m) _Pragma("unroll") for (int k = 0; k < 2; ++k) dst[m][k] = *(const LAS bf16x8*)(lds + PG8_SA(b, h) + aoff + m * 2048 + k * 1024); } while (0)
; #define PG8_LDB(dst, b, h) do { _Pragma("unroll") for (int n = 0; n < 2; ++n) _Pragma("unroll") for (int k = 0; k < 2; ++k) dst[n][k] = *(const LAS bf16x8*)(lds + PG8_SB(b, h) + boff + n * 2048 + k * 1024); } while (0)
; #define PG8_WAIT_V(n) asm volatile("s_waitcnt vmcnt(" #n ")" ::: "memory")
; #define PG8_WAIT_L(n) asm volatile("s_waitcnt lgkmcnt(" #n ")" ::: "memory")
; #define PG8_BAR __builtin_amdgcn_s_barrier()
; #define PG8_SCHED __builtin_amdgcn_sched_barrier(0)
; template <class Epi>
; __device__ __forceinline__ void gemm_phase(LAS unsigned char* lds, const Gemm g, const StaticOrder& S, const Epi& E) {
;     ...
;             PG8_LDB(B0, 0, 0); PG8_SCHED; PG8_LDA(At, 0, 0); PG8_STAGE(PG8_SA(1, 1), a1 + hstep, voffA);
;             PG8_WAIT_L(8); PG8_BAR; PG8_WAIT_L(0); PG8_MMA(0, 0, At, B0); PG8_BAR; PG8_SCHED;
;             PG8_LDB(B1, 0, 1); PG8_STAGE(PG8_SB(0, 0), b2, voffB);
;             PG8_BAR; PG8_WAIT_L(0); PG8_MMA(0, 1, At, B1); PG8_BAR;
;             PG8_LDA(At, 0, 1); PG8_STAGE(PG8_SA(0, 0), a2, voffA);
;             PG8_BAR; PG8_WAIT_L(0); PG8_MMA(1, 0, At, B0); PG8_BAR; PG8_SCHED;
;             PG8_STAGE(PG8_SB(0, 1), b2 + hstep, voffB);
;             PG8_WAIT_V(6); PG8_BAR; PG8_MMA(1, 1, At, B1); PG8_BAR;
;             PG8_LDB(B0, 1, 0); PG8_SCHED; PG8_LDA(At, 1, 0); PG8_STAGE(PG8_SA(0, 1), a2 + hstep, voffA);
;             PG8_WAIT_L(8); PG8_BAR; PG8_WAIT_L(0); PG8_MMA(0, 0, At, B0); PG8_BAR; PG8_SCHED;
;             PG8_LDB(B1, 1, 1); PG8_STAGE(PG8_SB(1, 0), b3, voffB);
;             PG8_BAR; PG8_WAIT_L(0); PG8_MMA(0, 1, At, B1); PG8_BAR;
;             PG8_LDA(At, 1, 1); PG8_STAGE(PG8_SA(1, 0), a3, voffA);
;             PG8_BAR; PG8_WAIT_L(0); PG8_MMA(1, 0, At, B0); PG8_BAR; PG8_SCHED;
;             PG8_STAGE(PG8_SB(1, 1), b3 + hstep, voffB);
;             PG8_WAIT_V(6); PG8_BAR; PG8_MMA(1, 1, At, B1); PG8_BAR;
.LdsE_skip_6:
	v_mfma_f32_16x16x32_bf16 v[38:41], v[230:233], v[184:187], v[38:41]
	v_mfma_f32_16x16x32_bf16 v[34:37], v[238:241], v[184:187], v[34:37]
	v_mfma_f32_16x16x32_bf16 v[22:25], v[230:233], v[208:211], v[22:25]
	v_mfma_f32_16x16x32_bf16 v[18:21], v[238:241], v[208:211], v[18:21]
	v_mfma_f32_16x16x32_bf16 v[6:9], v[230:233], v[216:219], v[6:9]
	v_mfma_f32_16x16x32_bf16 v[2:5], v[238:241], v[216:219], v[2:5]
	v_mfma_f32_16x16x32_bf16 v[54:57], v[234:237], v[180:183], v[54:57]
	v_mfma_f32_16x16x32_bf16 v[50:53], v[242:245], v[180:183], v[50:53]
	v_mfma_f32_16x16x32_bf16 v[38:41], v[234:237], v[204:207], v[38:41]
	v_mfma_f32_16x16x32_bf16 v[34:37], v[242:245], v[204:207], v[34:37]
	v_mfma_f32_16x16x32_bf16 v[22:25], v[234:237], v[212:215], v[22:25]
	v_mfma_f32_16x16x32_bf16 v[18:21], v[242:245], v[212:215], v[18:21]
	v_mfma_f32_16x16x32_bf16 v[6:9], v[234:237], v[226:229], v[6:9]
	v_mfma_f32_16x16x32_bf16 v[2:5], v[242:245], v[226:229], v[2:5]
	s_setprio 0
	s_add_i32 s58, 0, 0x18000
	v_add_u32_e32 v151, s58, v147
	s_barrier
	ds_read_b128 v[140:143], v151
	ds_read_b128 v[152:155], v151 offset:1024
	ds_read_b128 v[168:171], v151 offset:2048
	ds_read_b128 v[172:175], v151 offset:3072
	s_add_u32 s42, s42, 0x40000
	s_addc_u32 s43, s43, 0
	s_mov_b32 m0, s55
	ds_read_b128 v[176:179], v150 offset:32768
	ds_read_b128 v[180:183], v150 offset:33792
	ds_read_b128 v[184:187], v150 offset:34816
	ds_read_b128 v[204:207], v150 offset:35840
	ds_read_b128 v[208:211], v150 offset:36864
	ds_read_b128 v[212:215], v150 offset:37888
	ds_read_b128 v[216:219], v150 offset:38912
	ds_read_b128 v[226:229], v150 offset:39936
	global_load_lds_dwordx4 v134, s[42:43]
	s_mov_b32 m0, s83
	s_nop 0
	global_load_lds_dwordx4 v132, s[42:43]
	s_waitcnt lgkmcnt(8)
	s_barrier
	s_waitcnt lgkmcnt(0)
	s_setprio 1
	s_waitcnt lgkmcnt(0)
	v_mfma_f32_16x16x32_bf16 v[126:129], v[140:143], v[176:179], v[126:129]
	v_mfma_f32_16x16x32_bf16 v[122:125], v[168:171], v[176:179], v[122:125]
	v_mfma_f32_16x16x32_bf16 v[110:113], v[140:143], v[184:187], v[110:113]
	v_mfma_f32_16x16x32_bf16 v[106:109], v[168:171], v[184:187], v[106:109]
	v_mfma_f32_16x16x32_bf16 v[94:97], v[140:143], v[208:211], v[94:97]
	v_mfma_f32_16x16x32_bf16 v[90:93], v[168:171], v[208:211], v[90:93]
	v_mfma_f32_16x16x32_bf16 v[78:81], v[140:143], v[216:219], v[78:81]
	v_mfma_f32_16x16x32_bf16 v[74:77], v[168:171], v[216:219], v[74:77]
	v_mfma_f32_16x16x32_bf16 v[126:129], v[152:155], v[180:183], v[126:129]
	v_mfma_f32_16x16x32_bf16 v[122:125], v[172:175], v[180:183], v[122:125]
	v_mfma_f32_16x16x32_bf16 v[110:113], v[152:155], v[204:207], v[110:113]
	v_mfma_f32_16x16x32_bf16 v[106:109], v[172:175], v[204:207], v[106:109]
	v_mfma_f32_16x16x32_bf16 v[94:97], v[152:155], v[212:215], v[94:97]
	v_mfma_f32_16x16x32_bf16 v[90:93], v[172:175], v[212:215], v[90:93]
	v_mfma_f32_16x16x32_bf16 v[78:81], v[152:155], v[226:229], v[78:81]
	v_mfma_f32_16x16x32_bf16 v[74:77], v[172:175], v[226:229], v[74:77]
	s_setprio 0
	s_barrier
	s_add_i32 s42, 0, 0x1c000
	s_add_i32 s43, s58, s48
	v_add_u32_e32 v151, s42, v147
	s_add_u32 s60, s6, 0x80
	s_addc_u32 s61, s7, 0
	s_mov_b32 m0, s43
	ds_read_b128 v[230:233], v151
	ds_read_b128 v[234:237], v151 offset:1024
	ds_read_b128 v[238:241], v151 offset:2048
	ds_read_b128 v[242:245], v151 offset:3072
	global_load_lds_dwordx4 v0, s[60:61]
	s_add_i32 m0, s43, 0x2000
	s_nop 0
	global_load_lds_dwordx4 v130, s[60:61]
	s_barrier
	s_waitcnt lgkmcnt(0)
	s_setprio 1
	s_waitcnt lgkmcnt(0)
	v_mfma_f32_16x16x32_bf16 v[118:121], v[230:233], v[176:179], v[118:121]
	v_mfma_f32_16x16x32_bf16 v[114:117], v[238:241], v[176:179], v[114:117]
	v_mfma_f32_16x16x32_bf16 v[102:105], v[230:233], v[184:187], v[102:105]
	v_mfma_f32_16x16x32_bf16 v[98:101], v[238:241], v[184:187], v[98:101]
	v_mfma_f32_16x16x32_bf16 v[86:89], v[230:233], v[208:211], v[86:89]
	v_mfma_f32_16x16x32_bf16 v[82:85], v[238:241], v[208:211], v[82:85]
	v_mfma_f32_16x16x32_bf16 v[70:73], v[230:233], v[216:219], v[70:73]
	v_mfma_f32_16x16x32_bf16 v[66:69], v[238:241], v[216:219], v[66:69]
	v_mfma_f32_16x16x32_bf16 v[118:121], v[234:237], v[180:183], v[118:121]
	v_mfma_f32_16x16x32_bf16 v[114:117], v[242:245], v[180:183], v[114:117]
	v_mfma_f32_16x16x32_bf16 v[102:105], v[234:237], v[204:207], v[102:105]
	v_mfma_f32_16x16x32_bf16 v[98:101], v[242:245], v[204:207], v[98:101]
	v_mfma_f32_16x16x32_bf16 v[86:89], v[234:237], v[212:215], v[86:89]
	v_mfma_f32_16x16x32_bf16 v[82:85], v[242:245], v[212:215], v[82:85]
	v_mfma_f32_16x16x32_bf16 v[70:73], v[234:237], v[226:229], v[70:73]
	v_mfma_f32_16x16x32_bf16 v[66:69], v[242:245], v[226:229], v[66:69]
	s_setprio 0
	s_mov_b32 m0, s84
	s_barrier
	ds_read_b128 v[176:179], v150 offset:49152
	ds_read_b128 v[180:183], v150 offset:50176
	ds_read_b128 v[184:187], v150 offset:51200
	ds_read_b128 v[204:207], v150 offset:52224
	ds_read_b128 v[208:211], v150 offset:53248
	ds_read_b128 v[212:215], v150 offset:54272
	ds_read_b128 v[216:219], v150 offset:55296
	ds_read_b128 v[226:229], v150 offset:56320
	global_load_lds_dwordx4 v134, vcc
	s_mov_b32 m0, s85
	s_nop 0
	global_load_lds_dwordx4 v132, vcc
	s_barrier
; #define PG8_STAGE(bufoff, gbase, voff) do { _Pragma("unroll") for (int _i = 0; _i < 2; ++_i) \
;         __builtin_amdgcn_global_load_lds((const unsigned*)((const char*)(gbase) + (voff)[_i]), (LAS unsigned*)(lds + (bufoff) + ldsw + _i * 8192), 16, 0, 0); } while (0)
; #define PG8_LDA(dst, b, h) do { _Pragma("unroll") for (int m = 0; m < 4; ++m) _Pragma("unroll") for (int k = 0; k < 2; ++k) dst[m][k] = *(const LAS bf16x8*)(lds + PG8_SA(b, h) + aoff + m * 2048 + k * 1024); } while (0)
; #define PG8_LDB(dst, b, h) do { _Pragma("unroll") for (int n = 0; n < 2; ++n) _Pragma("unroll") for (int k = 0; k < 2; ++k) dst[n][k] = *(const LAS bf16x8*)(lds + PG8_SB(b, h) + boff + n * 2048 + k * 1024); } while (0)
; #define PG8_WAIT_V(n) asm volatile("s_waitcnt vmcnt(" #n ")" ::: "memory")
; #define PG8_WAIT_L(n) asm volatile("s_waitcnt lgkmcnt(" #n ")" ::: "memory")
; #define PG8_BAR __builtin_amdgcn_s_barrier()
; #define PG8_SCHED __builtin_amdgcn_sched_barrier(0)
; template <class Epi>
; __device__ __forceinline__ void gemm_phase(LAS unsigned char* lds, const Gemm g, const StaticOrder& S, const Epi& E) {
;     ...
;             PG8_LDB(B0, 0, 0); PG8_SCHED; PG8_LDA(At, 0, 0); PG8_STAGE(PG8_SA(1, 1), a1 + hstep, voffA);
;             PG8_WAIT_L(8); PG8_BAR; PG8_WAIT_L(0); PG8_MMA(0, 0, At, B0); PG8_BAR; PG8_SCHED;
;             PG8_LDB(B1, 0, 1); PG8_STAGE(PG8_SB(0, 0), b2, voffB);
;             PG8_BAR; PG8_WAIT_L(0); PG8_MMA(0, 1, At, B1); PG8_BAR;
;             PG8_LDA(At, 0, 1); PG8_STAGE(PG8_SA(0, 0), a2, voffA);
;             PG8_BAR; PG8_WAIT_L(0); PG8_MMA(1, 0, At, B0); PG8_BAR; PG8_SCHED;
;             PG8_STAGE(PG8_SB(0, 1), b2 + hstep, voffB);
;             PG8_WAIT_V(6); PG8_BAR; PG8_MMA(1, 1, At, B1); PG8_BAR;
;             PG8_LDB(B0, 1, 0); PG8_SCHED; PG8_LDA(At, 1, 0); PG8_STAGE(PG8_SA(0, 1), a2 + hstep, voffA);
;             PG8_WAIT_L(8); PG8_BAR; PG8_WAIT_L(0); PG8_MMA(0, 0, At, B0); PG8_BAR; PG8_SCHED;
;             PG8_LDB(B1, 1, 1); PG8_STAGE(PG8_SB(1, 0), b3, voffB);
;             PG8_BAR; PG8_WAIT_L(0); PG8_MMA(0, 1, At, B1); PG8_BAR;
;             PG8_LDA(At, 1, 1); PG8_STAGE(PG8_SA(1, 0), a3, voffA);
;             PG8_BAR; PG8_WAIT_L(0); PG8_MMA(1, 0, At, B0); PG8_BAR; PG8_SCHED;
;             PG8_STAGE(PG8_SB(1, 1), b3 + hstep, voffB);
;             PG8_WAIT_V(6); PG8_BAR; PG8_MMA(1, 1, At, B1); PG8_BAR;
	s_waitcnt lgkmcnt(0)
	s_setprio 1
	s_waitcnt lgkmcnt(0)
	v_mfma_f32_16x16x32_bf16 v[62:65], v[140:143], v[176:179], v[62:65]
	v_mfma_f32_16x16x32_bf16 v[58:61], v[168:171], v[176:179], v[58:61]
	v_mfma_f32_16x16x32_bf16 v[46:49], v[140:143], v[184:187], v[46:49]
	v_mfma_f32_16x16x32_bf16 v[42:45], v[168:171], v[184:187], v[42:45]
	v_mfma_f32_16x16x32_bf16 v[30:33], v[140:143], v[208:211], v[30:33]
	v_mfma_f32_16x16x32_bf16 v[26:29], v[168:171], v[208:211], v[26:29]
	v_mfma_f32_16x16x32_bf16 v[14:17], v[140:143], v[216:219], v[14:17]
	v_mfma_f32_16x16x32_bf16 v[10:13], v[168:171], v[216:219], v[10:13]
	v_mfma_f32_16x16x32_bf16 v[62:65], v[152:155], v[180:183], v[62:65]
	v_mfma_f32_16x16x32_bf16 v[58:61], v[172:175], v[180:183], v[58:61]
	v_mfma_f32_16x16x32_bf16 v[46:49], v[152:155], v[204:207], v[46:49]
	v_mfma_f32_16x16x32_bf16 v[42:45], v[172:175], v[204:207], v[42:45]
	v_mfma_f32_16x16x32_bf16 v[30:33], v[152:155], v[212:215], v[30:33]
	v_mfma_f32_16x16x32_bf16 v[26:29], v[172:175], v[212:215], v[26:29]
	v_mfma_f32_16x16x32_bf16 v[14:17], v[152:155], v[226:229], v[14:17]
	v_mfma_f32_16x16x32_bf16 v[10:13], v[172:175], v[226:229], v[10:13]
	s_setprio 0
	s_barrier
	s_add_u32 s6, s6, 0x40080
	s_addc_u32 s7, s7, 0
	s_add_i32 s42, s42, s48
	s_mov_b32 m0, s42
	s_nop 0
	global_load_lds_dwordx4 v0, s[6:7]
	s_add_i32 m0, s42, 0x2000
	s_nop 0
	global_load_lds_dwordx4 v130, s[6:7]
	s_waitcnt vmcnt(6)
	s_barrier
	s_setprio 1
	v_mfma_f32_16x16x32_bf16 v[54:57], v[230:233], v[176:179], v[54:57]
	v_mfma_f32_16x16x32_bf16 v[50:53], v[238:241], v[176:179], v[50:53]
	v_mfma_f32_16x16x32_bf16 v[38:41], v[230:233], v[184:187], v[38:41]
	v_mfma_f32_16x16x32_bf16 v[34:37], v[238:241], v[184:187], v[34:37]
	v_mfma_f32_16x16x32_bf16 v[22:25], v[230:233], v[208:211], v[22:25]
	v_mfma_f32_16x16x32_bf16 v[18:21], v[238:241], v[208:211], v[18:21]
	v_mfma_f32_16x16x32_bf16 v[6:9], v[230:233], v[216:219], v[6:9]
	v_mfma_f32_16x16x32_bf16 v[2:5], v[238:241], v[216:219], v[2:5]
	v_mfma_f32_16x16x32_bf16 v[54:57], v[234:237], v[180:183], v[54:57]
	v_mfma_f32_16x16x32_bf16 v[50:53], v[242:245], v[180:183], v[50:53]
	v_mfma_f32_16x16x32_bf16 v[38:41], v[234:237], v[204:207], v[38:41]
	v_mfma_f32_16x16x32_bf16 v[34:37], v[242:245], v[204:207], v[34:37]
	v_mfma_f32_16x16x32_bf16 v[22:25], v[234:237], v[212:215], v[22:25]
	v_mfma_f32_16x16x32_bf16 v[18:21], v[242:245], v[212:215], v[18:21]
	v_mfma_f32_16x16x32_bf16 v[6:9], v[234:237], v[226:229], v[6:9]
	v_mfma_f32_16x16x32_bf16 v[2:5], v[242:245], v[226:229], v[2:5]
	s_setprio 0
	s_add_i32 s93, s93, 2
	s_add_u32 s36, s36, 0x100
	s_addc_u32 s37, s37, 0
	s_add_u32 s91, s91, 0x100
	s_addc_u32 s92, s92, 0
	s_cmp_gt_u32 s93, 13
	s_barrier
	s_add_u32 s6, s36, 0xfffc0080
	s_addc_u32 s7, s37, -1
	s_add_i32 s58, 0, 0x10000
	v_add_u32_e32 v144, s58, v147
	ds_read_b128 v[140:143], v144
	ds_read_b128 v[152:155], v144 offset:1024
	ds_read_b128 v[168:171], v144 offset:2048
	ds_read_b128 v[172:175], v144 offset:3072
	s_cmp_eq_u32 s93, 12
	s_cselect_b32 s43, s11, s7
	s_cselect_b32 s42, s71, s6
	s_cselect_b32 s7, s9, s92
	s_cselect_b32 s6, s90, s91
	s_add_i32 m0, s49, 0xc000
	ds_read_b128 v[176:179], v150
	ds_read_b128 v[180:183], v150 offset:1024
	ds_read_b128 v[184:187], v150 offset:2048
	ds_read_b128 v[204:207], v150 offset:3072
	ds_read_b128 v[208:211], v150 offset:4096
	ds_read_b128 v[212:215], v150 offset:5120
	ds_read_b128 v[216:219], v150 offset:6144
	ds_read_b128 v[226:229], v150 offset:7168
	global_load_lds_dwordx4 v136, s[36:37]
	s_add_i32 m0, s49, 0xe000
	s_nop 0
	global_load_lds_dwordx4 v138, s[36:37]
	s_waitcnt lgkmcnt(8)
	s_barrier
	s_waitcnt lgkmcnt(0)
	s_setprio 1
	s_waitcnt lgkmcnt(0)
	v_mfma_f32_16x16x32_bf16 v[126:129], v[140:143], v[176:179], v[126:129]
	v_mfma_f32_16x16x32_bf16 v[122:125], v[168:171], v[176:179], v[122:125]
	v_mfma_f32_16x16x32_bf16 v[110:113], v[140:143], v[184:187], v[110:113]
	v_mfma_f32_16x16x32_bf16 v[106:109], v[168:171], v[184:187], v[106:109]
	v_mfma_f32_16x16x32_bf16 v[94:97], v[140:143], v[208:211], v[94:97]
	v_mfma_f32_16x16x32_bf16 v[90:93], v[168:171], v[208:211], v[90:93]
	v_mfma_f32_16x16x32_bf16 v[78:81], v[140:143], v[216:219], v[78:81]
	v_mfma_f32_16x16x32_bf16 v[74:77], v[168:171], v[216:219], v[74:77]
	v_mfma_f32_16x16x32_bf16 v[126:129], v[152:155], v[180:183], v[126:129]
	v_mfma_f32_16x16x32_bf16 v[122:125], v[172:175], v[180:183], v[122:125]
	v_mfma_f32_16x16x32_bf16 v[110:113], v[152:155], v[204:207], v[110:113]
	v_mfma_f32_16x16x32_bf16 v[106:109], v[172:175], v[204:207], v[106:109]
	v_mfma_f32_16x16x32_bf16 v[94:97], v[152:155], v[212:215], v[94:97]
	v_mfma_f32_16x16x32_bf16 v[90:93], v[172:175], v[212:215], v[90:93]
	v_mfma_f32_16x16x32_bf16 v[78:81], v[152:155], v[226:229], v[78:81]
	v_mfma_f32_16x16x32_bf16 v[74:77], v[172:175], v[226:229], v[74:77]
	s_setprio 0
	s_barrier
	s_add_i32 s70, 0, 0x14000
	v_add_u32_e32 v144, s70, v147
	s_add_i32 s58, s58, s48
	ds_read_b128 v[230:233], v144
	ds_read_b128 v[234:237], v144 offset:1024
	ds_read_b128 v[238:241], v144 offset:2048
	ds_read_b128 v[242:245], v144 offset:3072
	s_mov_b32 m0, s58
	s_nop 0
	global_load_lds_dwordx4 v0, s[6:7]
	s_add_i32 m0, s58, 0x2000
	s_nop 0
	global_load_lds_dwordx4 v130, s[6:7]
	s_barrier
; #define PG8_STAGE(bufoff, gbase, voff) do { _Pragma("unroll") for (int _i = 0; _i < 2; ++_i) \
;         __builtin_amdgcn_global_load_lds((const unsigned*)((const char*)(gbase) + (voff)[_i]), (LAS unsigned*)(lds + (bufoff) + ldsw + _i * 8192), 16, 0, 0); } while (0)
; #define PG8_LDA(dst, b, h) do { _Pragma("unroll") for (int m = 0; m < 4; ++m) _Pragma("unroll") for (int k = 0; k < 2; ++k) dst[m][k] = *(const LAS bf16x8*)(lds + PG8_SA(b, h) + aoff + m * 2048 + k * 1024); } while (0)
; #define PG8_LDB(dst, b, h) do { _Pragma("unroll") for (int n = 0; n < 2; ++n) _Pragma("unroll") for (int k = 0; k < 2; ++k) dst[n][k] = *(const LAS bf16x8*)(lds + PG8_SB(b, h) + boff + n * 2048 + k * 1024); } while (0)
; #define PG8_WAIT_V(n) asm volatile("s_waitcnt vmcnt(" #n ")" ::: "memory")
; #define PG8_WAIT_L(n) asm volatile("s_waitcnt lgkmcnt(" #n ")" ::: "memory")
; #define PG8_BAR __builtin_amdgcn_s_barrier()
; #define PG8_SCHED __builtin_amdgcn_sched_barrier(0)
; template <class Epi>
; __device__ __forceinline__ void gemm_phase(LAS unsigned char* lds, const Gemm g, const StaticOrder& S, const Epi& E) {
;     ...
;             PG8_LDB(B0, 0, 0); PG8_SCHED; PG8_LDA(At, 0, 0); PG8_STAGE(PG8_SA(1, 1), a1 + hstep, voffA);
;             PG8_WAIT_L(8); PG8_BAR; PG8_WAIT_L(0); PG8_MMA(0, 0, At, B0); PG8_BAR; PG8_SCHED;
;             PG8_LDB(B1, 0, 1); PG8_STAGE(PG8_SB(0, 0), b2, voffB);
;             PG8_BAR; PG8_WAIT_L(0); PG8_MMA(0, 1, At, B1); PG8_BAR;
;             PG8_LDA(At, 0, 1); PG8_STAGE(PG8_SA(0, 0), a2, voffA);
;             PG8_BAR; PG8_WAIT_L(0); PG8_MMA(1, 0, At, B0); PG8_BAR; PG8_SCHED;
;             PG8_STAGE(PG8_SB(0, 1), b2 + hstep, voffB);
;             PG8_WAIT_V(6); PG8_BAR; PG8_MMA(1, 1, At, B1); PG8_BAR;
;             PG8_LDB(B0, 1, 0); PG8_SCHED; PG8_LDA(At, 1, 0); PG8_STAGE(PG8_SA(0, 1), a2 + hstep, voffA);
;             PG8_WAIT_L(8); PG8_BAR; PG8_WAIT_L(0); PG8_MMA(0, 0, At, B0); PG8_BAR; PG8_SCHED;
;             PG8_LDB(B1, 1, 1); PG8_STAGE(PG8_SB(1, 0), b3, voffB);
;             PG8_BAR; PG8_WAIT_L(0); PG8_MMA(0, 1, At, B1); PG8_BAR;
;             PG8_LDA(At, 1, 1); PG8_STAGE(PG8_SA(1, 0), a3, voffA);
;             PG8_BAR; PG8_WAIT_L(0); PG8_MMA(1, 0, At, B0); PG8_BAR; PG8_SCHED;
;             PG8_STAGE(PG8_SB(1, 1), b3 + hstep, voffB);
;             PG8_WAIT_V(6); PG8_BAR; PG8_MMA(1, 1, At, B1); PG8_BAR;
	s_waitcnt lgkmcnt(0)
	s_setprio 1
	s_waitcnt lgkmcnt(0)
	v_mfma_f32_16x16x32_bf16 v[118:121], v[230:233], v[176:179], v[118:121]
	v_mfma_f32_16x16x32_bf16 v[114:117], v[238:241], v[176:179], v[114:117]
	v_mfma_f32_16x16x32_bf16 v[102:105], v[230:233], v[184:187], v[102:105]
	v_mfma_f32_16x16x32_bf16 v[98:101], v[238:241], v[184:187], v[98:101]
	v_mfma_f32_16x16x32_bf16 v[86:89], v[230:233], v[208:211], v[86:89]
	v_mfma_f32_16x16x32_bf16 v[82:85], v[238:241], v[208:211], v[82:85]
	v_mfma_f32_16x16x32_bf16 v[70:73], v[230:233], v[216:219], v[70:73]
	v_mfma_f32_16x16x32_bf16 v[66:69], v[238:241], v[216:219], v[66:69]
	v_mfma_f32_16x16x32_bf16 v[118:121], v[234:237], v[180:183], v[118:121]
	v_mfma_f32_16x16x32_bf16 v[114:117], v[242:245], v[180:183], v[114:117]
	v_mfma_f32_16x16x32_bf16 v[102:105], v[234:237], v[204:207], v[102:105]
	v_mfma_f32_16x16x32_bf16 v[98:101], v[242:245], v[204:207], v[98:101]
	v_mfma_f32_16x16x32_bf16 v[86:89], v[234:237], v[212:215], v[86:89]
	v_mfma_f32_16x16x32_bf16 v[82:85], v[242:245], v[212:215], v[82:85]
	v_mfma_f32_16x16x32_bf16 v[70:73], v[234:237], v[226:229], v[70:73]
	v_mfma_f32_16x16x32_bf16 v[66:69], v[242:245], v[226:229], v[66:69]
	s_setprio 0
	s_mov_b32 m0, s49
	s_add_u32 vcc_lo, s42, 0x80
	s_addc_u32 vcc_hi, s43, 0
	s_barrier
	ds_read_b128 v[176:179], v150 offset:16384
	ds_read_b128 v[180:183], v150 offset:17408
	ds_read_b128 v[184:187], v150 offset:18432
	ds_read_b128 v[204:207], v150 offset:19456
	ds_read_b128 v[208:211], v150 offset:20480
	ds_read_b128 v[212:215], v150 offset:21504
	ds_read_b128 v[216:219], v150 offset:22528
	ds_read_b128 v[226:229], v150 offset:23552
	global_load_lds_dwordx4 v134, s[42:43]
	s_mov_b32 m0, s54
	s_nop 0
	global_load_lds_dwordx4 v132, s[42:43]
	s_barrier
	s_waitcnt lgkmcnt(0)
	s_setprio 1
	s_waitcnt lgkmcnt(0)
	v_mfma_f32_16x16x32_bf16 v[62:65], v[140:143], v[176:179], v[62:65]
	v_mfma_f32_16x16x32_bf16 v[58:61], v[168:171], v[176:179], v[58:61]
	v_mfma_f32_16x16x32_bf16 v[46:49], v[140:143], v[184:187], v[46:49]
	v_mfma_f32_16x16x32_bf16 v[42:45], v[168:171], v[184:187], v[42:45]
	v_mfma_f32_16x16x32_bf16 v[30:33], v[140:143], v[208:211], v[30:33]
	v_mfma_f32_16x16x32_bf16 v[26:29], v[168:171], v[208:211], v[26:29]
	v_mfma_f32_16x16x32_bf16 v[14:17], v[140:143], v[216:219], v[14:17]
	v_mfma_f32_16x16x32_bf16 v[10:13], v[168:171], v[216:219], v[10:13]
	v_mfma_f32_16x16x32_bf16 v[62:65], v[152:155], v[180:183], v[62:65]
	v_mfma_f32_16x16x32_bf16 v[58:61], v[172:175], v[180:183], v[58:61]
	v_mfma_f32_16x16x32_bf16 v[46:49], v[152:155], v[204:207], v[46:49]
	v_mfma_f32_16x16x32_bf16 v[42:45], v[172:175], v[204:207], v[42:45]
	v_mfma_f32_16x16x32_bf16 v[30:33], v[152:155], v[212:215], v[30:33]
	v_mfma_f32_16x16x32_bf16 v[26:29], v[172:175], v[212:215], v[26:29]
	v_mfma_f32_16x16x32_bf16 v[14:17], v[152:155], v[226:229], v[14:17]
	v_mfma_f32_16x16x32_bf16 v[10:13], v[172:175], v[226:229], v[10:13]
	s_setprio 0
	s_barrier
	s_add_u32 s60, s6, 0x40000
	s_addc_u32 s61, s7, 0
	s_add_i32 s58, s70, s48
	s_mov_b32 m0, s58
	s_nop 0
	global_load_lds_dwordx4 v0, s[60:61]
	s_add_i32 m0, s58, 0x2000
	s_nop 0
	global_load_lds_dwordx4 v130, s[60:61]
	s_waitcnt vmcnt(6)
	s_barrier
	s_setprio 1
	v_mfma_f32_16x16x32_bf16 v[54:57], v[230:233], v[176:179], v[54:57]
	v_mfma_f32_16x16x32_bf16 v[50:53], v[238:241], v[176:179], v[50:53]
	s_cmp_eq_u32 s89, 0
	s_cbranch_scc1 .LdsE_skip_7
	global_store_dwordx4 v250, v[246:249], s[4:5] offset:256
.LdsE_skip_7:
	v_mfma_f32_16x16x32_bf16 v[38:41], v[230:233], v[184:187], v[38:41]
	v_mfma_f32_16x16x32_bf16 v[34:37], v[238:241], v[184:187], v[34:37]
	v_mfma_f32_16x16x32_bf16 v[22:25], v[230:233], v[208:211], v[22:25]
	v_mfma_f32_16x16x32_bf16 v[18:21], v[238:241], v[208:211], v[18:21]
	v_mfma_f32_16x16x32_bf16 v[6:9], v[230:233], v[216:219], v[6:9]
	v_mfma_f32_16x16x32_bf16 v[2:5], v[238:241], v[216:219], v[2:5]
	v_mfma_f32_16x16x32_bf16 v[54:57], v[234:237], v[180:183], v[54:57]
	v_mfma_f32_16x16x32_bf16 v[50:53], v[242:245], v[180:183], v[50:53]
	v_mfma_f32_16x16x32_bf16 v[38:41], v[234:237], v[204:207], v[38:41]
	v_mfma_f32_16x16x32_bf16 v[34:37], v[242:245], v[204:207], v[34:37]
	v_mfma_f32_16x16x32_bf16 v[22:25], v[234:237], v[212:215], v[22:25]
	v_mfma_f32_16x16x32_bf16 v[18:21], v[242:245], v[212:215], v[18:21]
	v_mfma_f32_16x16x32_bf16 v[6:9], v[234:237], v[226:229], v[6:9]
	v_mfma_f32_16x16x32_bf16 v[2:5], v[242:245], v[226:229], v[2:5]
	s_setprio 0
	s_add_i32 s58, 0, 0x18000
	v_add_u32_e32 v151, s58, v147
	s_barrier
	ds_read_b128 v[140:143], v151
	ds_read_b128 v[152:155], v151 offset:1024
	ds_read_b128 v[168:171], v151 offset:2048
	ds_read_b128 v[172:175], v151 offset:3072
	s_add_u32 s42, s42, 0x40000
	s_addc_u32 s43, s43, 0
	s_mov_b32 m0, s55
	ds_read_b128 v[176:179], v150 offset:32768
	ds_read_b128 v[180:183], v150 offset:33792
	ds_read_b128 v[184:187], v150 offset:34816
	ds_read_b128 v[204:207], v150 offset:35840
	ds_read_b128 v[208:211], v150 offset:36864
	ds_read_b128 v[212:215], v150 offset:37888
	ds_read_b128 v[216:219], v150 offset:38912
	ds_read_b128 v[226:229], v150 offset:39936
	global_load_lds_dwordx4 v134, s[42:43]
	s_mov_b32 m0, s83
	s_nop 0
	global_load_lds_dwordx4 v132, s[42:43]
	s_waitcnt lgkmcnt(8)
	s_barrier
; #define PG8_STAGE(bufoff, gbase, voff) do { _Pragma("unroll") for (int _i = 0; _i < 2; ++_i) \
;         __builtin_amdgcn_global_load_lds((const unsigned*)((const char*)(gbase) + (voff)[_i]), (LAS unsigned*)(lds + (bufoff) + ldsw + _i * 8192), 16, 0, 0); } while (0)
; #define PG8_LDA(dst, b, h) do { _Pragma("unroll") for (int m = 0; m < 4; ++m) _Pragma("unroll") for (int k = 0; k < 2; ++k) dst[m][k] = *(const LAS bf16x8*)(lds + PG8_SA(b, h) + aoff + m * 2048 + k * 1024); } while (0)
; #define PG8_LDB(dst, b, h) do { _Pragma("unroll") for (int n = 0; n < 2; ++n) _Pragma("unroll") for (int k = 0; k < 2; ++k) dst[n][k] = *(const LAS bf16x8*)(lds + PG8_SB(b, h) + boff + n * 2048 + k * 1024); } while (0)
; #define PG8_WAIT_V(n) asm volatile("s_waitcnt vmcnt(" #n ")" ::: "memory")
; #define PG8_WAIT_L(n) asm volatile("s_waitcnt lgkmcnt(" #n ")" ::: "memory")
; #define PG8_BAR __builtin_amdgcn_s_barrier()
; #define PG8_SCHED __builtin_amdgcn_sched_barrier(0)
; template <class Epi>
; __device__ __forceinline__ void gemm_phase(LAS unsigned char* lds, const Gemm g, const StaticOrder& S, const Epi& E) {
;     ...
;             PG8_LDB(B0, 0, 0); PG8_SCHED; PG8_LDA(At, 0, 0); PG8_STAGE(PG8_SA(1, 1), a1 + hstep, voffA);
;             PG8_WAIT_L(8); PG8_BAR; PG8_WAIT_L(0); PG8_MMA(0, 0, At, B0); PG8_BAR; PG8_SCHED;
;             PG8_LDB(B1, 0, 1); PG8_STAGE(PG8_SB(0, 0), b2, voffB);
;             PG8_BAR; PG8_WAIT_L(0); PG8_MMA(0, 1, At, B1); PG8_BAR;
;             PG8_LDA(At, 0, 1); PG8_STAGE(PG8_SA(0, 0), a2, voffA);
;             PG8_BAR; PG8_WAIT_L(0); PG8_MMA(1, 0, At, B0); PG8_BAR; PG8_SCHED;
;             PG8_STAGE(PG8_SB(0, 1), b2 + hstep, voffB);
;             PG8_WAIT_V(6); PG8_BAR; PG8_MMA(1, 1, At, B1); PG8_BAR;
;             PG8_LDB(B0, 1, 0); PG8_SCHED; PG8_LDA(At, 1, 0); PG8_STAGE(PG8_SA(0, 1), a2 + hstep, voffA);
;             PG8_WAIT_L(8); PG8_BAR; PG8_WAIT_L(0); PG8_MMA(0, 0, At, B0); PG8_BAR; PG8_SCHED;
;             PG8_LDB(B1, 1, 1); PG8_STAGE(PG8_SB(1, 0), b3, voffB);
;             PG8_BAR; PG8_WAIT_L(0); PG8_MMA(0, 1, At, B1); PG8_BAR;
;             PG8_LDA(At, 1, 1); PG8_STAGE(PG8_SA(1, 0), a3, voffA);
;             PG8_BAR; PG8_WAIT_L(0); PG8_MMA(1, 0, At, B0); PG8_BAR; PG8_SCHED;
;             PG8_STAGE(PG8_SB(1, 1), b3 + hstep, voffB);
;             PG8_WAIT_V(6); PG8_BAR; PG8_MMA(1, 1, At, B1); PG8_BAR;
	s_waitcnt lgkmcnt(0)
	s_setprio 1
	s_waitcnt lgkmcnt(0)
	v_mfma_f32_16x16x32_bf16 v[126:129], v[140:143], v[176:179], v[126:129]
	v_mfma_f32_16x16x32_bf16 v[122:125], v[168:171], v[176:179], v[122:125]
	v_mfma_f32_16x16x32_bf16 v[110:113], v[140:143], v[184:187], v[110:113]
	v_mfma_f32_16x16x32_bf16 v[106:109], v[168:171], v[184:187], v[106:109]
	v_mfma_f32_16x16x32_bf16 v[94:97], v[140:143], v[208:211], v[94:97]
	v_mfma_f32_16x16x32_bf16 v[90:93], v[168:171], v[208:211], v[90:93]
	v_mfma_f32_16x16x32_bf16 v[78:81], v[140:143], v[216:219], v[78:81]
	v_mfma_f32_16x16x32_bf16 v[74:77], v[168:171], v[216:219], v[74:77]
	v_mfma_f32_16x16x32_bf16 v[126:129], v[152:155], v[180:183], v[126:129]
	v_mfma_f32_16x16x32_bf16 v[122:125], v[172:175], v[180:183], v[122:125]
	v_mfma_f32_16x16x32_bf16 v[110:113], v[152:155], v[204:207], v[110:113]
	v_mfma_f32_16x16x32_bf16 v[106:109], v[172:175], v[204:207], v[106:109]
	v_mfma_f32_16x16x32_bf16 v[94:97], v[152:155], v[212:215], v[94:97]
	v_mfma_f32_16x16x32_bf16 v[90:93], v[172:175], v[212:215], v[90:93]
	v_mfma_f32_16x16x32_bf16 v[78:81], v[152:155], v[226:229], v[78:81]
	v_mfma_f32_16x16x32_bf16 v[74:77], v[172:175], v[226:229], v[74:77]
	s_setprio 0
	s_barrier
	s_add_i32 s42, 0, 0x1c000
	s_add_i32 s43, s58, s48
	v_add_u32_e32 v151, s42, v147
	s_add_u32 s60, s6, 0x80
	s_addc_u32 s61, s7, 0
	s_mov_b32 m0, s43
	ds_read_b128 v[230:233], v151
	ds_read_b128 v[234:237], v151 offset:1024
	ds_read_b128 v[238:241], v151 offset:2048
	ds_read_b128 v[242:245], v151 offset:3072
	global_load_lds_dwordx4 v0, s[60:61]
	s_add_i32 m0, s43, 0x2000
	s_nop 0
	global_load_lds_dwordx4 v130, s[60:61]
	s_barrier
	s_waitcnt lgkmcnt(0)
	s_setprio 1
	s_waitcnt lgkmcnt(0)
	v_mfma_f32_16x16x32_bf16 v[118:121], v[230:233], v[176:179], v[118:121]
	v_mfma_f32_16x16x32_bf16 v[114:117], v[238:241], v[176:179], v[114:117]
	v_mfma_f32_16x16x32_bf16 v[102:105], v[230:233], v[184:187], v[102:105]
	v_mfma_f32_16x16x32_bf16 v[98:101], v[238:241], v[184:187], v[98:101]
	v_mfma_f32_16x16x32_bf16 v[86:89], v[230:233], v[208:211], v[86:89]
	v_mfma_f32_16x16x32_bf16 v[82:85], v[238:241], v[208:211], v[82:85]
	v_mfma_f32_16x16x32_bf16 v[70:73], v[230:233], v[216:219], v[70:73]
	v_mfma_f32_16x16x32_bf16 v[66:69], v[238:241], v[216:219], v[66:69]
	v_mfma_f32_16x16x32_bf16 v[118:121], v[234:237], v[180:183], v[118:121]
	v_mfma_f32_16x16x32_bf16 v[114:117], v[242:245], v[180:183], v[114:117]
	v_mfma_f32_16x16x32_bf16 v[102:105], v[234:237], v[204:207], v[102:105]
	v_mfma_f32_16x16x32_bf16 v[98:101], v[242:245], v[204:207], v[98:101]
	v_mfma_f32_16x16x32_bf16 v[86:89], v[234:237], v[212:215], v[86:89]
	v_mfma_f32_16x16x32_bf16 v[82:85], v[242:245], v[212:215], v[82:85]
	v_mfma_f32_16x16x32_bf16 v[70:73], v[234:237], v[226:229], v[70:73]
	v_mfma_f32_16x16x32_bf16 v[66:69], v[242:245], v[226:229], v[66:69]
	s_setprio 0
	s_mov_b32 m0, s84
	s_barrier
	ds_read_b128 v[176:179], v150 offset:49152
	ds_read_b128 v[180:183], v150 offset:50176
	ds_read_b128 v[184:187], v150 offset:51200
	ds_read_b128 v[204:207], v150 offset:52224
	ds_read_b128 v[208:211], v150 offset:53248
	ds_read_b128 v[212:215], v150 offset:54272
	ds_read_b128 v[216:219], v150 offset:55296
	ds_read_b128 v[226:229], v150 offset:56320
	global_load_lds_dwordx4 v134, vcc
	s_mov_b32 m0, s85
	s_nop 0
	global_load_lds_dwordx4 v132, vcc
	s_barrier
	s_waitcnt lgkmcnt(0)
	s_setprio 1
	s_waitcnt lgkmcnt(0)
	v_mfma_f32_16x16x32_bf16 v[62:65], v[140:143], v[176:179], v[62:65]
	v_mfma_f32_16x16x32_bf16 v[58:61], v[168:171], v[176:179], v[58:61]
	v_mfma_f32_16x16x32_bf16 v[46:49], v[140:143], v[184:187], v[46:49]
	v_mfma_f32_16x16x32_bf16 v[42:45], v[168:171], v[184:187], v[42:45]
	v_mfma_f32_16x16x32_bf16 v[30:33], v[140:143], v[208:211], v[30:33]
	v_mfma_f32_16x16x32_bf16 v[26:29], v[168:171], v[208:211], v[26:29]
	v_mfma_f32_16x16x32_bf16 v[14:17], v[140:143], v[216:219], v[14:17]
	v_mfma_f32_16x16x32_bf16 v[10:13], v[168:171], v[216:219], v[10:13]
	v_mfma_f32_16x16x32_bf16 v[62:65], v[152:155], v[180:183], v[62:65]
	v_mfma_f32_16x16x32_bf16 v[58:61], v[172:175], v[180:183], v[58:61]
	v_mfma_f32_16x16x32_bf16 v[46:49], v[152:155], v[204:207], v[46:49]
	v_mfma_f32_16x16x32_bf16 v[42:45], v[172:175], v[204:207], v[42:45]
	v_mfma_f32_16x16x32_bf16 v[30:33], v[152:155], v[212:215], v[30:33]
	v_mfma_f32_16x16x32_bf16 v[26:29], v[172:175], v[212:215], v[26:29]
	v_mfma_f32_16x16x32_bf16 v[14:17], v[152:155], v[226:229], v[14:17]
	v_mfma_f32_16x16x32_bf16 v[10:13], v[172:175], v[226:229], v[10:13]
	s_setprio 0
	s_barrier
	s_add_u32 s6, s6, 0x40080
	s_addc_u32 s7, s7, 0
	s_add_i32 s42, s42, s48
	s_mov_b32 m0, s42
	s_nop 0
	global_load_lds_dwordx4 v0, s[6:7]
	s_add_i32 m0, s42, 0x2000
	s_nop 0
	global_load_lds_dwordx4 v130, s[6:7]
	s_waitcnt vmcnt(6)
	s_barrier
	s_setprio 1
	v_mfma_f32_16x16x32_bf16 v[54:57], v[230:233], v[176:179], v[54:57]
	v_mfma_f32_16x16x32_bf16 v[50:53], v[238:241], v[176:179], v[50:53]
	v_mfma_f32_16x16x32_bf16 v[38:41], v[230:233], v[184:187], v[38:41]
	v_mfma_f32_16x16x32_bf16 v[34:37], v[238:241], v[184:187], v[34:37]
	v_mfma_f32_16x16x32_bf16 v[22:25], v[230:233], v[208:211], v[22:25]
	v_mfma_f32_16x16x32_bf16 v[18:21], v[238:241], v[208:211], v[18:21]
	v_mfma_f32_16x16x32_bf16 v[6:9], v[230:233], v[216:219], v[6:9]
	v_mfma_f32_16x16x32_bf16 v[2:5], v[238:241], v[216:219], v[2:5]
	v_mfma_f32_16x16x32_bf16 v[54:57], v[234:237], v[180:183], v[54:57]
	v_mfma_f32_16x16x32_bf16 v[50:53], v[242:245], v[180:183], v[50:53]
	v_mfma_f32_16x16x32_bf16 v[38:41], v[234:237], v[204:207], v[38:41]
	v_mfma_f32_16x16x32_bf16 v[34:37], v[242:245], v[204:207], v[34:37]
	v_mfma_f32_16x16x32_bf16 v[22:25], v[234:237], v[212:215], v[22:25]
	v_mfma_f32_16x16x32_bf16 v[18:21], v[242:245], v[212:215], v[18:21]
	v_mfma_f32_16x16x32_bf16 v[6:9], v[234:237], v[226:229], v[6:9]
	v_mfma_f32_16x16x32_bf16 v[2:5], v[242:245], v[226:229], v[2:5]
	s_setprio 0
	s_add_i32 s93, s93, 2
	s_add_u32 s36, s36, 0x100
	s_addc_u32 s37, s37, 0
	s_add_u32 s91, s91, 0x100
	s_addc_u32 s92, s92, 0
	s_cmp_gt_u32 s93, 13
	s_barrier
; __device__ __forceinline__ unsigned pk2(float lo, float hi) { unsigned r; asm("v_cvt_pk_bf16_f32 %0, %1, %2" : "=v"(r) : "v"(lo), "v"(hi)); return r; }
;     __device__ __forceinline__ void operator()(const f32x4 (&acc)[2][2][4][2], const Unit& u, int ui, int wr, int wc, int fr, int fq) const {
;         const int lrow0 = wr * 64 + fr, row0 = u.pm * BM + lrow0, col0 = u.pn * BM + wc * 32 + 8 * fq;
;         float rsv[2][4];
; #pragma unroll
;         for (int ai = 0; ai < 2; ++ai)
; #pragma unroll
;             for (int m = 0; m < 4; ++m) rsv[ai][m] = rstab[ui * 256 + lrow0 + ai * HALF + m * 16];
; #pragma unroll
;         for (int ai = 0; ai < 2; ++ai)
; #pragma unroll
;             for (int m = 0; m < 4; ++m) {
;                 const int row = row0 + ai * HALF + m * 16; const float rs = rsv[ai][m];
;                 bf16_t* rowp = O + (size_t)row * ldc + col0;
; #pragma unroll
;                 for (int bj = 0; bj < 2; ++bj) {
;                     f32x4 v0 = acc[ai][bj][m][0] * rs, v1 = acc[ai][bj][m][1] * rs;
;                     if (ACT == 1) {
; #pragma unroll
;                         for (int j = 0; j < 4; ++j) { const float a = fmaxf(v0[j], 0.f), b = fmaxf(v1[j], 0.f); v0[j] = a * a; v1[j] = b * b; }
;                     }
;                     u32x4 w; w.x = pk2(v0[0], v0[1]); w.y = pk2(v0[2], v0[3]); w.z = pk2(v1[0], v1[1]); w.w = pk2(v1[2], v1[3]);
;                     *(u32x4*)(rowp + bj * HALF) = w;
;                 }
;             }
	v_lshl_add_u32 v140, s89, 10, v148
	ds_read2_b32 v[154:155], v140 offset1:16
	ds_read2_b32 v[156:157], v140 offset0:32 offset1:48
	ds_read2_b32 v[144:145], v140 offset0:128 offset1:144
	ds_read2_b32 v[142:143], v140 offset0:160 offset1:176
	v_lshl_add_u32 v152, s88, 8, v146
	s_waitcnt lgkmcnt(0)
	v_pk_mul_f32 v[122:123], v[122:123], v[154:155] op_sel_hi:[1,0]
	v_lshl_or_b32 v140, s87, 8, v149
	v_lshlrev_b32_e32 v250, 13, v152
	v_lshl_add_u32 v250, v140, 1, v250
	v_add_u32_e32 v250, 0x100000, v250
	v_ashrrev_i32_e32 v153, 31, v152
	v_pk_mul_f32 v[126:127], v[126:127], v[154:155] op_sel_hi:[1,0]
	v_pk_mul_f32 v[124:125], v[124:125], v[154:155] op_sel_hi:[1,0]
	v_max_f32_e32 v122, 0, v122
	v_ashrrev_i32_e32 v141, 31, v140
	v_lshlrev_b64 v[162:163], 13, v[152:153]
	v_pk_mul_f32 v[128:129], v[128:129], v[154:155] op_sel_hi:[1,0]
	v_mul_f32_e32 v151, v122, v122
	v_max_f32_e32 v122, 0, v127
	v_max_f32_e32 v123, 0, v123
	v_max_f32_e32 v124, 0, v124
	v_lshl_add_u64 v[162:163], s[4:5], 0, v[162:163]
	v_lshlrev_b64 v[168:169], 1, v[140:141]
	v_max_f32_e32 v126, 0, v126
	v_mul_f32_e32 v122, v122, v122
	v_mul_f32_e32 v127, v123, v123
	v_max_f32_e32 v123, 0, v128
	v_mul_f32_e32 v128, v124, v124
	v_max_f32_e32 v124, 0, v129
	v_max_f32_e32 v125, 0, v125
	v_pk_mul_f32 v[116:117], v[116:117], v[154:155] op_sel_hi:[1,0]
	v_pk_mul_f32 v[114:115], v[114:115], v[154:155] op_sel_hi:[1,0]
	v_lshl_add_u64 v[140:141], v[162:163], 0, v[168:169]
	v_mul_f32_e32 v126, v126, v126
	v_mul_f32_e32 v123, v123, v123
	v_mul_f32_e32 v124, v124, v124
	v_mul_f32_e32 v125, v125, v125
	v_cvt_pk_bf16_f32 v122, v126, v122
	v_pk_mul_f32 v[120:121], v[120:121], v[154:155] op_sel_hi:[1,0]
	v_pk_mul_f32 v[118:119], v[118:119], v[154:155] op_sel_hi:[1,0]
	v_max_f32_e32 v114, 0, v114
	v_max_f32_e32 v115, 0, v115
	v_max_f32_e32 v116, 0, v116
	v_cvt_pk_bf16_f32 v123, v123, v124
	v_cvt_pk_bf16_f32 v124, v151, v127
	v_cvt_pk_bf16_f32 v125, v128, v125
	global_store_dwordx4 v[140:141], v[122:125], off
	v_max_f32_e32 v117, 0, v117
	v_max_f32_e32 v118, 0, v118
	v_mul_f32_e32 v122, v114, v114
	v_max_f32_e32 v114, 0, v119
	v_mul_f32_e32 v119, v115, v115
	v_max_f32_e32 v115, 0, v120
	v_mul_f32_e32 v120, v116, v116
	v_max_f32_e32 v116, 0, v121
	v_mul_f32_e32 v115, v115, v115
	v_mul_f32_e32 v116, v116, v116
	v_mul_f32_e32 v114, v114, v114
	v_mul_f32_e32 v117, v117, v117
	v_cvt_pk_bf16_f32 v115, v115, v116
	v_cvt_pk_bf16_f32 v116, v122, v119
	v_mul_f32_e32 v118, v118, v118
	v_cvt_pk_bf16_f32 v114, v118, v114
	v_cvt_pk_bf16_f32 v117, v120, v117
	global_store_dwordx4 v[140:141], v[114:117], off offset:256
	v_pk_mul_f32 v[90:91], v[90:91], v[156:157] op_sel_hi:[1,0]
	v_pk_mul_f32 v[94:95], v[94:95], v[156:157] op_sel_hi:[1,0]
	v_mov_b32_e32 v116, v155
	v_or_b32_e32 v114, 16, v152
	v_pk_mul_f32 v[106:107], v[106:107], v[116:117] op_sel_hi:[1,0]
	v_ashrrev_i32_e32 v115, 31, v114
	v_pk_mul_f32 v[110:111], v[110:111], v[116:117] op_sel_hi:[1,0]
	v_pk_mul_f32 v[108:109], v[108:109], v[116:117] op_sel_hi:[1,0]
	v_max_f32_e32 v106, 0, v106
	v_lshlrev_b64 v[114:115], 13, v[114:115]
	v_pk_mul_f32 v[112:113], v[112:113], v[116:117] op_sel_hi:[1,0]
	v_mul_f32_e32 v117, v106, v106
	v_max_f32_e32 v106, 0, v111
	v_max_f32_e32 v107, 0, v107
	v_max_f32_e32 v108, 0, v108
	v_lshl_add_u64 v[114:115], s[4:5], 0, v[114:115]
	v_max_f32_e32 v110, 0, v110
	v_mul_f32_e32 v106, v106, v106
	v_mul_f32_e32 v111, v107, v107
	v_max_f32_e32 v107, 0, v112
	v_mul_f32_e32 v112, v108, v108
	v_max_f32_e32 v108, 0, v113
	v_max_f32_e32 v109, 0, v109
	v_pk_mul_f32 v[98:99], v[98:99], v[116:117] op_sel_hi:[1,0]
	v_lshl_add_u64 v[114:115], v[114:115], 0, v[168:169]
	v_mul_f32_e32 v110, v110, v110
	v_mul_f32_e32 v107, v107, v107
	v_mul_f32_e32 v108, v108, v108
	v_mul_f32_e32 v109, v109, v109
	v_cvt_pk_bf16_f32 v106, v110, v106
	v_pk_mul_f32 v[102:103], v[102:103], v[116:117] op_sel_hi:[1,0]
	v_pk_mul_f32 v[100:101], v[100:101], v[116:117] op_sel_hi:[1,0]
	v_max_f32_e32 v98, 0, v98
	v_cvt_pk_bf16_f32 v107, v107, v108
	v_cvt_pk_bf16_f32 v108, v117, v111
	v_cvt_pk_bf16_f32 v109, v112, v109
	global_store_dwordx4 v[114:115], v[106:109], off
	v_pk_mul_f32 v[104:105], v[104:105], v[116:117] op_sel_hi:[1,0]
	v_max_f32_e32 v99, 0, v99
	v_mul_f32_e32 v106, v98, v98
	v_max_f32_e32 v98, 0, v103
	v_max_f32_e32 v100, 0, v100
	v_max_f32_e32 v102, 0, v102
	v_mul_f32_e32 v98, v98, v98
	v_mul_f32_e32 v103, v99, v99
	v_max_f32_e32 v99, 0, v104
	v_mul_f32_e32 v104, v100, v100
	v_max_f32_e32 v100, 0, v105
	v_max_f32_e32 v101, 0, v101
	v_mul_f32_e32 v102, v102, v102
	v_mul_f32_e32 v99, v99, v99
	v_mul_f32_e32 v100, v100, v100
	v_mul_f32_e32 v101, v101, v101
	v_cvt_pk_bf16_f32 v98, v102, v98
	v_cvt_pk_bf16_f32 v99, v99, v100
	v_cvt_pk_bf16_f32 v100, v106, v103
	v_cvt_pk_bf16_f32 v101, v104, v101
	global_store_dwordx4 v[114:115], v[98:101], off offset:256
	v_pk_mul_f32 v[92:93], v[92:93], v[156:157] op_sel_hi:[1,0]
	v_max_f32_e32 v90, 0, v90
	v_or_b32_e32 v98, 32, v152
	v_ashrrev_i32_e32 v99, 31, v98
	v_lshlrev_b64 v[98:99], 13, v[98:99]
	v_pk_mul_f32 v[96:97], v[96:97], v[156:157] op_sel_hi:[1,0]
	v_mul_f32_e32 v100, v90, v90
	v_max_f32_e32 v90, 0, v95
	v_max_f32_e32 v91, 0, v91
	v_max_f32_e32 v92, 0, v92
	v_lshl_add_u64 v[98:99], s[4:5], 0, v[98:99]
	v_max_f32_e32 v94, 0, v94
	v_mul_f32_e32 v90, v90, v90
	v_mul_f32_e32 v95, v91, v91
	v_max_f32_e32 v91, 0, v96
	v_mul_f32_e32 v96, v92, v92
	v_max_f32_e32 v92, 0, v97
	v_max_f32_e32 v93, 0, v93
	v_pk_mul_f32 v[84:85], v[84:85], v[156:157] op_sel_hi:[1,0]
	v_pk_mul_f32 v[82:83], v[82:83], v[156:157] op_sel_hi:[1,0]
	v_lshl_add_u64 v[98:99], v[98:99], 0, v[168:169]
	v_mul_f32_e32 v94, v94, v94
	v_mul_f32_e32 v91, v91, v91
; __device__ __forceinline__ unsigned pk2(float lo, float hi) { unsigned r; asm("v_cvt_pk_bf16_f32 %0, %1, %2" : "=v"(r) : "v"(lo), "v"(hi)); return r; }
;     __device__ __forceinline__ void operator()(const f32x4 (&acc)[2][2][4][2], const Unit& u, int ui, int wr, int wc, int fr, int fq) const {
;     ...
;         for (int ai = 0; ai < 2; ++ai)
; #pragma unroll
;             for (int m = 0; m < 4; ++m) {
;                 const int row = row0 + ai * HALF + m * 16; const float rs = rsv[ai][m];
;                 bf16_t* rowp = O + (size_t)row * ldc + col0;
; #pragma unroll
;                 for (int bj = 0; bj < 2; ++bj) {
;                     f32x4 v0 = acc[ai][bj][m][0] * rs, v1 = acc[ai][bj][m][1] * rs;
;                     if (ACT == 1) {
; #pragma unroll
;                         for (int j = 0; j < 4; ++j) { const float a = fmaxf(v0[j], 0.f), b = fmaxf(v1[j], 0.f); v0[j] = a * a; v1[j] = b * b; }
;                     }
;                     u32x4 w; w.x = pk2(v0[0], v0[1]); w.y = pk2(v0[2], v0[3]); w.z = pk2(v1[0], v1[1]); w.w = pk2(v1[2], v1[3]);
;                     *(u32x4*)(rowp + bj * HALF) = w;
	v_mul_f32_e32 v92, v92, v92
	v_mul_f32_e32 v93, v93, v93
	v_cvt_pk_bf16_f32 v90, v94, v90
	v_pk_mul_f32 v[88:89], v[88:89], v[156:157] op_sel_hi:[1,0]
	v_pk_mul_f32 v[86:87], v[86:87], v[156:157] op_sel_hi:[1,0]
	v_max_f32_e32 v82, 0, v82
	v_max_f32_e32 v83, 0, v83
	v_max_f32_e32 v84, 0, v84
	v_cvt_pk_bf16_f32 v91, v91, v92
	v_cvt_pk_bf16_f32 v92, v100, v95
	v_cvt_pk_bf16_f32 v93, v96, v93
	global_store_dwordx4 v[98:99], v[90:93], off
	v_max_f32_e32 v85, 0, v85
	v_max_f32_e32 v86, 0, v86
	v_mul_f32_e32 v90, v82, v82
	v_max_f32_e32 v82, 0, v87
	v_mul_f32_e32 v87, v83, v83
	v_max_f32_e32 v83, 0, v88
	v_mul_f32_e32 v88, v84, v84
	v_max_f32_e32 v84, 0, v89
	v_mul_f32_e32 v83, v83, v83
	v_mul_f32_e32 v84, v84, v84
	v_mul_f32_e32 v82, v82, v82
	v_mul_f32_e32 v85, v85, v85
	v_cvt_pk_bf16_f32 v83, v83, v84
	v_cvt_pk_bf16_f32 v84, v90, v87
	v_mul_f32_e32 v86, v86, v86
	v_cvt_pk_bf16_f32 v82, v86, v82
	v_cvt_pk_bf16_f32 v85, v88, v85
	global_store_dwordx4 v[98:99], v[82:85], off offset:256
	v_pk_mul_f32 v[58:59], v[58:59], v[144:145] op_sel_hi:[1,0]
	v_pk_mul_f32 v[62:63], v[62:63], v[144:145] op_sel_hi:[1,0]
	v_mov_b32_e32 v84, v157
	v_or_b32_e32 v82, 48, v152
	v_pk_mul_f32 v[74:75], v[74:75], v[84:85] op_sel_hi:[1,0]
	v_ashrrev_i32_e32 v83, 31, v82
	v_pk_mul_f32 v[78:79], v[78:79], v[84:85] op_sel_hi:[1,0]
	v_pk_mul_f32 v[76:77], v[76:77], v[84:85] op_sel_hi:[1,0]
	v_max_f32_e32 v74, 0, v74
	v_lshlrev_b64 v[82:83], 13, v[82:83]
	v_pk_mul_f32 v[80:81], v[80:81], v[84:85] op_sel_hi:[1,0]
	v_mul_f32_e32 v85, v74, v74
	v_max_f32_e32 v74, 0, v79
	v_max_f32_e32 v75, 0, v75
	v_max_f32_e32 v76, 0, v76
	v_lshl_add_u64 v[82:83], s[4:5], 0, v[82:83]
	v_max_f32_e32 v78, 0, v78
	v_mul_f32_e32 v74, v74, v74
	v_mul_f32_e32 v79, v75, v75
	v_max_f32_e32 v75, 0, v80
	v_mul_f32_e32 v80, v76, v76
	v_max_f32_e32 v76, 0, v81
	v_max_f32_e32 v77, 0, v77
	v_pk_mul_f32 v[68:69], v[68:69], v[84:85] op_sel_hi:[1,0]
	v_pk_mul_f32 v[66:67], v[66:67], v[84:85] op_sel_hi:[1,0]
	v_lshl_add_u64 v[82:83], v[82:83], 0, v[168:169]
	v_mul_f32_e32 v78, v78, v78
	v_mul_f32_e32 v75, v75, v75
	v_mul_f32_e32 v76, v76, v76
	v_mul_f32_e32 v77, v77, v77
	v_cvt_pk_bf16_f32 v74, v78, v74
	v_pk_mul_f32 v[72:73], v[72:73], v[84:85] op_sel_hi:[1,0]
	v_pk_mul_f32 v[70:71], v[70:71], v[84:85] op_sel_hi:[1,0]
	v_max_f32_e32 v66, 0, v66
	v_max_f32_e32 v67, 0, v67
	v_max_f32_e32 v68, 0, v68
	v_cvt_pk_bf16_f32 v75, v75, v76
	v_cvt_pk_bf16_f32 v76, v85, v79
	v_cvt_pk_bf16_f32 v77, v80, v77
	global_store_dwordx4 v[82:83], v[74:77], off
	v_max_f32_e32 v69, 0, v69
	v_max_f32_e32 v70, 0, v70
	v_mul_f32_e32 v74, v66, v66
	v_max_f32_e32 v66, 0, v71
	v_mul_f32_e32 v71, v67, v67
	v_max_f32_e32 v67, 0, v72
	v_mul_f32_e32 v72, v68, v68
	v_max_f32_e32 v68, 0, v73
	v_mul_f32_e32 v67, v67, v67
	v_mul_f32_e32 v68, v68, v68
	v_mul_f32_e32 v66, v66, v66
	v_mul_f32_e32 v69, v69, v69
	v_cvt_pk_bf16_f32 v67, v67, v68
	v_cvt_pk_bf16_f32 v68, v74, v71
	v_pk_mul_f32 v[60:61], v[60:61], v[144:145] op_sel_hi:[1,0]
	v_max_f32_e32 v58, 0, v58
	v_mul_f32_e32 v70, v70, v70
	v_cvt_pk_bf16_f32 v66, v70, v66
	v_cvt_pk_bf16_f32 v69, v72, v69
	global_store_dwordx4 v[82:83], v[66:69], off offset:256
	s_mov_b64 s[6:7], 0x100000
	v_pk_mul_f32 v[64:65], v[64:65], v[144:145] op_sel_hi:[1,0]
	v_max_f32_e32 v62, 0, v62
	v_mul_f32_e32 v68, v58, v58
	v_max_f32_e32 v58, 0, v63
	v_max_f32_e32 v59, 0, v59
	v_max_f32_e32 v60, 0, v60
	v_lshl_add_u64 v[66:67], v[140:141], 0, s[6:7]
	v_mul_f32_e32 v62, v62, v62
	v_mul_f32_e32 v58, v58, v58
	v_mul_f32_e32 v63, v59, v59
	v_max_f32_e32 v59, 0, v64
	v_mul_f32_e32 v64, v60, v60
	v_max_f32_e32 v60, 0, v65
	s_mov_b32 s6, 0x100000
	v_mul_f32_e32 v59, v59, v59
	v_max_f32_e32 v61, 0, v61
	v_mul_f32_e32 v60, v60, v60
	v_cvt_pk_bf16_f32 v58, v62, v58
	v_add_co_u32_e32 v62, vcc, s6, v140
	v_pk_mul_f32 v[52:53], v[52:53], v[144:145] op_sel_hi:[1,0]
	v_pk_mul_f32 v[50:51], v[50:51], v[144:145] op_sel_hi:[1,0]
	v_mul_f32_e32 v61, v61, v61
	v_cvt_pk_bf16_f32 v59, v59, v60
	v_cvt_pk_bf16_f32 v60, v68, v63
	v_addc_co_u32_e32 v63, vcc, 0, v141, vcc
	v_pk_mul_f32 v[56:57], v[56:57], v[144:145] op_sel_hi:[1,0]
	v_pk_mul_f32 v[54:55], v[54:55], v[144:145] op_sel_hi:[1,0]
	v_max_f32_e32 v50, 0, v50
	v_max_f32_e32 v51, 0, v51
	v_max_f32_e32 v52, 0, v52
	v_cvt_pk_bf16_f32 v61, v64, v61
	v_mov_b32_e32 v158, v58
	v_mov_b32_e32 v159, v59
	v_mov_b32_e32 v160, v60
	v_mov_b32_e32 v161, v61
	v_max_f32_e32 v53, 0, v53
	v_max_f32_e32 v54, 0, v54
	v_mul_f32_e32 v58, v50, v50
	v_max_f32_e32 v50, 0, v55
	v_mul_f32_e32 v55, v51, v51
	v_max_f32_e32 v51, 0, v56
	v_mul_f32_e32 v56, v52, v52
	v_max_f32_e32 v52, 0, v57
	v_mul_f32_e32 v51, v51, v51
	v_mul_f32_e32 v52, v52, v52
	v_mul_f32_e32 v50, v50, v50
	v_mul_f32_e32 v53, v53, v53
	v_cvt_pk_bf16_f32 v51, v51, v52
	v_cvt_pk_bf16_f32 v52, v58, v55
	v_mul_f32_e32 v54, v54, v54
	v_cvt_pk_bf16_f32 v50, v54, v50
	v_cvt_pk_bf16_f32 v53, v56, v53
	v_mov_b32_e32 v164, v50
	v_mov_b32_e32 v165, v51
	v_mov_b32_e32 v166, v52
	v_mov_b32_e32 v167, v53
	s_mov_b64 s[6:7], 0x120000
	v_pk_mul_f32 v[26:27], v[26:27], v[142:143] op_sel_hi:[1,0]
	v_mov_b32_e32 v52, v145
	v_pk_mul_f32 v[42:43], v[42:43], v[52:53] op_sel_hi:[1,0]
	v_pk_mul_f32 v[46:47], v[46:47], v[52:53] op_sel_hi:[1,0]
	v_pk_mul_f32 v[44:45], v[44:45], v[52:53] op_sel_hi:[1,0]
	v_max_f32_e32 v42, 0, v42
	v_pk_mul_f32 v[48:49], v[48:49], v[52:53] op_sel_hi:[1,0]
	v_max_f32_e32 v46, 0, v46
	v_mul_f32_e32 v53, v42, v42
	v_max_f32_e32 v42, 0, v47
	v_max_f32_e32 v43, 0, v43
	v_max_f32_e32 v44, 0, v44
	v_lshl_add_u64 v[50:51], v[140:141], 0, s[6:7]
	v_mul_f32_e32 v46, v46, v46
	v_mul_f32_e32 v42, v42, v42
	v_mul_f32_e32 v47, v43, v43
	v_max_f32_e32 v43, 0, v48
; __device__ __forceinline__ unsigned pk2(float lo, float hi) { unsigned r; asm("v_cvt_pk_bf16_f32 %0, %1, %2" : "=v"(r) : "v"(lo), "v"(hi)); return r; }
; #define PG8_WAIT_V(n) asm volatile("s_waitcnt vmcnt(" #n ")" ::: "memory")
;     __device__ __forceinline__ void operator()(const f32x4 (&acc)[2][2][4][2], const Unit& u, int ui, int wr, int wc, int fr, int fq) const {
;     ...
;         for (int ai = 0; ai < 2; ++ai)
; #pragma unroll
;             for (int m = 0; m < 4; ++m) {
;                 const int row = row0 + ai * HALF + m * 16; const float rs = rsv[ai][m];
;                 bf16_t* rowp = O + (size_t)row * ldc + col0;
; #pragma unroll
;                 for (int bj = 0; bj < 2; ++bj) {
;                     f32x4 v0 = acc[ai][bj][m][0] * rs, v1 = acc[ai][bj][m][1] * rs;
;                     if (ACT == 1) {
; #pragma unroll
;                         for (int j = 0; j < 4; ++j) { const float a = fmaxf(v0[j], 0.f), b = fmaxf(v1[j], 0.f); v0[j] = a * a; v1[j] = b * b; }
;                     }
;                     u32x4 w; w.x = pk2(v0[0], v0[1]); w.y = pk2(v0[2], v0[3]); w.z = pk2(v1[0], v1[1]); w.w = pk2(v1[2], v1[3]);
;                     *(u32x4*)(rowp + bj * HALF) = w;
;                 }
;             }
; template <class Epi>
; __device__ __forceinline__ void gemm_phase(LAS unsigned char* lds, const Gemm g, const StaticOrder& S, const Epi& E) {
;     ...
;         E(acc, cur, ui, wr, wc, fr, fq);
;         if (!has_next) break;
; #pragma unroll
;         for (int a = 0; a < 2; ++a)
; #pragma unroll
;             for (int b = 0; b < 2; ++b)
; #pragma unroll
;                 for (int m = 0; m < 4; ++m)
; #pragma unroll
;                     for (int n = 0; n < 2; ++n) acc[a][b][m][n] = (f32x4){0.f, 0.f, 0.f, 0.f};
;         cur = nxt; cA = nA; cB = nB; ++ui;
;     }
;     PG8_WAIT_V(0);
	v_mul_f32_e32 v48, v44, v44
	v_max_f32_e32 v44, 0, v49
	s_mov_b32 s6, 0x120000
	v_mul_f32_e32 v43, v43, v43
	v_max_f32_e32 v45, 0, v45
	v_mul_f32_e32 v44, v44, v44
	v_cvt_pk_bf16_f32 v42, v46, v42
	v_add_co_u32_e32 v46, vcc, s6, v140
	v_pk_mul_f32 v[36:37], v[36:37], v[52:53] op_sel_hi:[1,0]
	v_pk_mul_f32 v[34:35], v[34:35], v[52:53] op_sel_hi:[1,0]
	v_mul_f32_e32 v45, v45, v45
	v_cvt_pk_bf16_f32 v43, v43, v44
	v_cvt_pk_bf16_f32 v44, v53, v47
	v_addc_co_u32_e32 v47, vcc, 0, v141, vcc
	v_pk_mul_f32 v[40:41], v[40:41], v[52:53] op_sel_hi:[1,0]
	v_pk_mul_f32 v[38:39], v[38:39], v[52:53] op_sel_hi:[1,0]
	v_max_f32_e32 v34, 0, v34
	v_max_f32_e32 v35, 0, v35
	v_max_f32_e32 v36, 0, v36
	v_cvt_pk_bf16_f32 v45, v48, v45
	v_mov_b32_e32 v188, v42
	v_mov_b32_e32 v189, v43
	v_mov_b32_e32 v190, v44
	v_mov_b32_e32 v191, v45
	v_max_f32_e32 v37, 0, v37
	v_max_f32_e32 v38, 0, v38
	v_mul_f32_e32 v42, v34, v34
	v_max_f32_e32 v34, 0, v39
	v_mul_f32_e32 v39, v35, v35
	v_max_f32_e32 v35, 0, v40
	v_mul_f32_e32 v40, v36, v36
	v_max_f32_e32 v36, 0, v41
	v_mul_f32_e32 v35, v35, v35
	v_mul_f32_e32 v36, v36, v36
	v_mul_f32_e32 v34, v34, v34
	v_mul_f32_e32 v37, v37, v37
	v_cvt_pk_bf16_f32 v35, v35, v36
	v_cvt_pk_bf16_f32 v36, v42, v39
	v_pk_mul_f32 v[30:31], v[30:31], v[142:143] op_sel_hi:[1,0]
	v_pk_mul_f32 v[28:29], v[28:29], v[142:143] op_sel_hi:[1,0]
	v_max_f32_e32 v26, 0, v26
	v_mul_f32_e32 v38, v38, v38
	v_cvt_pk_bf16_f32 v34, v38, v34
	v_cvt_pk_bf16_f32 v37, v40, v37
	v_mov_b32_e32 v192, v34
	v_mov_b32_e32 v193, v35
	v_mov_b32_e32 v194, v36
	v_mov_b32_e32 v195, v37
	s_mov_b64 s[6:7], 0x140000
	v_pk_mul_f32 v[32:33], v[32:33], v[142:143] op_sel_hi:[1,0]
	v_max_f32_e32 v30, 0, v30
	v_mul_f32_e32 v36, v26, v26
	v_max_f32_e32 v26, 0, v31
	v_max_f32_e32 v27, 0, v27
	v_max_f32_e32 v28, 0, v28
	v_lshl_add_u64 v[34:35], v[140:141], 0, s[6:7]
	v_mul_f32_e32 v30, v30, v30
	v_mul_f32_e32 v26, v26, v26
	v_mul_f32_e32 v31, v27, v27
	v_max_f32_e32 v27, 0, v32
	v_mul_f32_e32 v32, v28, v28
	v_max_f32_e32 v28, 0, v33
	s_mov_b32 s6, 0x140000
	v_mul_f32_e32 v27, v27, v27
	v_max_f32_e32 v29, 0, v29
	v_mul_f32_e32 v28, v28, v28
	v_cvt_pk_bf16_f32 v26, v30, v26
	v_add_co_u32_e32 v30, vcc, s6, v140
	v_pk_mul_f32 v[20:21], v[20:21], v[142:143] op_sel_hi:[1,0]
	v_pk_mul_f32 v[18:19], v[18:19], v[142:143] op_sel_hi:[1,0]
	v_mul_f32_e32 v29, v29, v29
	v_cvt_pk_bf16_f32 v27, v27, v28
	v_cvt_pk_bf16_f32 v28, v36, v31
	v_addc_co_u32_e32 v31, vcc, 0, v141, vcc
	v_pk_mul_f32 v[24:25], v[24:25], v[142:143] op_sel_hi:[1,0]
	v_pk_mul_f32 v[22:23], v[22:23], v[142:143] op_sel_hi:[1,0]
	v_max_f32_e32 v18, 0, v18
	v_max_f32_e32 v19, 0, v19
	v_max_f32_e32 v20, 0, v20
	v_cvt_pk_bf16_f32 v29, v32, v29
	v_mov_b32_e32 v196, v26
	v_mov_b32_e32 v197, v27
	v_mov_b32_e32 v198, v28
	v_mov_b32_e32 v199, v29
	v_max_f32_e32 v21, 0, v21
	v_max_f32_e32 v22, 0, v22
	v_mul_f32_e32 v26, v18, v18
	v_max_f32_e32 v18, 0, v23
	v_mul_f32_e32 v23, v19, v19
	v_max_f32_e32 v19, 0, v24
	v_mul_f32_e32 v24, v20, v20
	v_max_f32_e32 v20, 0, v25
	v_mul_f32_e32 v19, v19, v19
	v_mul_f32_e32 v20, v20, v20
	v_mul_f32_e32 v18, v18, v18
	v_mul_f32_e32 v21, v21, v21
	v_cvt_pk_bf16_f32 v19, v19, v20
	v_cvt_pk_bf16_f32 v20, v26, v23
	v_mul_f32_e32 v22, v22, v22
	v_cvt_pk_bf16_f32 v18, v22, v18
	v_cvt_pk_bf16_f32 v21, v24, v21
	v_mov_b32_e32 v200, v18
	v_mov_b32_e32 v201, v19
	v_mov_b32_e32 v202, v20
	v_mov_b32_e32 v203, v21
	s_mov_b64 s[6:7], 0x160000
	s_mov_b32 s87, s8
	v_mov_b32_e32 v20, v143
	v_pk_mul_f32 v[10:11], v[10:11], v[20:21] op_sel_hi:[1,0]
	v_pk_mul_f32 v[14:15], v[14:15], v[20:21] op_sel_hi:[1,0]
	v_pk_mul_f32 v[12:13], v[12:13], v[20:21] op_sel_hi:[1,0]
	v_max_f32_e32 v10, 0, v10
	v_pk_mul_f32 v[16:17], v[16:17], v[20:21] op_sel_hi:[1,0]
	v_max_f32_e32 v14, 0, v14
	v_mul_f32_e32 v21, v10, v10
	v_max_f32_e32 v10, 0, v15
	v_max_f32_e32 v11, 0, v11
	v_max_f32_e32 v12, 0, v12
	v_lshl_add_u64 v[18:19], v[140:141], 0, s[6:7]
	v_mul_f32_e32 v14, v14, v14
	v_mul_f32_e32 v10, v10, v10
	v_mul_f32_e32 v15, v11, v11
	v_max_f32_e32 v11, 0, v16
	v_mul_f32_e32 v16, v12, v12
	v_max_f32_e32 v12, 0, v17
	s_mov_b32 s6, 0x160000
	v_mul_f32_e32 v11, v11, v11
	v_max_f32_e32 v13, 0, v13
	v_mul_f32_e32 v12, v12, v12
	v_cvt_pk_bf16_f32 v10, v14, v10
	v_add_co_u32_e32 v14, vcc, s6, v140
	v_pk_mul_f32 v[4:5], v[4:5], v[20:21] op_sel_hi:[1,0]
	v_pk_mul_f32 v[2:3], v[2:3], v[20:21] op_sel_hi:[1,0]
	v_mul_f32_e32 v13, v13, v13
	v_cvt_pk_bf16_f32 v11, v11, v12
	v_cvt_pk_bf16_f32 v12, v21, v15
	v_addc_co_u32_e32 v15, vcc, 0, v141, vcc
	v_pk_mul_f32 v[8:9], v[8:9], v[20:21] op_sel_hi:[1,0]
	v_pk_mul_f32 v[6:7], v[6:7], v[20:21] op_sel_hi:[1,0]
	v_max_f32_e32 v2, 0, v2
	v_max_f32_e32 v3, 0, v3
	v_max_f32_e32 v4, 0, v4
	v_cvt_pk_bf16_f32 v13, v16, v13
	v_mov_b32_e32 v222, v10
	v_mov_b32_e32 v223, v11
	v_mov_b32_e32 v224, v12
	v_mov_b32_e32 v225, v13
	v_max_f32_e32 v5, 0, v5
	v_max_f32_e32 v6, 0, v6
	v_mul_f32_e32 v10, v2, v2
	v_max_f32_e32 v2, 0, v7
	v_mul_f32_e32 v7, v3, v3
	v_max_f32_e32 v3, 0, v8
	v_mul_f32_e32 v8, v4, v4
	v_max_f32_e32 v4, 0, v9
	v_mul_f32_e32 v2, v2, v2
	v_mul_f32_e32 v3, v3, v3
	v_mul_f32_e32 v4, v4, v4
	v_mul_f32_e32 v5, v5, v5
	s_and_b64 vcc, exec, s[40:41]
	s_mov_b32 s88, s10
	s_mov_b64 s[6:7], s[24:25]
	s_mov_b64 s[36:37], s[12:13]
	s_mov_b32 s89, s86
	v_mul_f32_e32 v6, v6, v6
	v_cvt_pk_bf16_f32 v2, v6, v2
	v_cvt_pk_bf16_f32 v3, v3, v4
	v_cvt_pk_bf16_f32 v4, v10, v7
	v_cvt_pk_bf16_f32 v5, v8, v5
	v_mov_b32_e32 v246, v2
	v_mov_b32_e32 v247, v3
	v_mov_b32_e32 v248, v4
	v_mov_b32_e32 v249, v5
	s_cbranch_vccz .LBB0_163
	global_store_dwordx4 v250, v[158:161], s[4:5]
	global_store_dwordx4 v250, v[164:167], s[4:5] offset:256
	v_add_u32_e32 v250, 0x20000, v250
	global_store_dwordx4 v250, v[188:191], s[4:5]
	global_store_dwordx4 v250, v[192:195], s[4:5] offset:256
	v_add_u32_e32 v250, 0x20000, v250
	global_store_dwordx4 v250, v[196:199], s[4:5]
	global_store_dwordx4 v250, v[200:203], s[4:5] offset:256
	v_add_u32_e32 v250, 0x20000, v250
	global_store_dwordx4 v250, v[222:225], s[4:5]
	global_store_dwordx4 v250, v[246:249], s[4:5] offset:256
	s_nop 1
	v_mov_b64_e32 v[164:165], 0x200
	v_mbcnt_lo_u32_b32 v193, -1, 0
	v_mbcnt_hi_u32_b32 v193, -1, v193
	v_add_u32_e32 v167, s18, v193
	v_mov_b32_e32 v188, 1
	v_mov_b32_e32 v189, 0x358637bd
	v_mov_b32_e32 v190, 0x260
	v_mov_b32_e32 v191, 0x3c0881c4
	v_mov_b32_e32 v192, 0xbab64f3b
	v_mov_b32_e32 v194, 0xf149f2ca
	v_mov_b32_e32 v195, 0xc0
	v_mov_b32_e32 v196, 0x70
	v_mov_b32_e32 v197, 0x71
	v_mov_b32_e32 v198, 5
	v_mov_b32_e32 v199, 2
	v_mov_b32_e32 v200, 3
	v_not_b32_e32 v201, 63
	v_not_b32_e32 v202, 31
	v_mov_b32_e32 v203, 0x7fc00000
	v_mov_b32_e32 v222, 0
	v_mov_b32_e32 v223, 0
	v_mov_b32_e32 v224, 0
	v_mov_b32_e32 v225, 0
	s_waitcnt vmcnt(0)
	v_readlane_b32 s70, v254, 40
	v_readlane_b32 s84, v254, 42
	s_cmpk_gt_u32 s18, 0xff
	v_readlane_b32 s71, v254, 41
	v_readlane_b32 s86, v254, 44
	v_readlane_b32 s87, v254, 45
	v_readlane_b32 s85, v254, 43
	s_cbranch_scc1 .LBB0_174
	s_barrier

; __device__ __forceinline__ float fast_rcp(float x) { return __builtin_amdgcn_rcpf(x); }
; __device__ __forceinline__ void attn_block(KP p, LAS unsigned char* lds, int bh, int q0) {
;     ...
;     const float ltot = lrun + __shfl_xor(lrun, 32), inv = fast_rcp(ltot);
;     o0 = o0 * inv; o1 = o1 * inv;
;     float ss = 0.f;
; #pragma unroll
;     for (int i = 0; i < 16; ++i) ss += o0[i] * o0[i] + o1[i] * o1[i];
;     ss += __shfl_xor(ss, 32);
;     const int b = bh >> 2, hd = bh & 3; const size_t grow = (size_t)b * SEQ + qrow;
;     if (lh == 0) ((float*)(ws + OFF_SSQM))[grow * 4 + hd] = ss;
.LBB0_275:
	ds_bpermute_b32 v0, v156, v175
	v_cmp_eq_u32_e32 vcc, 0, v157
	s_waitcnt lgkmcnt(0)
	v_add_f32_e32 v0, v175, v0
	v_rcp_f32_e32 v0, v0
	s_nop 0
	v_pk_mul_f32 v[2:3], v[2:3], v[0:1] op_sel_hi:[1,0]
	v_pk_mul_f32 v[32:33], v[32:33], v[0:1] op_sel_hi:[1,0]
	v_pk_mul_f32 v[30:31], v[30:31], v[0:1] op_sel_hi:[1,0]
	v_pk_mul_f32 v[28:29], v[28:29], v[0:1] op_sel_hi:[1,0]
	v_pk_mul_f32 v[26:27], v[26:27], v[0:1] op_sel_hi:[1,0]
	v_pk_mul_f32 v[24:25], v[24:25], v[0:1] op_sel_hi:[1,0]
	v_pk_mul_f32 v[22:23], v[22:23], v[0:1] op_sel_hi:[1,0]
	v_pk_mul_f32 v[20:21], v[20:21], v[0:1] op_sel_hi:[1,0]
	v_pk_mul_f32 v[18:19], v[18:19], v[0:1] op_sel_hi:[1,0]
	v_pk_mul_f32 v[16:17], v[16:17], v[0:1] op_sel_hi:[1,0]
	v_pk_mul_f32 v[14:15], v[14:15], v[0:1] op_sel_hi:[1,0]
	v_pk_mul_f32 v[12:13], v[12:13], v[0:1] op_sel_hi:[1,0]
	v_pk_mul_f32 v[10:11], v[10:11], v[0:1] op_sel_hi:[1,0]
	v_pk_mul_f32 v[8:9], v[8:9], v[0:1] op_sel_hi:[1,0]
	v_pk_mul_f32 v[6:7], v[6:7], v[0:1] op_sel_hi:[1,0]
	v_pk_mul_f32 v[4:5], v[4:5], v[0:1] op_sel_hi:[1,0]
	v_mul_f32_e32 v0, v2, v2
	v_mul_f32_e32 v34, v3, v3
	v_fmac_f32_e32 v0, v18, v18
	v_fmac_f32_e32 v34, v19, v19
	v_add_f32_e32 v0, v0, v34
	v_mul_f32_e32 v34, v4, v4
	v_fmac_f32_e32 v34, v20, v20
	v_add_f32_e32 v0, v34, v0
	v_mul_f32_e32 v34, v5, v5
	v_fmac_f32_e32 v34, v21, v21
	v_add_f32_e32 v0, v34, v0
	v_mul_f32_e32 v34, v6, v6
	v_fmac_f32_e32 v34, v22, v22
	v_add_f32_e32 v0, v34, v0
	v_mul_f32_e32 v34, v7, v7
	v_fmac_f32_e32 v34, v23, v23
	v_add_f32_e32 v0, v34, v0
	v_mul_f32_e32 v34, v8, v8
	v_fmac_f32_e32 v34, v24, v24
	v_add_f32_e32 v0, v34, v0
	v_mul_f32_e32 v34, v9, v9
	v_fmac_f32_e32 v34, v25, v25
	v_add_f32_e32 v0, v34, v0
	v_mul_f32_e32 v34, v10, v10
	v_fmac_f32_e32 v34, v26, v26
	v_add_f32_e32 v0, v34, v0
	v_mul_f32_e32 v34, v11, v11
	v_fmac_f32_e32 v34, v27, v27
	v_add_f32_e32 v0, v34, v0
	v_mul_f32_e32 v34, v12, v12
	v_fmac_f32_e32 v34, v28, v28
	v_add_f32_e32 v0, v34, v0
	v_mul_f32_e32 v34, v13, v13
	v_fmac_f32_e32 v34, v29, v29
	v_add_f32_e32 v0, v34, v0
	v_mul_f32_e32 v34, v14, v14
	v_fmac_f32_e32 v34, v30, v30
	v_add_f32_e32 v0, v34, v0
	v_mul_f32_e32 v34, v15, v15
	v_fmac_f32_e32 v34, v31, v31
	v_add_f32_e32 v0, v34, v0
	v_mul_f32_e32 v34, v16, v16
	v_fmac_f32_e32 v34, v32, v32
	v_add_f32_e32 v0, v34, v0
	v_mul_f32_e32 v34, v17, v17
	v_fmac_f32_e32 v34, v33, v33
	v_add_f32_e32 v0, v34, v0
	ds_bpermute_b32 v36, v156, v0
	v_lshl_add_u64 v[34:35], s[42:43], 0, v[142:143]
	s_and_saveexec_b64 s[6:7], vcc
	s_cbranch_execz .LBB0_240
	s_waitcnt lgkmcnt(0)
	v_add_f32_e32 v0, v0, v36
	v_lshl_add_u64 v[36:37], v[34:35], 4, s[4:5]
	s_lshl_b32 s18, s83, 2
	v_lshl_add_u64 v[36:37], v[36:37], 0, s[18:19]
	global_store_dword v[36:37], v0, off
	s_branch .LBB0_240
.Ltramp_17:
	s_branch .LBB0_17
.LBB0_277:
	v_readlane_b32 s84, v254, 42
	v_readlane_b32 s85, v254, 43
	v_readlane_b32 s84, v253, 0
	s_mov_b64 s[4:5], 0
	v_readlane_b32 s86, v254, 44
	v_readlane_b32 s87, v254, 45
	v_readlane_b32 s85, v253, 1
